# GEMM calls followed by another GEMM call no longer drain their epilogue stores (vmcnt(0)) before the next call's first tile loads
# speedup vs baseline: 1.0469x; 1.0051x over previous
; #define PG8_STAGE(bufoff, gbase, voff) do { _Pragma("unroll") for (int _i = 0; _i < 2; ++_i) \
;         __builtin_amdgcn_global_load_lds((const unsigned*)((const char*)(gbase) + (voff)[_i]), (PG8_LAS unsigned*)(lds + (bufoff) + ldsw + _i * 8192), 16, 0, 0); } while (0)
; #define PG8_LDA(dst, b, h) do { _Pragma("unroll") for (int m = 0; m < 4; ++m) _Pragma("unroll") for (int k = 0; k < 2; ++k) dst[m][k] = *(const PG8_LAS bf16x8*)(lds + PG8_SA(b, h) + aoff + m * 2048 + k * 1024); } while (0)
; #define PG8_LDB(dst, b, h) do { _Pragma("unroll") for (int n = 0; n < 2; ++n) _Pragma("unroll") for (int k = 0; k < 2; ++k) dst[n][k] = *(const PG8_LAS bf16x8*)(lds + PG8_SB(b, h) + boff + n * 2048 + k * 1024); } while (0)
; #define PG8_MMA(ai, bj, At, Bt) do { __builtin_amdgcn_s_setprio(1); _Pragma("unroll") for (int m = 0; m < 4; ++m) _Pragma("unroll") for (int n = 0; n < 2; ++n) _Pragma("unroll") for (int k = 0; k < 2; ++k) \
;         acc[ai][bj][m][n] = __builtin_amdgcn_mfma_f32_16x16x32_bf16(Bt[n][k], At[m][k], acc[ai][bj][m][n], 0, 0, 0); __builtin_amdgcn_s_setprio(0); } while (0)
; #define PG8_WAIT_L(n) asm volatile("s_waitcnt lgkmcnt(" #n ")" ::: "memory")
; #define PG8_BAR __builtin_amdgcn_s_barrier()
; #define PG8_SCHED __builtin_amdgcn_sched_barrier(0)
; template <class Epi, class Sched, bool STAMP = false>
; __device__ __forceinline__ void gemm_phase(PG8_LAS unsigned char* lds, const Gemm g, const Sched& S, const Epi& E, unsigned long long* stamps) {
;     ...
;             const bool last = (t == nt - 2);
;             const char* a1 = cA + (size_t)(t + 1) * kstep;
;             const char* a2 = last ? nA : cA + (size_t)(t + 2) * kstep; const char* b2 = last ? nB : cB + (size_t)(t + 2) * kstep;
;             const char* a3 = a2 + kstep; const char* b3 = b2 + kstep;
;             if (last && has_next) S.a_ready(nxt);
;             PG8_LDB(B0, 0, 0); PG8_SCHED; PG8_LDA(At, 0, 0); PG8_STAGE(PG8_SA(1, 1), a1 + hstep, voffA);
;             PG8_WAIT_L(8); PG8_BAR; PG8_WAIT_L(0); PG8_MMA(0, 0, At, B0); PG8_BAR; PG8_SCHED;
;             PG8_LDB(B1, 0, 1); PG8_STAGE(PG8_SB(0, 0), b2, voffB);
;             PG8_BAR; PG8_WAIT_L(0); PG8_MMA(0, 1, At, B1); PG8_BAR;
;             PG8_LDA(At, 0, 1); PG8_STAGE(PG8_SA(0, 0), a2, voffA);
;             PG8_BAR; PG8_WAIT_L(0); PG8_MMA(1, 0, At, B0); PG8_BAR; PG8_SCHED;
.LBB0_44:
	s_add_u32 s14, s24, 0xfffc0080
	s_addc_u32 s15, s25, -1
	s_add_i32 s16, 0, 0x10000
	v_add_u32_e32 v169, s16, v166
	ds_read_b128 v[158:161], v169
	ds_read_b128 v[162:165], v169 offset:1024
	ds_read_b128 v[170:173], v169 offset:2048
	ds_read_b128 v[174:177], v169 offset:3072
	s_cmp_eq_u32 s61, 12
	s_cselect_b32 s31, s7, s15
	s_cselect_b32 s30, s57, s14
	s_cselect_b32 s27, s5, s60
	s_cselect_b32 s26, s58, s59
	v_lshl_add_u64 v[182:183], s[24:25], 0, v[154:155]
	s_add_i32 m0, s23, 0xc000
	ds_read_b128 v[178:181], v168
	ds_read_b128 v[192:195], v168 offset:1024
	ds_read_b128 v[196:199], v168 offset:2048
	ds_read_b128 v[200:203], v168 offset:3072
	ds_read_b128 v[204:207], v168 offset:4096
	ds_read_b128 v[208:211], v168 offset:5120
	ds_read_b128 v[212:215], v168 offset:6144
	ds_read_b128 v[216:219], v168 offset:7168
	global_load_lds_dwordx4 v[182:183], off
	v_lshl_add_u64 v[182:183], s[24:25], 0, v[156:157]
	s_add_i32 m0, s23, 0xe000
	s_nop 0
	global_load_lds_dwordx4 v[182:183], off
	s_waitcnt lgkmcnt(8)
	s_barrier
	s_waitcnt lgkmcnt(0)
	s_setprio 1
	s_waitcnt lgkmcnt(0)
	v_mfma_f32_16x16x32_bf16 v[124:127], v[158:161], v[178:181], v[124:127]
	v_mfma_f32_16x16x32_bf16 v[120:123], v[170:173], v[178:181], v[120:123]
	v_mfma_f32_16x16x32_bf16 v[108:111], v[158:161], v[196:199], v[108:111]
	v_mfma_f32_16x16x32_bf16 v[104:107], v[170:173], v[196:199], v[104:107]
	v_mfma_f32_16x16x32_bf16 v[92:95], v[158:161], v[204:207], v[92:95]
	v_mfma_f32_16x16x32_bf16 v[88:91], v[170:173], v[204:207], v[88:91]
	v_mfma_f32_16x16x32_bf16 v[76:79], v[158:161], v[212:215], v[76:79]
	v_mfma_f32_16x16x32_bf16 v[72:75], v[170:173], v[212:215], v[72:75]
	v_mfma_f32_16x16x32_bf16 v[124:127], v[162:165], v[192:195], v[124:127]
	v_mfma_f32_16x16x32_bf16 v[120:123], v[174:177], v[192:195], v[120:123]
	v_mfma_f32_16x16x32_bf16 v[108:111], v[162:165], v[200:203], v[108:111]
	v_mfma_f32_16x16x32_bf16 v[104:107], v[174:177], v[200:203], v[104:107]
	v_mfma_f32_16x16x32_bf16 v[92:95], v[162:165], v[208:211], v[92:95]
	v_mfma_f32_16x16x32_bf16 v[88:91], v[174:177], v[208:211], v[88:91]
	v_mfma_f32_16x16x32_bf16 v[76:79], v[162:165], v[216:219], v[76:79]
	v_mfma_f32_16x16x32_bf16 v[72:75], v[174:177], v[216:219], v[72:75]
	s_setprio 0
	s_barrier
	s_add_i32 s17, 0, 0x14000
	s_add_i32 s14, s16, s43
	v_add_u32_e32 v169, s17, v166
	v_lshl_add_u64 v[182:183], s[26:27], 0, v[128:129]
	s_mov_b32 m0, s14
	ds_read_b128 v[220:223], v169
	ds_read_b128 v[224:227], v169 offset:1024
	ds_read_b128 v[228:231], v169 offset:2048
	ds_read_b128 v[232:235], v169 offset:3072
	global_load_lds_dwordx4 v[182:183], off
	v_lshl_add_u64 v[236:237], s[26:27], 0, v[148:149]
	s_add_i32 m0, s14, 0x2000
	s_nop 0
	global_load_lds_dwordx4 v[236:237], off
	s_barrier
	s_waitcnt lgkmcnt(0)
	s_setprio 1
	s_waitcnt lgkmcnt(0)
	v_mfma_f32_16x16x32_bf16 v[116:119], v[220:223], v[178:181], v[116:119]
	v_mfma_f32_16x16x32_bf16 v[112:115], v[228:231], v[178:181], v[112:115]
	v_mfma_f32_16x16x32_bf16 v[100:103], v[220:223], v[196:199], v[100:103]
	v_mfma_f32_16x16x32_bf16 v[96:99], v[228:231], v[196:199], v[96:99]
	v_mfma_f32_16x16x32_bf16 v[84:87], v[220:223], v[204:207], v[84:87]
	v_mfma_f32_16x16x32_bf16 v[80:83], v[228:231], v[204:207], v[80:83]
	v_mfma_f32_16x16x32_bf16 v[68:71], v[220:223], v[212:215], v[68:71]
	v_mfma_f32_16x16x32_bf16 v[64:67], v[228:231], v[212:215], v[64:67]
	v_mfma_f32_16x16x32_bf16 v[116:119], v[224:227], v[192:195], v[116:119]
	v_mfma_f32_16x16x32_bf16 v[112:115], v[232:235], v[192:195], v[112:115]
	v_mfma_f32_16x16x32_bf16 v[100:103], v[224:227], v[200:203], v[100:103]
	v_mfma_f32_16x16x32_bf16 v[96:99], v[232:235], v[200:203], v[96:99]
	v_mfma_f32_16x16x32_bf16 v[84:87], v[224:227], v[208:211], v[84:87]
	v_mfma_f32_16x16x32_bf16 v[80:83], v[232:235], v[208:211], v[80:83]
	v_mfma_f32_16x16x32_bf16 v[68:71], v[224:227], v[216:219], v[68:71]
	v_mfma_f32_16x16x32_bf16 v[64:67], v[232:235], v[216:219], v[64:67]
	s_setprio 0
	s_mov_b32 m0, s23
	v_lshl_add_u64 v[238:239], s[30:31], 0, v[152:153]
	s_barrier
	ds_read_b128 v[178:181], v168 offset:16384
	ds_read_b128 v[192:195], v168 offset:17408
	ds_read_b128 v[196:199], v168 offset:18432
	ds_read_b128 v[200:203], v168 offset:19456
	ds_read_b128 v[204:207], v168 offset:20480
	ds_read_b128 v[208:211], v168 offset:21504
	ds_read_b128 v[212:215], v168 offset:22528
	ds_read_b128 v[216:219], v168 offset:23552
	global_load_lds_dwordx4 v[238:239], off
	v_lshl_add_u64 v[240:241], s[30:31], 0, v[150:151]
	s_mov_b32 m0, s45
	s_nop 0
	global_load_lds_dwordx4 v[240:241], off
	s_barrier
	s_waitcnt lgkmcnt(0)
	s_setprio 1
	s_waitcnt lgkmcnt(0)
	v_mfma_f32_16x16x32_bf16 v[60:63], v[158:161], v[178:181], v[60:63]
	v_mfma_f32_16x16x32_bf16 v[56:59], v[170:173], v[178:181], v[56:59]
	v_mfma_f32_16x16x32_bf16 v[44:47], v[158:161], v[196:199], v[44:47]
	v_mfma_f32_16x16x32_bf16 v[40:43], v[170:173], v[196:199], v[40:43]
	v_mfma_f32_16x16x32_bf16 v[28:31], v[158:161], v[204:207], v[28:31]
	v_mfma_f32_16x16x32_bf16 v[24:27], v[170:173], v[204:207], v[24:27]
	v_mfma_f32_16x16x32_bf16 v[12:15], v[158:161], v[212:215], v[12:15]
	v_mfma_f32_16x16x32_bf16 v[8:11], v[170:173], v[212:215], v[8:11]
	v_mfma_f32_16x16x32_bf16 v[60:63], v[162:165], v[192:195], v[60:63]
	v_mfma_f32_16x16x32_bf16 v[56:59], v[174:177], v[192:195], v[56:59]
	v_mfma_f32_16x16x32_bf16 v[44:47], v[162:165], v[200:203], v[44:47]
	v_mfma_f32_16x16x32_bf16 v[40:43], v[174:177], v[200:203], v[40:43]
	v_mfma_f32_16x16x32_bf16 v[28:31], v[162:165], v[208:211], v[28:31]
	v_mfma_f32_16x16x32_bf16 v[24:27], v[174:177], v[208:211], v[24:27]
	v_mfma_f32_16x16x32_bf16 v[12:15], v[162:165], v[216:219], v[12:15]
	v_mfma_f32_16x16x32_bf16 v[8:11], v[174:177], v[216:219], v[8:11]
	s_setprio 0
	s_barrier
; #define PG8_STAGE(bufoff, gbase, voff) do { _Pragma("unroll") for (int _i = 0; _i < 2; ++_i) \
;         __builtin_amdgcn_global_load_lds((const unsigned*)((const char*)(gbase) + (voff)[_i]), (PG8_LAS unsigned*)(lds + (bufoff) + ldsw + _i * 8192), 16, 0, 0); } while (0)
; #define PG8_LDA(dst, b, h) do { _Pragma("unroll") for (int m = 0; m < 4; ++m) _Pragma("unroll") for (int k = 0; k < 2; ++k) dst[m][k] = *(const PG8_LAS bf16x8*)(lds + PG8_SA(b, h) + aoff + m * 2048 + k * 1024); } while (0)
; #define PG8_LDB(dst, b, h) do { _Pragma("unroll") for (int n = 0; n < 2; ++n) _Pragma("unroll") for (int k = 0; k < 2; ++k) dst[n][k] = *(const PG8_LAS bf16x8*)(lds + PG8_SB(b, h) + boff + n * 2048 + k * 1024); } while (0)
; #define PG8_MMA(ai, bj, At, Bt) do { __builtin_amdgcn_s_setprio(1); _Pragma("unroll") for (int m = 0; m < 4; ++m) _Pragma("unroll") for (int n = 0; n < 2; ++n) _Pragma("unroll") for (int k = 0; k < 2; ++k) \
;         acc[ai][bj][m][n] = __builtin_amdgcn_mfma_f32_16x16x32_bf16(Bt[n][k], At[m][k], acc[ai][bj][m][n], 0, 0, 0); __builtin_amdgcn_s_setprio(0); } while (0)
; #define PG8_WAIT_V(n) asm volatile("s_waitcnt vmcnt(" #n ")" ::: "memory")
; #define PG8_WAIT_L(n) asm volatile("s_waitcnt lgkmcnt(" #n ")" ::: "memory")
; #define PG8_BAR __builtin_amdgcn_s_barrier()
; #define PG8_SCHED __builtin_amdgcn_sched_barrier(0)
; template <class Epi, class Sched, bool STAMP = false>
; __device__ __forceinline__ void gemm_phase(PG8_LAS unsigned char* lds, const Gemm g, const Sched& S, const Epi& E, unsigned long long* stamps) {
;     ...
;             PG8_STAGE(PG8_SB(0, 1), b2 + hstep, voffB);
;             PG8_WAIT_V(6); PG8_BAR; PG8_MMA(1, 1, At, B1); PG8_BAR;
;             PG8_LDB(B0, 1, 0); PG8_SCHED; PG8_LDA(At, 1, 0); PG8_STAGE(PG8_SA(0, 1), a2 + hstep, voffA);
;             PG8_WAIT_L(8); PG8_BAR; PG8_WAIT_L(0); PG8_MMA(0, 0, At, B0); PG8_BAR; PG8_SCHED;
;             PG8_LDB(B1, 1, 1); PG8_STAGE(PG8_SB(1, 0), b3, voffB);
;             PG8_BAR; PG8_WAIT_L(0); PG8_MMA(0, 1, At, B1); PG8_BAR;
;             PG8_LDA(At, 1, 1); PG8_STAGE(PG8_SA(1, 0), a3, voffA);
	s_add_u32 s14, s26, 0x40000
	s_addc_u32 s15, s27, 0
	s_add_i32 s16, s17, s43
	v_lshl_add_u64 v[158:159], s[14:15], 0, v[128:129]
	s_mov_b32 m0, s16
	s_nop 0
	global_load_lds_dwordx4 v[158:159], off
	v_lshl_add_u64 v[158:159], s[14:15], 0, v[148:149]
	s_add_i32 m0, s16, 0x2000
	s_nop 0
	global_load_lds_dwordx4 v[158:159], off
	s_waitcnt vmcnt(6)
	s_barrier
	s_setprio 1
	v_mfma_f32_16x16x32_bf16 v[52:55], v[220:223], v[178:181], v[52:55]
	v_mfma_f32_16x16x32_bf16 v[48:51], v[228:231], v[178:181], v[48:51]
	v_mfma_f32_16x16x32_bf16 v[36:39], v[220:223], v[196:199], v[36:39]
	v_mfma_f32_16x16x32_bf16 v[32:35], v[228:231], v[196:199], v[32:35]
	v_mfma_f32_16x16x32_bf16 v[20:23], v[220:223], v[204:207], v[20:23]
	v_mfma_f32_16x16x32_bf16 v[16:19], v[228:231], v[204:207], v[16:19]
	v_mfma_f32_16x16x32_bf16 v[4:7], v[220:223], v[212:215], v[4:7]
	v_mfma_f32_16x16x32_bf16 v[0:3], v[228:231], v[212:215], v[0:3]
	v_mfma_f32_16x16x32_bf16 v[52:55], v[224:227], v[192:195], v[52:55]
	v_mfma_f32_16x16x32_bf16 v[48:51], v[232:235], v[192:195], v[48:51]
	v_mfma_f32_16x16x32_bf16 v[36:39], v[224:227], v[200:203], v[36:39]
	v_mfma_f32_16x16x32_bf16 v[32:35], v[232:235], v[200:203], v[32:35]
	v_mfma_f32_16x16x32_bf16 v[20:23], v[224:227], v[208:211], v[20:23]
	v_mfma_f32_16x16x32_bf16 v[16:19], v[232:235], v[208:211], v[16:19]
	v_mfma_f32_16x16x32_bf16 v[4:7], v[224:227], v[216:219], v[4:7]
	v_mfma_f32_16x16x32_bf16 v[0:3], v[232:235], v[216:219], v[0:3]
	s_setprio 0
	s_add_i32 s16, 0, 0x18000
	v_add_u32_e32 v169, s16, v166
	s_barrier
	ds_read_b128 v[158:161], v169
	ds_read_b128 v[162:165], v169 offset:1024
	ds_read_b128 v[170:173], v169 offset:2048
	ds_read_b128 v[174:177], v169 offset:3072
	s_add_u32 s14, s30, 0x40000
	s_addc_u32 s15, s31, 0
	s_mov_b32 m0, s46
	v_lshl_add_u64 v[220:221], s[14:15], 0, v[152:153]
	ds_read_b128 v[178:181], v168 offset:32768
	ds_read_b128 v[192:195], v168 offset:33792
	ds_read_b128 v[196:199], v168 offset:34816
	ds_read_b128 v[200:203], v168 offset:35840
	ds_read_b128 v[204:207], v168 offset:36864
	ds_read_b128 v[208:211], v168 offset:37888
	ds_read_b128 v[212:215], v168 offset:38912
	ds_read_b128 v[216:219], v168 offset:39936
	global_load_lds_dwordx4 v[220:221], off
	v_lshl_add_u64 v[220:221], s[14:15], 0, v[150:151]
	s_mov_b32 m0, s47
	s_nop 0
	global_load_lds_dwordx4 v[220:221], off
	s_waitcnt lgkmcnt(8)
	s_barrier
	s_waitcnt lgkmcnt(0)
	s_setprio 1
	s_waitcnt lgkmcnt(0)
	v_mfma_f32_16x16x32_bf16 v[124:127], v[158:161], v[178:181], v[124:127]
	v_mfma_f32_16x16x32_bf16 v[120:123], v[170:173], v[178:181], v[120:123]
	v_mfma_f32_16x16x32_bf16 v[108:111], v[158:161], v[196:199], v[108:111]
	v_mfma_f32_16x16x32_bf16 v[104:107], v[170:173], v[196:199], v[104:107]
	v_mfma_f32_16x16x32_bf16 v[92:95], v[158:161], v[204:207], v[92:95]
	v_mfma_f32_16x16x32_bf16 v[88:91], v[170:173], v[204:207], v[88:91]
	v_mfma_f32_16x16x32_bf16 v[76:79], v[158:161], v[212:215], v[76:79]
	v_mfma_f32_16x16x32_bf16 v[72:75], v[170:173], v[212:215], v[72:75]
	v_mfma_f32_16x16x32_bf16 v[124:127], v[162:165], v[192:195], v[124:127]
	v_mfma_f32_16x16x32_bf16 v[120:123], v[174:177], v[192:195], v[120:123]
	v_mfma_f32_16x16x32_bf16 v[108:111], v[162:165], v[200:203], v[108:111]
	v_mfma_f32_16x16x32_bf16 v[104:107], v[174:177], v[200:203], v[104:107]
	v_mfma_f32_16x16x32_bf16 v[92:95], v[162:165], v[208:211], v[92:95]
	v_mfma_f32_16x16x32_bf16 v[88:91], v[174:177], v[208:211], v[88:91]
	v_mfma_f32_16x16x32_bf16 v[76:79], v[162:165], v[216:219], v[76:79]
	v_mfma_f32_16x16x32_bf16 v[72:75], v[174:177], v[216:219], v[72:75]
	s_setprio 0
	s_barrier
	s_add_i32 s17, 0, 0x1c000
	s_add_i32 s14, s16, s43
	v_add_u32_e32 v169, s17, v166
	v_lshl_add_u64 v[182:183], v[182:183], 0, s[18:19]
	s_mov_b32 m0, s14
	ds_read_b128 v[220:223], v169
	ds_read_b128 v[224:227], v169 offset:1024
	ds_read_b128 v[228:231], v169 offset:2048
	ds_read_b128 v[232:235], v169 offset:3072
	global_load_lds_dwordx4 v[182:183], off
	v_lshl_add_u64 v[182:183], v[236:237], 0, s[18:19]
	s_add_i32 m0, s14, 0x2000
	s_nop 0
	global_load_lds_dwordx4 v[182:183], off
	s_barrier
	s_waitcnt lgkmcnt(0)
	s_setprio 1
	s_waitcnt lgkmcnt(0)
	v_mfma_f32_16x16x32_bf16 v[116:119], v[220:223], v[178:181], v[116:119]
	v_mfma_f32_16x16x32_bf16 v[112:115], v[228:231], v[178:181], v[112:115]
	v_mfma_f32_16x16x32_bf16 v[100:103], v[220:223], v[196:199], v[100:103]
	v_mfma_f32_16x16x32_bf16 v[96:99], v[228:231], v[196:199], v[96:99]
	v_mfma_f32_16x16x32_bf16 v[84:87], v[220:223], v[204:207], v[84:87]
	v_mfma_f32_16x16x32_bf16 v[80:83], v[228:231], v[204:207], v[80:83]
	v_mfma_f32_16x16x32_bf16 v[68:71], v[220:223], v[212:215], v[68:71]
	v_mfma_f32_16x16x32_bf16 v[64:67], v[228:231], v[212:215], v[64:67]
	v_mfma_f32_16x16x32_bf16 v[116:119], v[224:227], v[192:195], v[116:119]
	v_mfma_f32_16x16x32_bf16 v[112:115], v[232:235], v[192:195], v[112:115]
	v_mfma_f32_16x16x32_bf16 v[100:103], v[224:227], v[200:203], v[100:103]
	v_mfma_f32_16x16x32_bf16 v[96:99], v[232:235], v[200:203], v[96:99]
	v_mfma_f32_16x16x32_bf16 v[84:87], v[224:227], v[208:211], v[84:87]
	v_mfma_f32_16x16x32_bf16 v[80:83], v[232:235], v[208:211], v[80:83]
	v_mfma_f32_16x16x32_bf16 v[68:71], v[224:227], v[216:219], v[68:71]
	v_mfma_f32_16x16x32_bf16 v[64:67], v[232:235], v[216:219], v[64:67]
	s_setprio 0
	s_mov_b32 m0, s49
	v_lshl_add_u64 v[182:183], v[238:239], 0, s[18:19]
	s_barrier
	ds_read_b128 v[178:181], v168 offset:49152
	ds_read_b128 v[192:195], v168 offset:50176
	ds_read_b128 v[196:199], v168 offset:51200
	ds_read_b128 v[200:203], v168 offset:52224
	ds_read_b128 v[204:207], v168 offset:53248
	ds_read_b128 v[208:211], v168 offset:54272
	ds_read_b128 v[212:215], v168 offset:55296
	ds_read_b128 v[216:219], v168 offset:56320
	global_load_lds_dwordx4 v[182:183], off
	v_lshl_add_u64 v[182:183], v[240:241], 0, s[18:19]
	s_mov_b32 m0, s53
	s_nop 0
	global_load_lds_dwordx4 v[182:183], off
	s_barrier
; __device__ __forceinline__ unsigned cvt_pk_bf16(float lo, float hi) { const f32x2_cv v = {lo, hi}; const bf16x2_cv b = __builtin_convertvector(v, bf16x2_cv); return __builtin_bit_cast(unsigned, b); }
; #define PG8_STAGE(bufoff, gbase, voff) do { _Pragma("unroll") for (int _i = 0; _i < 2; ++_i) \
;         __builtin_amdgcn_global_load_lds((const unsigned*)((const char*)(gbase) + (voff)[_i]), (PG8_LAS unsigned*)(lds + (bufoff) + ldsw + _i * 8192), 16, 0, 0); } while (0)
; #define PG8_MMA(ai, bj, At, Bt) do { __builtin_amdgcn_s_setprio(1); _Pragma("unroll") for (int m = 0; m < 4; ++m) _Pragma("unroll") for (int n = 0; n < 2; ++n) _Pragma("unroll") for (int k = 0; k < 2; ++k) \
;         acc[ai][bj][m][n] = __builtin_amdgcn_mfma_f32_16x16x32_bf16(Bt[n][k], At[m][k], acc[ai][bj][m][n], 0, 0, 0); __builtin_amdgcn_s_setprio(0); } while (0)
; template <class Epi, class Sched, bool STAMP = false>
; __device__ __forceinline__ void gemm_phase(PG8_LAS unsigned char* lds, const Gemm g, const Sched& S, const Epi& E, unsigned long long* stamps) {
;     ...
;             PG8_BAR; PG8_WAIT_L(0); PG8_MMA(1, 0, At, B0); PG8_BAR; PG8_SCHED;
;             PG8_STAGE(PG8_SB(1, 1), b3 + hstep, voffB);
;             PG8_WAIT_V(6); PG8_BAR; PG8_MMA(1, 1, At, B1); PG8_BAR;
;     __device__ __forceinline__ void operator()(const f32x4 (&acc)[2][2][4][2], const pg8::Unit& u, int wr, int wc, int fr, int fq) const {
;         const int row0 = u.pm * 256 + wr * 64 + fr, col0 = u.pn * 256 + wc * 32 + 8 * fq;
; #pragma unroll
;         for (int ai = 0; ai < 2; ++ai)
; #pragma unroll
;             for (int m = 0; m < 4; ++m) {
;                 const int row = row0 + ai * 128 + m * 16;
;                 const float s = (MODE == 2) ? 1.0f : rstd_of(rowss, row);
;                 bf16_t* rowp = O + (size_t)row * ldc + col0;
; #pragma unroll
;                 for (int bj = 0; bj < 2; ++bj) {
;                     f32x4 v0 = acc[ai][bj][m][0] * s, v1 = acc[ai][bj][m][1] * s;
;                     if (MODE == 1) {
; #pragma unroll
;                         for (int j = 0; j < 4; ++j) { const float a = fmaxf(v0[j], 0.f), b = fmaxf(v1[j], 0.f); v0[j] = a * a; v1[j] = b * b; } }
;                     u32x4 w; w.x = cvt_pk_bf16(v0[0], v0[1]); w.y = cvt_pk_bf16(v0[2], v0[3]); w.z = cvt_pk_bf16(v1[0], v1[1]); w.w = cvt_pk_bf16(v1[2], v1[3]);
;                     *(u32x4*)(rowp + bj * 128) = w; } }
	s_waitcnt lgkmcnt(0)
	s_setprio 1
	s_waitcnt lgkmcnt(0)
	v_mfma_f32_16x16x32_bf16 v[60:63], v[158:161], v[178:181], v[60:63]
	v_mfma_f32_16x16x32_bf16 v[56:59], v[170:173], v[178:181], v[56:59]
	v_mfma_f32_16x16x32_bf16 v[44:47], v[158:161], v[196:199], v[44:47]
	v_mfma_f32_16x16x32_bf16 v[40:43], v[170:173], v[196:199], v[40:43]
	v_mfma_f32_16x16x32_bf16 v[28:31], v[158:161], v[204:207], v[28:31]
	v_mfma_f32_16x16x32_bf16 v[24:27], v[170:173], v[204:207], v[24:27]
	v_mfma_f32_16x16x32_bf16 v[12:15], v[158:161], v[212:215], v[12:15]
	v_mfma_f32_16x16x32_bf16 v[8:11], v[170:173], v[212:215], v[8:11]
	v_mfma_f32_16x16x32_bf16 v[60:63], v[162:165], v[192:195], v[60:63]
	v_mfma_f32_16x16x32_bf16 v[56:59], v[174:177], v[192:195], v[56:59]
	v_mfma_f32_16x16x32_bf16 v[44:47], v[162:165], v[200:203], v[44:47]
	v_mfma_f32_16x16x32_bf16 v[40:43], v[174:177], v[200:203], v[40:43]
	v_mfma_f32_16x16x32_bf16 v[28:31], v[162:165], v[208:211], v[28:31]
	v_mfma_f32_16x16x32_bf16 v[24:27], v[174:177], v[208:211], v[24:27]
	v_mfma_f32_16x16x32_bf16 v[12:15], v[162:165], v[216:219], v[12:15]
	v_mfma_f32_16x16x32_bf16 v[8:11], v[174:177], v[216:219], v[8:11]
	s_setprio 0
	s_barrier
	s_add_u32 s14, s26, 0x40080
	s_addc_u32 s15, s27, 0
	s_add_i32 s16, s17, s43
	v_lshl_add_u64 v[158:159], s[14:15], 0, v[128:129]
	s_mov_b32 m0, s16
	s_nop 0
	global_load_lds_dwordx4 v[158:159], off
	v_lshl_add_u64 v[158:159], s[14:15], 0, v[148:149]
	s_add_i32 m0, s16, 0x2000
	s_nop 0
	global_load_lds_dwordx4 v[158:159], off
	s_waitcnt vmcnt(6)
	s_barrier
	s_setprio 1
	v_mfma_f32_16x16x32_bf16 v[52:55], v[220:223], v[178:181], v[52:55]
	v_mfma_f32_16x16x32_bf16 v[48:51], v[228:231], v[178:181], v[48:51]
	v_mfma_f32_16x16x32_bf16 v[36:39], v[220:223], v[196:199], v[36:39]
	v_mfma_f32_16x16x32_bf16 v[32:35], v[228:231], v[196:199], v[32:35]
	v_mfma_f32_16x16x32_bf16 v[20:23], v[220:223], v[204:207], v[20:23]
	v_mfma_f32_16x16x32_bf16 v[16:19], v[228:231], v[204:207], v[16:19]
	v_mfma_f32_16x16x32_bf16 v[4:7], v[220:223], v[212:215], v[4:7]
	v_mfma_f32_16x16x32_bf16 v[0:3], v[228:231], v[212:215], v[0:3]
	v_mfma_f32_16x16x32_bf16 v[52:55], v[224:227], v[192:195], v[52:55]
	v_mfma_f32_16x16x32_bf16 v[48:51], v[232:235], v[192:195], v[48:51]
	v_mfma_f32_16x16x32_bf16 v[36:39], v[224:227], v[200:203], v[36:39]
	v_mfma_f32_16x16x32_bf16 v[32:35], v[232:235], v[200:203], v[32:35]
	v_mfma_f32_16x16x32_bf16 v[20:23], v[224:227], v[208:211], v[20:23]
	v_mfma_f32_16x16x32_bf16 v[16:19], v[232:235], v[208:211], v[16:19]
	v_mfma_f32_16x16x32_bf16 v[4:7], v[224:227], v[216:219], v[4:7]
	v_mfma_f32_16x16x32_bf16 v[0:3], v[232:235], v[216:219], v[0:3]
	s_setprio 0
	s_add_i32 s61, s61, 2
	s_add_u32 s24, s24, 0x100
	s_addc_u32 s25, s25, 0
	s_add_u32 s59, s59, 0x100
	s_addc_u32 s60, s60, 0
	s_cmp_gt_u32 s61, 13
	s_barrier
	s_cbranch_scc0 .LBB0_44
	v_lshl_add_u32 v162, s22, 8, v139
	v_ashrrev_i32_e32 v163, 31, v162
	v_lshl_add_u64 v[158:159], v[162:163], 2, s[0:1]
	global_load_dword v164, v[158:159], off
	global_load_dword v193, v[158:159], off offset:64
	global_load_dword v194, v[158:159], off offset:128
	global_load_dword v195, v[158:159], off offset:192
	global_load_dword v196, v[158:159], off offset:512
	global_load_dword v197, v[158:159], off offset:576
	global_load_dword v198, v[158:159], off offset:640
	global_load_dword v199, v[158:159], off offset:704
	v_lshl_or_b32 v160, s56, 8, v167
	v_ashrrev_i32_e32 v161, 31, v160
	s_mov_b32 s5, 0x100000
	s_mov_b64 s[14:15], 0x100000
	s_mov_b32 s56, s4
	s_mov_b32 s22, s6
	s_mov_b64 s[26:27], s[20:21]
	s_mov_b64 s[24:25], s[12:13]
	s_waitcnt vmcnt(0)
	v_fmamk_f32 v164, v164, 0x3a800000, v187
	v_cmp_gt_f32_e32 vcc, s67, v164
	v_mul_f32_e32 v165, 0x4b800000, v164
	s_nop 0
	v_cndmask_b32_e32 v164, v164, v165, vcc
	v_rsq_f32_e32 v164, v164
	s_nop 0
	v_mul_f32_e32 v165, 0x45800000, v164
	v_cndmask_b32_e32 v170, v164, v165, vcc
	v_lshlrev_b64 v[164:165], 13, v[162:163]
	v_pk_mul_f32 v[120:121], v[120:121], v[170:171] op_sel_hi:[1,0]
	v_lshl_add_u64 v[172:173], s[2:3], 0, v[164:165]
	v_lshlrev_b64 v[164:165], 1, v[160:161]
	v_pk_mul_f32 v[126:127], v[126:127], v[170:171] op_sel_hi:[1,0]
	v_pk_mul_f32 v[124:125], v[124:125], v[170:171] op_sel_hi:[1,0]
	v_pk_mul_f32 v[122:123], v[122:123], v[170:171] op_sel_hi:[1,0]
	v_max_f32_e32 v120, 0, v120
	v_max_f32_e32 v121, 0, v121
	v_lshl_add_u64 v[160:161], v[172:173], 0, v[164:165]
	v_max_f32_e32 v124, 0, v124
	v_max_f32_e32 v125, 0, v125
	v_pk_mul_f32 v[172:173], v[120:121], v[120:121]
	v_max_f32_e32 v120, 0, v126
	v_max_f32_e32 v122, 0, v122
	v_max_f32_e32 v121, 0, v127
	v_max_f32_e32 v123, 0, v123
	v_pk_mul_f32 v[124:125], v[124:125], v[124:125]
	v_pk_mul_f32 v[126:127], v[120:121], v[120:121]
	v_pk_mul_f32 v[174:175], v[122:123], v[122:123]
	v_pk_mul_f32 v[112:113], v[112:113], v[170:171] op_sel_hi:[1,0]
	v_cvt_pk_bf16_f32 v120, v124, v125
	v_cvt_pk_bf16_f32 v121, v126, v127
	v_cvt_pk_bf16_f32 v122, v172, v173
	v_cvt_pk_bf16_f32 v123, v174, v175
	v_pk_mul_f32 v[118:119], v[118:119], v[170:171] op_sel_hi:[1,0]
	v_pk_mul_f32 v[116:117], v[116:117], v[170:171] op_sel_hi:[1,0]
	v_pk_mul_f32 v[114:115], v[114:115], v[170:171] op_sel_hi:[1,0]
	v_max_f32_e32 v112, 0, v112
	v_max_f32_e32 v113, 0, v113
	global_store_dwordx4 v[160:161], v[120:123], off
	v_max_f32_e32 v116, 0, v116
	v_max_f32_e32 v117, 0, v117
	v_pk_mul_f32 v[120:121], v[112:113], v[112:113]
	v_max_f32_e32 v112, 0, v118
	v_max_f32_e32 v114, 0, v114
	v_max_f32_e32 v113, 0, v119
	v_max_f32_e32 v115, 0, v115
	v_pk_mul_f32 v[116:117], v[116:117], v[116:117]
	v_pk_mul_f32 v[118:119], v[112:113], v[112:113]
	v_pk_mul_f32 v[122:123], v[114:115], v[114:115]
; __device__ __forceinline__ unsigned cvt_pk_bf16(float lo, float hi) { const f32x2_cv v = {lo, hi}; const bf16x2_cv b = __builtin_convertvector(v, bf16x2_cv); return __builtin_bit_cast(unsigned, b); }
; __device__ __forceinline__ float rstd_of(const float* rowss, int row) { return rsqrtf(rowss[row] * (1.0f / 1024.0f) + 1e-6f); }
;     __device__ __forceinline__ void operator()(const f32x4 (&acc)[2][2][4][2], const pg8::Unit& u, int wr, int wc, int fr, int fq) const {
;         const int row0 = u.pm * 256 + wr * 64 + fr, col0 = u.pn * 256 + wc * 32 + 8 * fq;
; #pragma unroll
;         for (int ai = 0; ai < 2; ++ai)
; #pragma unroll
;             for (int m = 0; m < 4; ++m) {
;                 const int row = row0 + ai * 128 + m * 16;
;                 const float s = (MODE == 2) ? 1.0f : rstd_of(rowss, row);
;                 bf16_t* rowp = O + (size_t)row * ldc + col0;
; #pragma unroll
;                 for (int bj = 0; bj < 2; ++bj) {
;                     f32x4 v0 = acc[ai][bj][m][0] * s, v1 = acc[ai][bj][m][1] * s;
;                     if (MODE == 1) {
; #pragma unroll
;                         for (int j = 0; j < 4; ++j) { const float a = fmaxf(v0[j], 0.f), b = fmaxf(v1[j], 0.f); v0[j] = a * a; v1[j] = b * b; } }
;                     u32x4 w; w.x = cvt_pk_bf16(v0[0], v0[1]); w.y = cvt_pk_bf16(v0[2], v0[3]); w.z = cvt_pk_bf16(v1[0], v1[1]); w.w = cvt_pk_bf16(v1[2], v1[3]);
;                     *(u32x4*)(rowp + bj * 128) = w; } }
	v_cvt_pk_bf16_f32 v112, v116, v117
	v_cvt_pk_bf16_f32 v113, v118, v119
	v_cvt_pk_bf16_f32 v114, v120, v121
	v_cvt_pk_bf16_f32 v115, v122, v123
	global_store_dwordx4 v[160:161], v[112:115], off offset:256
	s_nop 1
	v_mov_b32_e32 v114, v193
	s_nop 0
	v_or_b32_e32 v112, 16, v162
	v_ashrrev_i32_e32 v113, 31, v112
	v_lshlrev_b64 v[112:113], 13, v[112:113]
	v_lshl_add_u64 v[112:113], s[2:3], 0, v[112:113]
	v_lshl_add_u64 v[112:113], v[112:113], 0, v[164:165]
	v_fmamk_f32 v114, v114, 0x3a800000, v187
	v_cmp_gt_f32_e32 vcc, s67, v114
	v_mul_f32_e32 v115, 0x4b800000, v114
	s_nop 0
	v_cndmask_b32_e32 v114, v114, v115, vcc
	v_rsq_f32_e32 v114, v114
	s_nop 0
	v_mul_f32_e32 v115, 0x45800000, v114
	v_cndmask_b32_e32 v114, v114, v115, vcc
	v_pk_mul_f32 v[104:105], v[104:105], v[114:115] op_sel_hi:[1,0]
	v_pk_mul_f32 v[110:111], v[110:111], v[114:115] op_sel_hi:[1,0]
	v_pk_mul_f32 v[108:109], v[108:109], v[114:115] op_sel_hi:[1,0]
	v_pk_mul_f32 v[106:107], v[106:107], v[114:115] op_sel_hi:[1,0]
	v_max_f32_e32 v104, 0, v104
	v_max_f32_e32 v105, 0, v105
	v_max_f32_e32 v108, 0, v108
	v_max_f32_e32 v109, 0, v109
	v_pk_mul_f32 v[116:117], v[104:105], v[104:105]
	v_max_f32_e32 v104, 0, v110
	v_max_f32_e32 v106, 0, v106
	v_max_f32_e32 v105, 0, v111
	v_max_f32_e32 v107, 0, v107
	v_pk_mul_f32 v[108:109], v[108:109], v[108:109]
	v_pk_mul_f32 v[110:111], v[104:105], v[104:105]
	v_pk_mul_f32 v[118:119], v[106:107], v[106:107]
	v_pk_mul_f32 v[96:97], v[96:97], v[114:115] op_sel_hi:[1,0]
	v_cvt_pk_bf16_f32 v104, v108, v109
	v_cvt_pk_bf16_f32 v105, v110, v111
	v_cvt_pk_bf16_f32 v106, v116, v117
	v_cvt_pk_bf16_f32 v107, v118, v119
	v_pk_mul_f32 v[102:103], v[102:103], v[114:115] op_sel_hi:[1,0]
	v_pk_mul_f32 v[100:101], v[100:101], v[114:115] op_sel_hi:[1,0]
	v_pk_mul_f32 v[98:99], v[98:99], v[114:115] op_sel_hi:[1,0]
	v_max_f32_e32 v96, 0, v96
	v_max_f32_e32 v97, 0, v97
	global_store_dwordx4 v[112:113], v[104:107], off
	v_max_f32_e32 v100, 0, v100
	v_max_f32_e32 v101, 0, v101
	v_pk_mul_f32 v[104:105], v[96:97], v[96:97]
	v_max_f32_e32 v96, 0, v102
	v_max_f32_e32 v98, 0, v98
	v_max_f32_e32 v97, 0, v103
	v_max_f32_e32 v99, 0, v99
	v_pk_mul_f32 v[100:101], v[100:101], v[100:101]
	v_pk_mul_f32 v[102:103], v[96:97], v[96:97]
	v_pk_mul_f32 v[106:107], v[98:99], v[98:99]
	v_cvt_pk_bf16_f32 v96, v100, v101
	v_cvt_pk_bf16_f32 v97, v102, v103
	v_cvt_pk_bf16_f32 v98, v104, v105
	v_cvt_pk_bf16_f32 v99, v106, v107
	global_store_dwordx4 v[112:113], v[96:99], off offset:256
	s_nop 1
	v_mov_b32_e32 v98, v194
	s_nop 0
	v_or_b32_e32 v96, 32, v162
	v_ashrrev_i32_e32 v97, 31, v96
	v_lshlrev_b64 v[96:97], 13, v[96:97]
	v_lshl_add_u64 v[96:97], s[2:3], 0, v[96:97]
	v_lshl_add_u64 v[96:97], v[96:97], 0, v[164:165]
	v_fmamk_f32 v98, v98, 0x3a800000, v187
	v_cmp_gt_f32_e32 vcc, s67, v98
	v_mul_f32_e32 v99, 0x4b800000, v98
	s_nop 0
	v_cndmask_b32_e32 v98, v98, v99, vcc
	v_rsq_f32_e32 v98, v98
	s_nop 0
	v_mul_f32_e32 v99, 0x45800000, v98
	v_cndmask_b32_e32 v98, v98, v99, vcc
	v_pk_mul_f32 v[88:89], v[88:89], v[98:99] op_sel_hi:[1,0]
	v_pk_mul_f32 v[94:95], v[94:95], v[98:99] op_sel_hi:[1,0]
	v_pk_mul_f32 v[92:93], v[92:93], v[98:99] op_sel_hi:[1,0]
	v_pk_mul_f32 v[90:91], v[90:91], v[98:99] op_sel_hi:[1,0]
	v_max_f32_e32 v88, 0, v88
	v_max_f32_e32 v89, 0, v89
	v_max_f32_e32 v92, 0, v92
	v_max_f32_e32 v93, 0, v93
	v_pk_mul_f32 v[100:101], v[88:89], v[88:89]
	v_max_f32_e32 v88, 0, v94
	v_max_f32_e32 v90, 0, v90
	v_max_f32_e32 v89, 0, v95
	v_max_f32_e32 v91, 0, v91
	v_pk_mul_f32 v[92:93], v[92:93], v[92:93]
	v_pk_mul_f32 v[94:95], v[88:89], v[88:89]
	v_pk_mul_f32 v[102:103], v[90:91], v[90:91]
	v_pk_mul_f32 v[80:81], v[80:81], v[98:99] op_sel_hi:[1,0]
	v_cvt_pk_bf16_f32 v88, v92, v93
	v_cvt_pk_bf16_f32 v89, v94, v95
	v_cvt_pk_bf16_f32 v90, v100, v101
	v_cvt_pk_bf16_f32 v91, v102, v103
	v_pk_mul_f32 v[86:87], v[86:87], v[98:99] op_sel_hi:[1,0]
	v_pk_mul_f32 v[84:85], v[84:85], v[98:99] op_sel_hi:[1,0]
	v_pk_mul_f32 v[82:83], v[82:83], v[98:99] op_sel_hi:[1,0]
	v_max_f32_e32 v80, 0, v80
	v_max_f32_e32 v81, 0, v81
	global_store_dwordx4 v[96:97], v[88:91], off
	v_max_f32_e32 v84, 0, v84
	v_max_f32_e32 v85, 0, v85
	v_pk_mul_f32 v[88:89], v[80:81], v[80:81]
	v_max_f32_e32 v80, 0, v86
	v_max_f32_e32 v82, 0, v82
	v_max_f32_e32 v81, 0, v87
	v_max_f32_e32 v83, 0, v83
	v_pk_mul_f32 v[84:85], v[84:85], v[84:85]
	v_pk_mul_f32 v[86:87], v[80:81], v[80:81]
	v_pk_mul_f32 v[90:91], v[82:83], v[82:83]
	v_cvt_pk_bf16_f32 v80, v84, v85
	v_cvt_pk_bf16_f32 v81, v86, v87
	v_cvt_pk_bf16_f32 v82, v88, v89
	v_cvt_pk_bf16_f32 v83, v90, v91
	global_store_dwordx4 v[96:97], v[80:83], off offset:256
	s_nop 1
	v_mov_b32_e32 v82, v195
	s_nop 0
	v_or_b32_e32 v80, 48, v162
	v_ashrrev_i32_e32 v81, 31, v80
	v_lshlrev_b64 v[80:81], 13, v[80:81]
	v_lshl_add_u64 v[80:81], s[2:3], 0, v[80:81]
	v_lshl_add_u64 v[80:81], v[80:81], 0, v[164:165]
	v_fmamk_f32 v82, v82, 0x3a800000, v187
	v_cmp_gt_f32_e32 vcc, s67, v82
	v_mul_f32_e32 v83, 0x4b800000, v82
	s_nop 0
	v_cndmask_b32_e32 v82, v82, v83, vcc
	v_rsq_f32_e32 v82, v82
	s_nop 0
	v_mul_f32_e32 v83, 0x45800000, v82
	v_cndmask_b32_e32 v82, v82, v83, vcc
	v_pk_mul_f32 v[72:73], v[72:73], v[82:83] op_sel_hi:[1,0]
	v_pk_mul_f32 v[78:79], v[78:79], v[82:83] op_sel_hi:[1,0]
	v_pk_mul_f32 v[76:77], v[76:77], v[82:83] op_sel_hi:[1,0]
	v_pk_mul_f32 v[74:75], v[74:75], v[82:83] op_sel_hi:[1,0]
	v_max_f32_e32 v72, 0, v72
	v_max_f32_e32 v73, 0, v73
	v_max_f32_e32 v76, 0, v76
	v_max_f32_e32 v77, 0, v77
	v_pk_mul_f32 v[84:85], v[72:73], v[72:73]
	v_max_f32_e32 v72, 0, v78
	v_max_f32_e32 v74, 0, v74
	v_max_f32_e32 v73, 0, v79
	v_max_f32_e32 v75, 0, v75
	v_pk_mul_f32 v[76:77], v[76:77], v[76:77]
; __device__ __forceinline__ unsigned cvt_pk_bf16(float lo, float hi) { const f32x2_cv v = {lo, hi}; const bf16x2_cv b = __builtin_convertvector(v, bf16x2_cv); return __builtin_bit_cast(unsigned, b); }
; __device__ __forceinline__ float rstd_of(const float* rowss, int row) { return rsqrtf(rowss[row] * (1.0f / 1024.0f) + 1e-6f); }
;     __device__ __forceinline__ void operator()(const f32x4 (&acc)[2][2][4][2], const pg8::Unit& u, int wr, int wc, int fr, int fq) const {
;         const int row0 = u.pm * 256 + wr * 64 + fr, col0 = u.pn * 256 + wc * 32 + 8 * fq;
; #pragma unroll
;         for (int ai = 0; ai < 2; ++ai)
; #pragma unroll
;             for (int m = 0; m < 4; ++m) {
;                 const int row = row0 + ai * 128 + m * 16;
;                 const float s = (MODE == 2) ? 1.0f : rstd_of(rowss, row);
;                 bf16_t* rowp = O + (size_t)row * ldc + col0;
; #pragma unroll
;                 for (int bj = 0; bj < 2; ++bj) {
;                     f32x4 v0 = acc[ai][bj][m][0] * s, v1 = acc[ai][bj][m][1] * s;
;                     if (MODE == 1) {
; #pragma unroll
;                         for (int j = 0; j < 4; ++j) { const float a = fmaxf(v0[j], 0.f), b = fmaxf(v1[j], 0.f); v0[j] = a * a; v1[j] = b * b; } }
;                     u32x4 w; w.x = cvt_pk_bf16(v0[0], v0[1]); w.y = cvt_pk_bf16(v0[2], v0[3]); w.z = cvt_pk_bf16(v1[0], v1[1]); w.w = cvt_pk_bf16(v1[2], v1[3]);
;                     *(u32x4*)(rowp + bj * 128) = w; } }
	v_pk_mul_f32 v[78:79], v[72:73], v[72:73]
	v_pk_mul_f32 v[86:87], v[74:75], v[74:75]
	v_pk_mul_f32 v[64:65], v[64:65], v[82:83] op_sel_hi:[1,0]
	v_cvt_pk_bf16_f32 v72, v76, v77
	v_cvt_pk_bf16_f32 v73, v78, v79
	v_cvt_pk_bf16_f32 v74, v84, v85
	v_cvt_pk_bf16_f32 v75, v86, v87
	v_pk_mul_f32 v[70:71], v[70:71], v[82:83] op_sel_hi:[1,0]
	v_pk_mul_f32 v[68:69], v[68:69], v[82:83] op_sel_hi:[1,0]
	v_pk_mul_f32 v[66:67], v[66:67], v[82:83] op_sel_hi:[1,0]
	v_max_f32_e32 v64, 0, v64
	v_max_f32_e32 v65, 0, v65
	global_store_dwordx4 v[80:81], v[72:75], off
	v_max_f32_e32 v68, 0, v68
	v_max_f32_e32 v69, 0, v69
	v_pk_mul_f32 v[72:73], v[64:65], v[64:65]
	v_max_f32_e32 v64, 0, v70
	v_max_f32_e32 v66, 0, v66
	v_max_f32_e32 v65, 0, v71
	v_max_f32_e32 v67, 0, v67
	v_pk_mul_f32 v[68:69], v[68:69], v[68:69]
	v_pk_mul_f32 v[70:71], v[64:65], v[64:65]
	v_pk_mul_f32 v[74:75], v[66:67], v[66:67]
	v_cvt_pk_bf16_f32 v64, v68, v69
	v_cvt_pk_bf16_f32 v65, v70, v71
	v_cvt_pk_bf16_f32 v66, v72, v73
	v_cvt_pk_bf16_f32 v67, v74, v75
	global_store_dwordx4 v[80:81], v[64:67], off offset:256
	s_nop 1
	v_mov_b32_e32 v64, v196
	v_fmamk_f32 v64, v64, 0x3a800000, v187
	v_cmp_gt_f32_e32 vcc, s67, v64
	v_mul_f32_e32 v65, 0x4b800000, v64
	s_nop 0
	v_cndmask_b32_e32 v64, v64, v65, vcc
	v_rsq_f32_e32 v64, v64
	s_nop 0
	v_mul_f32_e32 v65, 0x45800000, v64
	v_cndmask_b32_e32 v66, v64, v65, vcc
	v_pk_mul_f32 v[60:61], v[60:61], v[66:67] op_sel_hi:[1,0]
	v_pk_mul_f32 v[56:57], v[56:57], v[66:67] op_sel_hi:[1,0]
	v_pk_mul_f32 v[62:63], v[62:63], v[66:67] op_sel_hi:[1,0]
	v_pk_mul_f32 v[58:59], v[58:59], v[66:67] op_sel_hi:[1,0]
	v_max_f32_e32 v60, 0, v60
	v_max_f32_e32 v56, 0, v56
	v_max_f32_e32 v61, 0, v61
	v_max_f32_e32 v57, 0, v57
	v_pk_mul_f32 v[60:61], v[60:61], v[60:61]
	v_pk_mul_f32 v[68:69], v[56:57], v[56:57]
	v_max_f32_e32 v56, 0, v62
	v_max_f32_e32 v58, 0, v58
	v_max_f32_e32 v57, 0, v63
	v_max_f32_e32 v59, 0, v59
	v_pk_mul_f32 v[62:63], v[56:57], v[56:57]
	v_pk_mul_f32 v[70:71], v[58:59], v[58:59]
	v_cvt_pk_bf16_f32 v56, v60, v61
	v_add_co_u32_e32 v60, vcc, s5, v160
	v_pk_mul_f32 v[48:49], v[48:49], v[66:67] op_sel_hi:[1,0]
	v_cvt_pk_bf16_f32 v57, v62, v63
	v_cvt_pk_bf16_f32 v58, v68, v69
	v_cvt_pk_bf16_f32 v59, v70, v71
	v_addc_co_u32_e32 v61, vcc, 0, v161, vcc
	v_pk_mul_f32 v[54:55], v[54:55], v[66:67] op_sel_hi:[1,0]
	v_pk_mul_f32 v[52:53], v[52:53], v[66:67] op_sel_hi:[1,0]
	v_pk_mul_f32 v[50:51], v[50:51], v[66:67] op_sel_hi:[1,0]
	v_max_f32_e32 v48, 0, v48
	v_max_f32_e32 v49, 0, v49
	global_store_dwordx4 v[60:61], v[56:59], off
	v_max_f32_e32 v52, 0, v52
	v_max_f32_e32 v53, 0, v53
	v_pk_mul_f32 v[56:57], v[48:49], v[48:49]
	v_max_f32_e32 v48, 0, v54
	v_max_f32_e32 v50, 0, v50
	v_max_f32_e32 v49, 0, v55
	v_max_f32_e32 v51, 0, v51
	v_pk_mul_f32 v[52:53], v[52:53], v[52:53]
	v_pk_mul_f32 v[54:55], v[48:49], v[48:49]
	v_pk_mul_f32 v[58:59], v[50:51], v[50:51]
	v_lshl_add_u64 v[64:65], v[160:161], 0, s[14:15]
	v_cvt_pk_bf16_f32 v48, v52, v53
	v_cvt_pk_bf16_f32 v49, v54, v55
	v_cvt_pk_bf16_f32 v50, v56, v57
	v_cvt_pk_bf16_f32 v51, v58, v59
	global_store_dwordx4 v[64:65], v[48:51], off offset:256
	s_nop 1
	v_mov_b32_e32 v48, v197
	s_mov_b32 s5, 0x120000
	s_mov_b64 s[14:15], 0x120000
	v_fmamk_f32 v48, v48, 0x3a800000, v187
	v_cmp_gt_f32_e32 vcc, s67, v48
	v_mul_f32_e32 v49, 0x4b800000, v48
	s_nop 0
	v_cndmask_b32_e32 v48, v48, v49, vcc
	v_rsq_f32_e32 v48, v48
	s_nop 0
	v_mul_f32_e32 v49, 0x45800000, v48
	v_cndmask_b32_e32 v50, v48, v49, vcc
	v_pk_mul_f32 v[44:45], v[44:45], v[50:51] op_sel_hi:[1,0]
	v_pk_mul_f32 v[40:41], v[40:41], v[50:51] op_sel_hi:[1,0]
	v_pk_mul_f32 v[46:47], v[46:47], v[50:51] op_sel_hi:[1,0]
	v_pk_mul_f32 v[42:43], v[42:43], v[50:51] op_sel_hi:[1,0]
	v_max_f32_e32 v44, 0, v44
	v_max_f32_e32 v40, 0, v40
	v_max_f32_e32 v45, 0, v45
	v_max_f32_e32 v41, 0, v41
	v_pk_mul_f32 v[44:45], v[44:45], v[44:45]
	v_pk_mul_f32 v[52:53], v[40:41], v[40:41]
	v_max_f32_e32 v40, 0, v46
	v_max_f32_e32 v42, 0, v42
	v_max_f32_e32 v41, 0, v47
	v_max_f32_e32 v43, 0, v43
	v_pk_mul_f32 v[46:47], v[40:41], v[40:41]
	v_pk_mul_f32 v[54:55], v[42:43], v[42:43]
	v_cvt_pk_bf16_f32 v40, v44, v45
	v_add_co_u32_e32 v44, vcc, s5, v160
	v_pk_mul_f32 v[32:33], v[32:33], v[50:51] op_sel_hi:[1,0]
	v_cvt_pk_bf16_f32 v41, v46, v47
	v_cvt_pk_bf16_f32 v42, v52, v53
	v_cvt_pk_bf16_f32 v43, v54, v55
	v_addc_co_u32_e32 v45, vcc, 0, v161, vcc
	v_pk_mul_f32 v[38:39], v[38:39], v[50:51] op_sel_hi:[1,0]
	v_pk_mul_f32 v[36:37], v[36:37], v[50:51] op_sel_hi:[1,0]
	v_pk_mul_f32 v[34:35], v[34:35], v[50:51] op_sel_hi:[1,0]
	v_max_f32_e32 v32, 0, v32
	v_max_f32_e32 v33, 0, v33
	global_store_dwordx4 v[44:45], v[40:43], off
	v_max_f32_e32 v36, 0, v36
	v_max_f32_e32 v37, 0, v37
	v_pk_mul_f32 v[40:41], v[32:33], v[32:33]
; __device__ __forceinline__ unsigned cvt_pk_bf16(float lo, float hi) { const f32x2_cv v = {lo, hi}; const bf16x2_cv b = __builtin_convertvector(v, bf16x2_cv); return __builtin_bit_cast(unsigned, b); }
; #define PG8_WAIT_V(n) asm volatile("s_waitcnt vmcnt(" #n ")" ::: "memory")
; #define PG8_BAR __builtin_amdgcn_s_barrier()
; __device__ __forceinline__ float rstd_of(const float* rowss, int row) { return rsqrtf(rowss[row] * (1.0f / 1024.0f) + 1e-6f); }
; template <class Epi, class Sched, bool STAMP = false>
; __device__ __forceinline__ void gemm_phase(PG8_LAS unsigned char* lds, const Gemm g, const Sched& S, const Epi& E, unsigned long long* stamps) {
;     ...
;         if (!has_next) break;
; #pragma unroll
;         for (int a = 0; a < 2; ++a)
; #pragma unroll
;             for (int b = 0; b < 2; ++b)
; #pragma unroll
;                 for (int m = 0; m < 4; ++m)
; #pragma unroll
;                     for (int n = 0; n < 2; ++n) acc[a][b][m][n] = (f32x4){0.f, 0.f, 0.f, 0.f};
;         cur = nxt; cA = nA; cB = nB; ++ui;
;     }
;     PG8_WAIT_V(0);
;     if (wr == 0) PG8_BAR;
;     PG8_BAR;
;     __device__ __forceinline__ void operator()(const f32x4 (&acc)[2][2][4][2], const pg8::Unit& u, int wr, int wc, int fr, int fq) const {
;     ...
;             for (int m = 0; m < 4; ++m) {
;                 const int row = row0 + ai * 128 + m * 16;
;                 const float s = (MODE == 2) ? 1.0f : rstd_of(rowss, row);
;                 bf16_t* rowp = O + (size_t)row * ldc + col0;
; #pragma unroll
;                 for (int bj = 0; bj < 2; ++bj) {
;                     f32x4 v0 = acc[ai][bj][m][0] * s, v1 = acc[ai][bj][m][1] * s;
;                     if (MODE == 1) {
; #pragma unroll
;                         for (int j = 0; j < 4; ++j) { const float a = fmaxf(v0[j], 0.f), b = fmaxf(v1[j], 0.f); v0[j] = a * a; v1[j] = b * b; } }
;                     u32x4 w; w.x = cvt_pk_bf16(v0[0], v0[1]); w.y = cvt_pk_bf16(v0[2], v0[3]); w.z = cvt_pk_bf16(v1[0], v1[1]); w.w = cvt_pk_bf16(v1[2], v1[3]);
;                     *(u32x4*)(rowp + bj * 128) = w; } }
	v_max_f32_e32 v32, 0, v38
	v_max_f32_e32 v34, 0, v34
	v_max_f32_e32 v33, 0, v39
	v_max_f32_e32 v35, 0, v35
	v_pk_mul_f32 v[36:37], v[36:37], v[36:37]
	v_pk_mul_f32 v[38:39], v[32:33], v[32:33]
	v_pk_mul_f32 v[42:43], v[34:35], v[34:35]
	v_lshl_add_u64 v[48:49], v[160:161], 0, s[14:15]
	v_cvt_pk_bf16_f32 v32, v36, v37
	v_cvt_pk_bf16_f32 v33, v38, v39
	v_cvt_pk_bf16_f32 v34, v40, v41
	v_cvt_pk_bf16_f32 v35, v42, v43
	global_store_dwordx4 v[48:49], v[32:35], off offset:256
	s_nop 1
	v_mov_b32_e32 v32, v198
	s_mov_b32 s5, 0x140000
	s_mov_b64 s[14:15], 0x140000
	v_fmamk_f32 v32, v32, 0x3a800000, v187
	v_cmp_gt_f32_e32 vcc, s67, v32
	v_mul_f32_e32 v33, 0x4b800000, v32
	s_nop 0
	v_cndmask_b32_e32 v32, v32, v33, vcc
	v_rsq_f32_e32 v32, v32
	s_nop 0
	v_mul_f32_e32 v33, 0x45800000, v32
	v_cndmask_b32_e32 v34, v32, v33, vcc
	v_pk_mul_f32 v[28:29], v[28:29], v[34:35] op_sel_hi:[1,0]
	v_pk_mul_f32 v[24:25], v[24:25], v[34:35] op_sel_hi:[1,0]
	v_pk_mul_f32 v[30:31], v[30:31], v[34:35] op_sel_hi:[1,0]
	v_pk_mul_f32 v[26:27], v[26:27], v[34:35] op_sel_hi:[1,0]
	v_max_f32_e32 v28, 0, v28
	v_max_f32_e32 v24, 0, v24
	v_max_f32_e32 v29, 0, v29
	v_max_f32_e32 v25, 0, v25
	v_pk_mul_f32 v[28:29], v[28:29], v[28:29]
	v_pk_mul_f32 v[36:37], v[24:25], v[24:25]
	v_max_f32_e32 v24, 0, v30
	v_max_f32_e32 v26, 0, v26
	v_max_f32_e32 v25, 0, v31
	v_max_f32_e32 v27, 0, v27
	v_pk_mul_f32 v[30:31], v[24:25], v[24:25]
	v_pk_mul_f32 v[38:39], v[26:27], v[26:27]
	v_cvt_pk_bf16_f32 v24, v28, v29
	v_add_co_u32_e32 v28, vcc, s5, v160
	v_pk_mul_f32 v[16:17], v[16:17], v[34:35] op_sel_hi:[1,0]
	v_cvt_pk_bf16_f32 v25, v30, v31
	v_cvt_pk_bf16_f32 v26, v36, v37
	v_cvt_pk_bf16_f32 v27, v38, v39
	v_addc_co_u32_e32 v29, vcc, 0, v161, vcc
	v_pk_mul_f32 v[22:23], v[22:23], v[34:35] op_sel_hi:[1,0]
	v_pk_mul_f32 v[20:21], v[20:21], v[34:35] op_sel_hi:[1,0]
	v_pk_mul_f32 v[18:19], v[18:19], v[34:35] op_sel_hi:[1,0]
	v_max_f32_e32 v16, 0, v16
	v_max_f32_e32 v17, 0, v17
	global_store_dwordx4 v[28:29], v[24:27], off
	v_max_f32_e32 v20, 0, v20
	v_max_f32_e32 v21, 0, v21
	v_pk_mul_f32 v[24:25], v[16:17], v[16:17]
	v_max_f32_e32 v16, 0, v22
	v_max_f32_e32 v18, 0, v18
	v_max_f32_e32 v17, 0, v23
	v_max_f32_e32 v19, 0, v19
	v_pk_mul_f32 v[20:21], v[20:21], v[20:21]
	v_pk_mul_f32 v[22:23], v[16:17], v[16:17]
	v_pk_mul_f32 v[26:27], v[18:19], v[18:19]
	v_lshl_add_u64 v[32:33], v[160:161], 0, s[14:15]
	v_cvt_pk_bf16_f32 v16, v20, v21
	v_cvt_pk_bf16_f32 v17, v22, v23
	v_cvt_pk_bf16_f32 v18, v24, v25
	v_cvt_pk_bf16_f32 v19, v26, v27
	global_store_dwordx4 v[32:33], v[16:19], off offset:256
	s_nop 1
	v_mov_b32_e32 v16, v199
	s_mov_b32 s5, 0x160000
	s_mov_b64 s[14:15], 0x160000
	v_lshl_add_u64 v[18:19], v[160:161], 0, s[14:15]
	v_fmamk_f32 v16, v16, 0x3a800000, v187
	v_cmp_gt_f32_e32 vcc, s67, v16
	v_mul_f32_e32 v17, 0x4b800000, v16
	s_nop 0
	v_cndmask_b32_e32 v16, v16, v17, vcc
	v_rsq_f32_e32 v16, v16
	s_nop 0
	v_mul_f32_e32 v17, 0x45800000, v16
	v_cndmask_b32_e32 v16, v16, v17, vcc
	v_pk_mul_f32 v[12:13], v[12:13], v[16:17] op_sel_hi:[1,0]
	v_pk_mul_f32 v[8:9], v[8:9], v[16:17] op_sel_hi:[1,0]
	v_pk_mul_f32 v[14:15], v[14:15], v[16:17] op_sel_hi:[1,0]
	v_pk_mul_f32 v[10:11], v[10:11], v[16:17] op_sel_hi:[1,0]
	v_max_f32_e32 v12, 0, v12
	v_max_f32_e32 v8, 0, v8
	v_max_f32_e32 v13, 0, v13
	v_max_f32_e32 v9, 0, v9
	v_pk_mul_f32 v[12:13], v[12:13], v[12:13]
	v_pk_mul_f32 v[20:21], v[8:9], v[8:9]
	v_max_f32_e32 v8, 0, v14
	v_max_f32_e32 v10, 0, v10
	v_max_f32_e32 v9, 0, v15
	v_max_f32_e32 v11, 0, v11
	v_pk_mul_f32 v[14:15], v[8:9], v[8:9]
	v_pk_mul_f32 v[22:23], v[10:11], v[10:11]
	v_cvt_pk_bf16_f32 v8, v12, v13
	v_add_co_u32_e32 v12, vcc, s5, v160
	v_pk_mul_f32 v[0:1], v[0:1], v[16:17] op_sel_hi:[1,0]
	v_cvt_pk_bf16_f32 v9, v14, v15
	v_cvt_pk_bf16_f32 v10, v20, v21
	v_cvt_pk_bf16_f32 v11, v22, v23
	v_addc_co_u32_e32 v13, vcc, 0, v161, vcc
	v_pk_mul_f32 v[6:7], v[6:7], v[16:17] op_sel_hi:[1,0]
	v_pk_mul_f32 v[4:5], v[4:5], v[16:17] op_sel_hi:[1,0]
	v_pk_mul_f32 v[2:3], v[2:3], v[16:17] op_sel_hi:[1,0]
	v_max_f32_e32 v0, 0, v0
	v_max_f32_e32 v1, 0, v1
	global_store_dwordx4 v[12:13], v[8:11], off
	v_max_f32_e32 v4, 0, v4
	v_max_f32_e32 v5, 0, v5
	v_pk_mul_f32 v[8:9], v[0:1], v[0:1]
	v_max_f32_e32 v0, 0, v6
	v_max_f32_e32 v2, 0, v2
	v_max_f32_e32 v1, 0, v7
	v_max_f32_e32 v3, 0, v3
	v_pk_mul_f32 v[4:5], v[4:5], v[4:5]
	v_pk_mul_f32 v[6:7], v[0:1], v[0:1]
	v_pk_mul_f32 v[10:11], v[2:3], v[2:3]
	v_cvt_pk_bf16_f32 v0, v4, v5
	v_cvt_pk_bf16_f32 v1, v6, v7
	v_cvt_pk_bf16_f32 v2, v8, v9
	v_cvt_pk_bf16_f32 v3, v10, v11
	s_and_b64 vcc, exec, s[38:39]
	global_store_dwordx4 v[18:19], v[0:3], off offset:256
	s_cbranch_vccz .LBB0_41
	s_cmpk_gt_u32 s36, 0xff
	s_cbranch_scc1 .LBB0_48
	s_barrier

; #define PG8_WAIT_V(n) asm volatile("s_waitcnt vmcnt(" #n ")" ::: "memory")
; #define PG8_BAR __builtin_amdgcn_s_barrier()
; template <class Epi, class Sched, bool STAMP = false>
; __device__ __forceinline__ void gemm_phase(PG8_LAS unsigned char* lds, const Gemm g, const Sched& S, const Epi& E, unsigned long long* stamps) {
;     ...
;     PG8_WAIT_V(0);
;     if (wr == 0) PG8_BAR;
;     PG8_BAR;
.LBB0_206:
	v_readlane_b32 s88, v242, 39
	s_cmpk_gt_u32 s53, 0xff
	s_movk_i32 s77, 0xa0
	v_readlane_b32 s89, v242, 40
	s_mov_b32 s65, s75
	s_cbranch_scc1 .LBB0_208
	s_barrier

; #define PG8_STAGE(bufoff, gbase, voff) do { _Pragma("unroll") for (int _i = 0; _i < 2; ++_i) \
;         __builtin_amdgcn_global_load_lds((const unsigned*)((const char*)(gbase) + (voff)[_i]), (PG8_LAS unsigned*)(lds + (bufoff) + ldsw + _i * 8192), 16, 0, 0); } while (0)
; #define PG8_LDA(dst, b, h) do { _Pragma("unroll") for (int m = 0; m < 4; ++m) _Pragma("unroll") for (int k = 0; k < 2; ++k) dst[m][k] = *(const PG8_LAS bf16x8*)(lds + PG8_SA(b, h) + aoff + m * 2048 + k * 1024); } while (0)
; #define PG8_LDB(dst, b, h) do { _Pragma("unroll") for (int n = 0; n < 2; ++n) _Pragma("unroll") for (int k = 0; k < 2; ++k) dst[n][k] = *(const PG8_LAS bf16x8*)(lds + PG8_SB(b, h) + boff + n * 2048 + k * 1024); } while (0)
; #define PG8_MMA(ai, bj, At, Bt) do { __builtin_amdgcn_s_setprio(1); _Pragma("unroll") for (int m = 0; m < 4; ++m) _Pragma("unroll") for (int n = 0; n < 2; ++n) _Pragma("unroll") for (int k = 0; k < 2; ++k) \
;         acc[ai][bj][m][n] = __builtin_amdgcn_mfma_f32_16x16x32_bf16(Bt[n][k], At[m][k], acc[ai][bj][m][n], 0, 0, 0); __builtin_amdgcn_s_setprio(0); } while (0)
; #define PG8_WAIT_L(n) asm volatile("s_waitcnt lgkmcnt(" #n ")" ::: "memory")
; #define PG8_BAR __builtin_amdgcn_s_barrier()
; #define PG8_SCHED __builtin_amdgcn_sched_barrier(0)
; template <class Epi, class Sched, bool STAMP = false>
; __device__ __forceinline__ void gemm_phase(PG8_LAS unsigned char* lds, const Gemm g, const Sched& S, const Epi& E, unsigned long long* stamps) {
;     ...
;             const bool last = (t == nt - 2);
;             const char* a1 = cA + (size_t)(t + 1) * kstep;
;             const char* a2 = last ? nA : cA + (size_t)(t + 2) * kstep; const char* b2 = last ? nB : cB + (size_t)(t + 2) * kstep;
;             const char* a3 = a2 + kstep; const char* b3 = b2 + kstep;
;             if (last && has_next) S.a_ready(nxt);
;             PG8_LDB(B0, 0, 0); PG8_SCHED; PG8_LDA(At, 0, 0); PG8_STAGE(PG8_SA(1, 1), a1 + hstep, voffA);
;             PG8_WAIT_L(8); PG8_BAR; PG8_WAIT_L(0); PG8_MMA(0, 0, At, B0); PG8_BAR; PG8_SCHED;
;             PG8_LDB(B1, 0, 1); PG8_STAGE(PG8_SB(0, 0), b2, voffB);
;             PG8_BAR; PG8_WAIT_L(0); PG8_MMA(0, 1, At, B1); PG8_BAR;
;             PG8_LDA(At, 0, 1); PG8_STAGE(PG8_SA(0, 0), a2, voffA);
;             PG8_BAR; PG8_WAIT_L(0); PG8_MMA(1, 0, At, B0); PG8_BAR; PG8_SCHED;
.LBB0_293:
	s_add_u32 s14, s24, 0xfffe0080
	s_addc_u32 s15, s25, -1
	s_add_i32 s16, 0, 0x10000
	v_add_u32_e32 v161, s16, v158
	ds_read_b128 v[162:165], v161
	ds_read_b128 v[166:169], v161 offset:1024
	ds_read_b128 v[170:173], v161 offset:2048
	ds_read_b128 v[174:177], v161 offset:3072
	s_cmp_eq_u32 s59, 4
	s_cselect_b32 s31, s7, s15
	s_cselect_b32 s30, s53, s14
	s_cselect_b32 s27, s5, s58
	s_cselect_b32 s26, s56, s57
	v_lshl_add_u64 v[182:183], s[24:25], 0, v[154:155]
	s_add_i32 m0, s3, 0xc000
	ds_read_b128 v[178:181], v160
	ds_read_b128 v[192:195], v160 offset:1024
	ds_read_b128 v[196:199], v160 offset:2048
	ds_read_b128 v[200:203], v160 offset:3072
	ds_read_b128 v[204:207], v160 offset:4096
	ds_read_b128 v[208:211], v160 offset:5120
	ds_read_b128 v[212:215], v160 offset:6144
	ds_read_b128 v[216:219], v160 offset:7168
	global_load_lds_dwordx4 v[182:183], off
	v_lshl_add_u64 v[182:183], s[24:25], 0, v[156:157]
	s_add_i32 m0, s3, 0xe000
	s_nop 0
	global_load_lds_dwordx4 v[182:183], off
	s_waitcnt lgkmcnt(8)
	s_barrier
	s_waitcnt lgkmcnt(0)
	s_setprio 1
	s_waitcnt lgkmcnt(0)
	v_mfma_f32_16x16x32_bf16 v[124:127], v[162:165], v[178:181], v[124:127]
	v_mfma_f32_16x16x32_bf16 v[120:123], v[170:173], v[178:181], v[120:123]
	v_mfma_f32_16x16x32_bf16 v[116:119], v[162:165], v[196:199], v[116:119]
	v_mfma_f32_16x16x32_bf16 v[112:115], v[170:173], v[196:199], v[112:115]
	v_mfma_f32_16x16x32_bf16 v[100:103], v[162:165], v[204:207], v[100:103]
	v_mfma_f32_16x16x32_bf16 v[96:99], v[170:173], v[204:207], v[96:99]
	v_mfma_f32_16x16x32_bf16 v[84:87], v[162:165], v[212:215], v[84:87]
	v_mfma_f32_16x16x32_bf16 v[80:83], v[170:173], v[212:215], v[80:83]
	v_mfma_f32_16x16x32_bf16 v[124:127], v[166:169], v[192:195], v[124:127]
	v_mfma_f32_16x16x32_bf16 v[120:123], v[174:177], v[192:195], v[120:123]
	v_mfma_f32_16x16x32_bf16 v[116:119], v[166:169], v[200:203], v[116:119]
	v_mfma_f32_16x16x32_bf16 v[112:115], v[174:177], v[200:203], v[112:115]
	v_mfma_f32_16x16x32_bf16 v[100:103], v[166:169], v[208:211], v[100:103]
	v_mfma_f32_16x16x32_bf16 v[96:99], v[174:177], v[208:211], v[96:99]
	v_mfma_f32_16x16x32_bf16 v[84:87], v[166:169], v[216:219], v[84:87]
	v_mfma_f32_16x16x32_bf16 v[80:83], v[174:177], v[216:219], v[80:83]
	s_setprio 0
	s_barrier
	s_add_i32 s17, 0, 0x14000
	s_add_i32 s14, s16, s40
	v_add_u32_e32 v161, s17, v158
	v_lshl_add_u64 v[182:183], s[26:27], 0, v[128:129]
	s_mov_b32 m0, s14
	ds_read_b128 v[220:223], v161
	ds_read_b128 v[224:227], v161 offset:1024
	ds_read_b128 v[228:231], v161 offset:2048
	ds_read_b128 v[232:235], v161 offset:3072
	global_load_lds_dwordx4 v[182:183], off
	v_lshl_add_u64 v[236:237], s[26:27], 0, v[152:153]
	s_add_i32 m0, s14, 0x2000
	s_nop 0
	global_load_lds_dwordx4 v[236:237], off
	s_barrier
	s_waitcnt lgkmcnt(0)
	s_setprio 1
	s_waitcnt lgkmcnt(0)
	v_mfma_f32_16x16x32_bf16 v[108:111], v[220:223], v[178:181], v[108:111]
	v_mfma_f32_16x16x32_bf16 v[104:107], v[228:231], v[178:181], v[104:107]
	v_mfma_f32_16x16x32_bf16 v[92:95], v[220:223], v[196:199], v[92:95]
	v_mfma_f32_16x16x32_bf16 v[88:91], v[228:231], v[196:199], v[88:91]
	v_mfma_f32_16x16x32_bf16 v[76:79], v[220:223], v[204:207], v[76:79]
	v_mfma_f32_16x16x32_bf16 v[72:75], v[228:231], v[204:207], v[72:75]
	v_mfma_f32_16x16x32_bf16 v[68:71], v[220:223], v[212:215], v[68:71]
	v_mfma_f32_16x16x32_bf16 v[64:67], v[228:231], v[212:215], v[64:67]
	v_mfma_f32_16x16x32_bf16 v[108:111], v[224:227], v[192:195], v[108:111]
	v_mfma_f32_16x16x32_bf16 v[104:107], v[232:235], v[192:195], v[104:107]
	v_mfma_f32_16x16x32_bf16 v[92:95], v[224:227], v[200:203], v[92:95]
	v_mfma_f32_16x16x32_bf16 v[88:91], v[232:235], v[200:203], v[88:91]
	v_mfma_f32_16x16x32_bf16 v[76:79], v[224:227], v[208:211], v[76:79]
	v_mfma_f32_16x16x32_bf16 v[72:75], v[232:235], v[208:211], v[72:75]
	v_mfma_f32_16x16x32_bf16 v[68:71], v[224:227], v[216:219], v[68:71]
	v_mfma_f32_16x16x32_bf16 v[64:67], v[232:235], v[216:219], v[64:67]
	s_setprio 0
	s_mov_b32 m0, s3
	v_lshl_add_u64 v[238:239], s[30:31], 0, v[148:149]
	s_barrier
	ds_read_b128 v[178:181], v160 offset:16384
	ds_read_b128 v[192:195], v160 offset:17408
	ds_read_b128 v[196:199], v160 offset:18432
	ds_read_b128 v[200:203], v160 offset:19456
	ds_read_b128 v[204:207], v160 offset:20480
	ds_read_b128 v[208:211], v160 offset:21504
	ds_read_b128 v[212:215], v160 offset:22528
	ds_read_b128 v[216:219], v160 offset:23552
	global_load_lds_dwordx4 v[238:239], off
	v_lshl_add_u64 v[240:241], s[30:31], 0, v[150:151]
	s_mov_b32 m0, s41
	s_nop 0
	global_load_lds_dwordx4 v[240:241], off
	s_barrier
	s_waitcnt lgkmcnt(0)
	s_setprio 1
	s_waitcnt lgkmcnt(0)
	v_mfma_f32_16x16x32_bf16 v[60:63], v[162:165], v[178:181], v[60:63]
	v_mfma_f32_16x16x32_bf16 v[56:59], v[170:173], v[178:181], v[56:59]
	v_mfma_f32_16x16x32_bf16 v[52:55], v[162:165], v[196:199], v[52:55]
	v_mfma_f32_16x16x32_bf16 v[48:51], v[170:173], v[196:199], v[48:51]
	v_mfma_f32_16x16x32_bf16 v[36:39], v[162:165], v[204:207], v[36:39]
	v_mfma_f32_16x16x32_bf16 v[32:35], v[170:173], v[204:207], v[32:35]
	v_mfma_f32_16x16x32_bf16 v[20:23], v[162:165], v[212:215], v[20:23]
	v_mfma_f32_16x16x32_bf16 v[16:19], v[170:173], v[212:215], v[16:19]
	v_mfma_f32_16x16x32_bf16 v[60:63], v[166:169], v[192:195], v[60:63]
	v_mfma_f32_16x16x32_bf16 v[56:59], v[174:177], v[192:195], v[56:59]
	v_mfma_f32_16x16x32_bf16 v[52:55], v[166:169], v[200:203], v[52:55]
	v_mfma_f32_16x16x32_bf16 v[48:51], v[174:177], v[200:203], v[48:51]
	v_mfma_f32_16x16x32_bf16 v[36:39], v[166:169], v[208:211], v[36:39]
	v_mfma_f32_16x16x32_bf16 v[32:35], v[174:177], v[208:211], v[32:35]
	v_mfma_f32_16x16x32_bf16 v[20:23], v[166:169], v[216:219], v[20:23]
	v_mfma_f32_16x16x32_bf16 v[16:19], v[174:177], v[216:219], v[16:19]
	s_setprio 0
	s_barrier
; #define PG8_STAGE(bufoff, gbase, voff) do { _Pragma("unroll") for (int _i = 0; _i < 2; ++_i) \
;         __builtin_amdgcn_global_load_lds((const unsigned*)((const char*)(gbase) + (voff)[_i]), (PG8_LAS unsigned*)(lds + (bufoff) + ldsw + _i * 8192), 16, 0, 0); } while (0)
; #define PG8_LDA(dst, b, h) do { _Pragma("unroll") for (int m = 0; m < 4; ++m) _Pragma("unroll") for (int k = 0; k < 2; ++k) dst[m][k] = *(const PG8_LAS bf16x8*)(lds + PG8_SA(b, h) + aoff + m * 2048 + k * 1024); } while (0)
; #define PG8_LDB(dst, b, h) do { _Pragma("unroll") for (int n = 0; n < 2; ++n) _Pragma("unroll") for (int k = 0; k < 2; ++k) dst[n][k] = *(const PG8_LAS bf16x8*)(lds + PG8_SB(b, h) + boff + n * 2048 + k * 1024); } while (0)
; #define PG8_MMA(ai, bj, At, Bt) do { __builtin_amdgcn_s_setprio(1); _Pragma("unroll") for (int m = 0; m < 4; ++m) _Pragma("unroll") for (int n = 0; n < 2; ++n) _Pragma("unroll") for (int k = 0; k < 2; ++k) \
;         acc[ai][bj][m][n] = __builtin_amdgcn_mfma_f32_16x16x32_bf16(Bt[n][k], At[m][k], acc[ai][bj][m][n], 0, 0, 0); __builtin_amdgcn_s_setprio(0); } while (0)
; #define PG8_WAIT_V(n) asm volatile("s_waitcnt vmcnt(" #n ")" ::: "memory")
; #define PG8_WAIT_L(n) asm volatile("s_waitcnt lgkmcnt(" #n ")" ::: "memory")
; #define PG8_BAR __builtin_amdgcn_s_barrier()
; #define PG8_SCHED __builtin_amdgcn_sched_barrier(0)
; template <class Epi, class Sched, bool STAMP = false>
; __device__ __forceinline__ void gemm_phase(PG8_LAS unsigned char* lds, const Gemm g, const Sched& S, const Epi& E, unsigned long long* stamps) {
;     ...
;             PG8_STAGE(PG8_SB(0, 1), b2 + hstep, voffB);
;             PG8_WAIT_V(6); PG8_BAR; PG8_MMA(1, 1, At, B1); PG8_BAR;
;             PG8_LDB(B0, 1, 0); PG8_SCHED; PG8_LDA(At, 1, 0); PG8_STAGE(PG8_SA(0, 1), a2 + hstep, voffA);
;             PG8_WAIT_L(8); PG8_BAR; PG8_WAIT_L(0); PG8_MMA(0, 0, At, B0); PG8_BAR; PG8_SCHED;
;             PG8_LDB(B1, 1, 1); PG8_STAGE(PG8_SB(1, 0), b3, voffB);
;             PG8_BAR; PG8_WAIT_L(0); PG8_MMA(0, 1, At, B1); PG8_BAR;
;             PG8_LDA(At, 1, 1); PG8_STAGE(PG8_SA(1, 0), a3, voffA);
	s_add_u32 s14, s26, 0x20000
	s_addc_u32 s15, s27, 0
	s_add_i32 s16, s17, s40
	v_lshl_add_u64 v[162:163], s[14:15], 0, v[128:129]
	s_mov_b32 m0, s16
	s_nop 0
	global_load_lds_dwordx4 v[162:163], off
	v_lshl_add_u64 v[162:163], s[14:15], 0, v[152:153]
	s_add_i32 m0, s16, 0x2000
	s_nop 0
	global_load_lds_dwordx4 v[162:163], off
	s_waitcnt vmcnt(6)
	s_barrier
	s_setprio 1
	v_mfma_f32_16x16x32_bf16 v[44:47], v[220:223], v[178:181], v[44:47]
	v_mfma_f32_16x16x32_bf16 v[40:43], v[228:231], v[178:181], v[40:43]
	v_mfma_f32_16x16x32_bf16 v[28:31], v[220:223], v[196:199], v[28:31]
	v_mfma_f32_16x16x32_bf16 v[24:27], v[228:231], v[196:199], v[24:27]
	v_mfma_f32_16x16x32_bf16 v[12:15], v[220:223], v[204:207], v[12:15]
	v_mfma_f32_16x16x32_bf16 v[8:11], v[228:231], v[204:207], v[8:11]
	v_mfma_f32_16x16x32_bf16 v[4:7], v[220:223], v[212:215], v[4:7]
	v_mfma_f32_16x16x32_bf16 v[0:3], v[228:231], v[212:215], v[0:3]
	v_mfma_f32_16x16x32_bf16 v[44:47], v[224:227], v[192:195], v[44:47]
	v_mfma_f32_16x16x32_bf16 v[40:43], v[232:235], v[192:195], v[40:43]
	v_mfma_f32_16x16x32_bf16 v[28:31], v[224:227], v[200:203], v[28:31]
	v_mfma_f32_16x16x32_bf16 v[24:27], v[232:235], v[200:203], v[24:27]
	v_mfma_f32_16x16x32_bf16 v[12:15], v[224:227], v[208:211], v[12:15]
	v_mfma_f32_16x16x32_bf16 v[8:11], v[232:235], v[208:211], v[8:11]
	v_mfma_f32_16x16x32_bf16 v[4:7], v[224:227], v[216:219], v[4:7]
	v_mfma_f32_16x16x32_bf16 v[0:3], v[232:235], v[216:219], v[0:3]
	s_setprio 0
	s_add_i32 s16, 0, 0x18000
	v_add_u32_e32 v161, s16, v158
	s_barrier
	ds_read_b128 v[162:165], v161
	ds_read_b128 v[166:169], v161 offset:1024
	ds_read_b128 v[170:173], v161 offset:2048
	ds_read_b128 v[174:177], v161 offset:3072
	s_add_u32 s14, s30, 0x20000
	s_addc_u32 s15, s31, 0
	s_mov_b32 m0, s42
	v_lshl_add_u64 v[220:221], s[14:15], 0, v[148:149]
	ds_read_b128 v[178:181], v160 offset:32768
	ds_read_b128 v[192:195], v160 offset:33792
	ds_read_b128 v[196:199], v160 offset:34816
	ds_read_b128 v[200:203], v160 offset:35840
	ds_read_b128 v[204:207], v160 offset:36864
	ds_read_b128 v[208:211], v160 offset:37888
	ds_read_b128 v[212:215], v160 offset:38912
	ds_read_b128 v[216:219], v160 offset:39936
	global_load_lds_dwordx4 v[220:221], off
	v_lshl_add_u64 v[220:221], s[14:15], 0, v[150:151]
	s_mov_b32 m0, s43
	s_nop 0
	global_load_lds_dwordx4 v[220:221], off
	s_waitcnt lgkmcnt(8)
	s_barrier
	s_waitcnt lgkmcnt(0)
	s_setprio 1
	s_waitcnt lgkmcnt(0)
	v_mfma_f32_16x16x32_bf16 v[124:127], v[162:165], v[178:181], v[124:127]
	v_mfma_f32_16x16x32_bf16 v[120:123], v[170:173], v[178:181], v[120:123]
	v_mfma_f32_16x16x32_bf16 v[116:119], v[162:165], v[196:199], v[116:119]
	v_mfma_f32_16x16x32_bf16 v[112:115], v[170:173], v[196:199], v[112:115]
	v_mfma_f32_16x16x32_bf16 v[100:103], v[162:165], v[204:207], v[100:103]
	v_mfma_f32_16x16x32_bf16 v[96:99], v[170:173], v[204:207], v[96:99]
	v_mfma_f32_16x16x32_bf16 v[84:87], v[162:165], v[212:215], v[84:87]
	v_mfma_f32_16x16x32_bf16 v[80:83], v[170:173], v[212:215], v[80:83]
	v_mfma_f32_16x16x32_bf16 v[124:127], v[166:169], v[192:195], v[124:127]
	v_mfma_f32_16x16x32_bf16 v[120:123], v[174:177], v[192:195], v[120:123]
	v_mfma_f32_16x16x32_bf16 v[116:119], v[166:169], v[200:203], v[116:119]
	v_mfma_f32_16x16x32_bf16 v[112:115], v[174:177], v[200:203], v[112:115]
	v_mfma_f32_16x16x32_bf16 v[100:103], v[166:169], v[208:211], v[100:103]
	v_mfma_f32_16x16x32_bf16 v[96:99], v[174:177], v[208:211], v[96:99]
	v_mfma_f32_16x16x32_bf16 v[84:87], v[166:169], v[216:219], v[84:87]
	v_mfma_f32_16x16x32_bf16 v[80:83], v[174:177], v[216:219], v[80:83]
	s_setprio 0
	s_barrier
	s_add_i32 s17, 0, 0x1c000
	s_add_i32 s14, s16, s40
	v_add_u32_e32 v161, s17, v158
	v_lshl_add_u64 v[182:183], v[182:183], 0, s[18:19]
	s_mov_b32 m0, s14
	ds_read_b128 v[220:223], v161
	ds_read_b128 v[224:227], v161 offset:1024
	ds_read_b128 v[228:231], v161 offset:2048
	ds_read_b128 v[232:235], v161 offset:3072
	global_load_lds_dwordx4 v[182:183], off
	v_lshl_add_u64 v[182:183], v[236:237], 0, s[18:19]
	s_add_i32 m0, s14, 0x2000
	s_nop 0
	global_load_lds_dwordx4 v[182:183], off
	s_barrier
	s_waitcnt lgkmcnt(0)
	s_setprio 1
	s_waitcnt lgkmcnt(0)
	v_mfma_f32_16x16x32_bf16 v[108:111], v[220:223], v[178:181], v[108:111]
	v_mfma_f32_16x16x32_bf16 v[104:107], v[228:231], v[178:181], v[104:107]
	v_mfma_f32_16x16x32_bf16 v[92:95], v[220:223], v[196:199], v[92:95]
	v_mfma_f32_16x16x32_bf16 v[88:91], v[228:231], v[196:199], v[88:91]
	v_mfma_f32_16x16x32_bf16 v[76:79], v[220:223], v[204:207], v[76:79]
	v_mfma_f32_16x16x32_bf16 v[72:75], v[228:231], v[204:207], v[72:75]
	v_mfma_f32_16x16x32_bf16 v[68:71], v[220:223], v[212:215], v[68:71]
	v_mfma_f32_16x16x32_bf16 v[64:67], v[228:231], v[212:215], v[64:67]
	v_mfma_f32_16x16x32_bf16 v[108:111], v[224:227], v[192:195], v[108:111]
	v_mfma_f32_16x16x32_bf16 v[104:107], v[232:235], v[192:195], v[104:107]
	v_mfma_f32_16x16x32_bf16 v[92:95], v[224:227], v[200:203], v[92:95]
	v_mfma_f32_16x16x32_bf16 v[88:91], v[232:235], v[200:203], v[88:91]
	v_mfma_f32_16x16x32_bf16 v[76:79], v[224:227], v[208:211], v[76:79]
	v_mfma_f32_16x16x32_bf16 v[72:75], v[232:235], v[208:211], v[72:75]
	v_mfma_f32_16x16x32_bf16 v[68:71], v[224:227], v[216:219], v[68:71]
	v_mfma_f32_16x16x32_bf16 v[64:67], v[232:235], v[216:219], v[64:67]
	s_setprio 0
	s_mov_b32 m0, s46
	v_lshl_add_u64 v[182:183], v[238:239], 0, s[18:19]
	s_barrier
	ds_read_b128 v[178:181], v160 offset:49152
	ds_read_b128 v[192:195], v160 offset:50176
	ds_read_b128 v[196:199], v160 offset:51200
	ds_read_b128 v[200:203], v160 offset:52224
	ds_read_b128 v[204:207], v160 offset:53248
	ds_read_b128 v[208:211], v160 offset:54272
	ds_read_b128 v[212:215], v160 offset:55296
	ds_read_b128 v[216:219], v160 offset:56320
	global_load_lds_dwordx4 v[182:183], off
	v_lshl_add_u64 v[182:183], v[240:241], 0, s[18:19]
	s_mov_b32 m0, s47
	s_nop 0
	global_load_lds_dwordx4 v[182:183], off
	s_barrier
; #define PG8_STAGE(bufoff, gbase, voff) do { _Pragma("unroll") for (int _i = 0; _i < 2; ++_i) \
;         __builtin_amdgcn_global_load_lds((const unsigned*)((const char*)(gbase) + (voff)[_i]), (PG8_LAS unsigned*)(lds + (bufoff) + ldsw + _i * 8192), 16, 0, 0); } while (0)
; #define PG8_MMA(ai, bj, At, Bt) do { __builtin_amdgcn_s_setprio(1); _Pragma("unroll") for (int m = 0; m < 4; ++m) _Pragma("unroll") for (int n = 0; n < 2; ++n) _Pragma("unroll") for (int k = 0; k < 2; ++k) \
;         acc[ai][bj][m][n] = __builtin_amdgcn_mfma_f32_16x16x32_bf16(Bt[n][k], At[m][k], acc[ai][bj][m][n], 0, 0, 0); __builtin_amdgcn_s_setprio(0); } while (0)
; #define PG8_WAIT_V(n) asm volatile("s_waitcnt vmcnt(" #n ")" ::: "memory")
; #define PG8_WAIT_L(n) asm volatile("s_waitcnt lgkmcnt(" #n ")" ::: "memory")
; #define PG8_BAR __builtin_amdgcn_s_barrier()
; #define PG8_SCHED __builtin_amdgcn_sched_barrier(0)
; template <class Epi, class Sched, bool STAMP = false>
; __device__ __forceinline__ void gemm_phase(PG8_LAS unsigned char* lds, const Gemm g, const Sched& S, const Epi& E, unsigned long long* stamps) {
;     ...
;             PG8_BAR; PG8_WAIT_L(0); PG8_MMA(1, 0, At, B0); PG8_BAR; PG8_SCHED;
;             PG8_STAGE(PG8_SB(1, 1), b3 + hstep, voffB);
;             PG8_WAIT_V(6); PG8_BAR; PG8_MMA(1, 1, At, B1); PG8_BAR;
	s_waitcnt lgkmcnt(0)
	s_setprio 1
	s_waitcnt lgkmcnt(0)
	v_mfma_f32_16x16x32_bf16 v[60:63], v[162:165], v[178:181], v[60:63]
	v_mfma_f32_16x16x32_bf16 v[56:59], v[170:173], v[178:181], v[56:59]
	v_mfma_f32_16x16x32_bf16 v[52:55], v[162:165], v[196:199], v[52:55]
	v_mfma_f32_16x16x32_bf16 v[48:51], v[170:173], v[196:199], v[48:51]
	v_mfma_f32_16x16x32_bf16 v[36:39], v[162:165], v[204:207], v[36:39]
	v_mfma_f32_16x16x32_bf16 v[32:35], v[170:173], v[204:207], v[32:35]
	v_mfma_f32_16x16x32_bf16 v[20:23], v[162:165], v[212:215], v[20:23]
	v_mfma_f32_16x16x32_bf16 v[16:19], v[170:173], v[212:215], v[16:19]
	v_mfma_f32_16x16x32_bf16 v[60:63], v[166:169], v[192:195], v[60:63]
	v_mfma_f32_16x16x32_bf16 v[56:59], v[174:177], v[192:195], v[56:59]
	v_mfma_f32_16x16x32_bf16 v[52:55], v[166:169], v[200:203], v[52:55]
	v_mfma_f32_16x16x32_bf16 v[48:51], v[174:177], v[200:203], v[48:51]
	v_mfma_f32_16x16x32_bf16 v[36:39], v[166:169], v[208:211], v[36:39]
	v_mfma_f32_16x16x32_bf16 v[32:35], v[174:177], v[208:211], v[32:35]
	v_mfma_f32_16x16x32_bf16 v[20:23], v[166:169], v[216:219], v[20:23]
	v_mfma_f32_16x16x32_bf16 v[16:19], v[174:177], v[216:219], v[16:19]
	s_setprio 0
	s_barrier
	s_add_u32 s14, s26, 0x20080
	s_addc_u32 s15, s27, 0
	s_add_i32 s16, s17, s40
	v_lshl_add_u64 v[162:163], s[14:15], 0, v[128:129]
	s_mov_b32 m0, s16
	s_nop 0
	global_load_lds_dwordx4 v[162:163], off
	v_lshl_add_u64 v[162:163], s[14:15], 0, v[152:153]
	s_add_i32 m0, s16, 0x2000
	s_nop 0
	global_load_lds_dwordx4 v[162:163], off
	s_waitcnt vmcnt(6)
	s_barrier
	s_setprio 1
	v_mfma_f32_16x16x32_bf16 v[44:47], v[220:223], v[178:181], v[44:47]
	v_mfma_f32_16x16x32_bf16 v[40:43], v[228:231], v[178:181], v[40:43]
	v_mfma_f32_16x16x32_bf16 v[28:31], v[220:223], v[196:199], v[28:31]
	v_mfma_f32_16x16x32_bf16 v[24:27], v[228:231], v[196:199], v[24:27]
	v_mfma_f32_16x16x32_bf16 v[12:15], v[220:223], v[204:207], v[12:15]
	v_mfma_f32_16x16x32_bf16 v[8:11], v[228:231], v[204:207], v[8:11]
	v_mfma_f32_16x16x32_bf16 v[4:7], v[220:223], v[212:215], v[4:7]
	v_mfma_f32_16x16x32_bf16 v[0:3], v[228:231], v[212:215], v[0:3]
	v_mfma_f32_16x16x32_bf16 v[44:47], v[224:227], v[192:195], v[44:47]
	v_mfma_f32_16x16x32_bf16 v[40:43], v[232:235], v[192:195], v[40:43]
	v_mfma_f32_16x16x32_bf16 v[28:31], v[224:227], v[200:203], v[28:31]
	v_mfma_f32_16x16x32_bf16 v[24:27], v[232:235], v[200:203], v[24:27]
	v_mfma_f32_16x16x32_bf16 v[12:15], v[224:227], v[208:211], v[12:15]
	v_mfma_f32_16x16x32_bf16 v[8:11], v[232:235], v[208:211], v[8:11]
	v_mfma_f32_16x16x32_bf16 v[4:7], v[224:227], v[216:219], v[4:7]
	v_mfma_f32_16x16x32_bf16 v[0:3], v[232:235], v[216:219], v[0:3]
	s_setprio 0
	s_add_i32 s59, s59, 2
	s_add_u32 s24, s24, 0x100
	s_addc_u32 s25, s25, 0
	s_add_u32 s57, s57, 0x100
	s_addc_u32 s58, s58, 0
	s_cmp_gt_u32 s59, 5
	s_barrier
	s_cbranch_scc0 .LBB0_293
; __device__ __forceinline__ unsigned cvt_pk_bf16(float lo, float hi) { const f32x2_cv v = {lo, hi}; const bf16x2_cv b = __builtin_convertvector(v, bf16x2_cv); return __builtin_bit_cast(unsigned, b); }
; #define PG8_WAIT_V(n) asm volatile("s_waitcnt vmcnt(" #n ")" ::: "memory")
; #define PG8_BAR __builtin_amdgcn_s_barrier()
; __device__ __forceinline__ float rstd_of(const float* rowss, int row) { return rsqrtf(rowss[row] * (1.0f / 1024.0f) + 1e-6f); }
; template <class Epi, class Sched, bool STAMP = false>
; __device__ __forceinline__ void gemm_phase(PG8_LAS unsigned char* lds, const Gemm g, const Sched& S, const Epi& E, unsigned long long* stamps) {
;     ...
;         if (!has_next) break;
; #pragma unroll
;         for (int a = 0; a < 2; ++a)
; #pragma unroll
;             for (int b = 0; b < 2; ++b)
; #pragma unroll
;                 for (int m = 0; m < 4; ++m)
; #pragma unroll
;                     for (int n = 0; n < 2; ++n) acc[a][b][m][n] = (f32x4){0.f, 0.f, 0.f, 0.f};
;         cur = nxt; cA = nA; cB = nB; ++ui;
;     }
;     PG8_WAIT_V(0);
;     if (wr == 0) PG8_BAR;
;     PG8_BAR;
;     __device__ __forceinline__ void operator()(const f32x4 (&acc)[2][2][4][2], const pg8::Unit& u, int wr, int wc, int fr, int fq) const {
;         const int row0 = u.pm * 256 + wr * 64 + fr, col0 = u.pn * 256 + wc * 32 + 8 * fq;
; #pragma unroll
;         for (int ai = 0; ai < 2; ++ai)
; #pragma unroll
;             for (int m = 0; m < 4; ++m) {
;                 const int row = row0 + ai * 128 + m * 16;
;                 const float s = (MODE == 2) ? 1.0f : rstd_of(rowss, row);
;                 bf16_t* rowp = O + (size_t)row * ldc + col0;
; #pragma unroll
;                 for (int bj = 0; bj < 2; ++bj) {
;                     f32x4 v0 = acc[ai][bj][m][0] * s, v1 = acc[ai][bj][m][1] * s;
;                     if (MODE == 1) {
; #pragma unroll
;                         for (int j = 0; j < 4; ++j) { const float a = fmaxf(v0[j], 0.f), b = fmaxf(v1[j], 0.f); v0[j] = a * a; v1[j] = b * b; } }
;                     u32x4 w; w.x = cvt_pk_bf16(v0[0], v0[1]); w.y = cvt_pk_bf16(v0[2], v0[3]); w.z = cvt_pk_bf16(v1[0], v1[1]); w.w = cvt_pk_bf16(v1[2], v1[3]);
;                     *(u32x4*)(rowp + bj * 128) = w; } }
	v_lshl_add_u32 v162, s2, 8, v139
	v_lshl_or_b32 v164, s49, 8, v159
	v_ashrrev_i32_e32 v163, 31, v162
	v_ashrrev_i32_e32 v165, 31, v164
	v_lshlrev_b64 v[166:167], 11, v[162:163]
	v_lshl_add_u64 v[166:167], s[0:1], 0, v[166:167]
	v_lshlrev_b64 v[164:165], 1, v[164:165]
	v_lshl_add_u64 v[166:167], v[166:167], 0, v[164:165]
	s_mov_b32 s2, 0x40000
	s_mov_b64 s[14:15], 0x40000
	v_cvt_pk_bf16_f32 v60, v60, v61
	v_cvt_pk_bf16_f32 v61, v62, v63
	v_cvt_pk_bf16_f32 v62, v56, v57
	v_add_co_u32_e32 v56, vcc, s2, v166
	v_cvt_pk_bf16_f32 v68, v68, v69
	v_cvt_pk_bf16_f32 v69, v70, v71
	v_cvt_pk_bf16_f32 v70, v64, v65
	v_lshl_add_u64 v[64:65], v[166:167], 0, s[14:15]
	v_addc_co_u32_e32 v57, vcc, 0, v167, vcc
	v_cvt_pk_bf16_f32 v44, v44, v45
	v_cvt_pk_bf16_f32 v45, v46, v47
	v_cvt_pk_bf16_f32 v46, v40, v41
	v_cvt_pk_bf16_f32 v47, v42, v43
	s_mov_b32 s2, 0x48000
	v_cvt_pk_bf16_f32 v108, v108, v109
	v_cvt_pk_bf16_f32 v109, v110, v111
	v_cvt_pk_bf16_f32 v110, v104, v105
	v_or_b32_e32 v104, 16, v162
	global_store_dwordx4 v[64:65], v[44:47], off offset:256
	s_mov_b64 s[14:15], 0x48000
	v_ashrrev_i32_e32 v105, 31, v104
	v_add_co_u32_e32 v46, vcc, s2, v166
	v_cvt_pk_bf16_f32 v92, v92, v93
	v_cvt_pk_bf16_f32 v93, v94, v95
	v_cvt_pk_bf16_f32 v94, v88, v89
	v_or_b32_e32 v88, 32, v162
	v_lshl_add_u64 v[44:45], v[166:167], 0, s[14:15]
	v_addc_co_u32_e32 v47, vcc, 0, v167, vcc
	v_cvt_pk_bf16_f32 v28, v28, v29
	v_cvt_pk_bf16_f32 v29, v30, v31
	v_cvt_pk_bf16_f32 v30, v24, v25
	v_cvt_pk_bf16_f32 v31, v26, v27
	s_mov_b32 s2, 0x50000
	v_lshlrev_b64 v[104:105], 11, v[104:105]
	v_ashrrev_i32_e32 v89, 31, v88
	v_cvt_pk_bf16_f32 v76, v76, v77
	v_cvt_pk_bf16_f32 v77, v78, v79
	v_cvt_pk_bf16_f32 v78, v72, v73
	v_or_b32_e32 v72, 48, v162
	global_store_dwordx4 v[44:45], v[28:31], off offset:256
	s_mov_b64 s[14:15], 0x50000
	v_cvt_pk_bf16_f32 v111, v106, v107
	v_add_co_u32_e32 v30, vcc, s2, v166
	v_lshl_add_u64 v[104:105], s[0:1], 0, v[104:105]
	v_lshlrev_b64 v[88:89], 11, v[88:89]
	v_ashrrev_i32_e32 v73, 31, v72
	v_lshl_add_u64 v[28:29], v[166:167], 0, s[14:15]
	v_addc_co_u32_e32 v31, vcc, 0, v167, vcc
	v_cvt_pk_bf16_f32 v12, v12, v13
	v_cvt_pk_bf16_f32 v13, v14, v15
	v_cvt_pk_bf16_f32 v14, v8, v9
	v_cvt_pk_bf16_f32 v15, v10, v11
	s_mov_b32 s2, 0x58000
	global_store_dwordx4 v[166:167], v[108:111], off offset:256
	v_cvt_pk_bf16_f32 v95, v90, v91
	v_lshl_add_u64 v[88:89], s[0:1], 0, v[88:89]
	v_lshl_add_u64 v[108:109], v[104:105], 0, v[164:165]
	v_lshlrev_b64 v[72:73], 11, v[72:73]
	global_store_dwordx4 v[28:29], v[12:15], off offset:256
	global_store_dwordx4 v[108:109], v[92:95], off offset:256
	v_cvt_pk_bf16_f32 v79, v74, v75
	v_add_co_u32_e32 v14, vcc, s2, v166
	v_lshl_add_u64 v[92:93], v[88:89], 0, v[164:165]
	v_lshl_add_u64 v[72:73], s[0:1], 0, v[72:73]
	s_mov_b64 s[14:15], 0x58000
	v_addc_co_u32_e32 v15, vcc, 0, v167, vcc
	v_cvt_pk_bf16_f32 v124, v124, v125
	v_cvt_pk_bf16_f32 v125, v126, v127
	v_cvt_pk_bf16_f32 v126, v120, v121
	v_cvt_pk_bf16_f32 v127, v122, v123
	v_cvt_pk_bf16_f32 v104, v116, v117
	v_cvt_pk_bf16_f32 v105, v118, v119
	v_cvt_pk_bf16_f32 v106, v112, v113
	v_cvt_pk_bf16_f32 v107, v114, v115
	v_cvt_pk_bf16_f32 v88, v100, v101
	v_cvt_pk_bf16_f32 v89, v102, v103
	v_cvt_pk_bf16_f32 v90, v96, v97
	v_cvt_pk_bf16_f32 v91, v98, v99
	global_store_dwordx4 v[92:93], v[76:79], off offset:256
	v_cvt_pk_bf16_f32 v74, v80, v81
	v_cvt_pk_bf16_f32 v75, v82, v83
	v_lshl_add_u64 v[76:77], v[72:73], 0, v[164:165]
	v_cvt_pk_bf16_f32 v72, v84, v85
	v_cvt_pk_bf16_f32 v73, v86, v87
	v_cvt_pk_bf16_f32 v71, v66, v67
	v_cvt_pk_bf16_f32 v63, v58, v59
	v_cvt_pk_bf16_f32 v40, v52, v53
	v_cvt_pk_bf16_f32 v41, v54, v55
	v_cvt_pk_bf16_f32 v42, v48, v49
	v_cvt_pk_bf16_f32 v43, v50, v51
	v_cvt_pk_bf16_f32 v24, v36, v37
	v_cvt_pk_bf16_f32 v25, v38, v39
	v_cvt_pk_bf16_f32 v26, v32, v33
	v_cvt_pk_bf16_f32 v27, v34, v35
	v_lshl_add_u64 v[12:13], v[166:167], 0, s[14:15]
	v_cvt_pk_bf16_f32 v8, v20, v21
	v_cvt_pk_bf16_f32 v9, v22, v23
	v_cvt_pk_bf16_f32 v10, v16, v17
	v_cvt_pk_bf16_f32 v11, v18, v19
	v_cvt_pk_bf16_f32 v4, v4, v5
	v_cvt_pk_bf16_f32 v5, v6, v7
	v_cvt_pk_bf16_f32 v6, v0, v1
	v_cvt_pk_bf16_f32 v7, v2, v3
	s_and_b64 vcc, exec, s[38:39]
	s_mov_b32 s49, s4
	s_mov_b32 s2, s6
	s_mov_b64 s[26:27], s[22:23]
	s_mov_b64 s[24:25], s[12:13]
	s_movk_i32 s58, 0xff60
	global_store_dwordx4 v[166:167], v[124:127], off
	global_store_dwordx4 v[108:109], v[104:107], off
	global_store_dwordx4 v[92:93], v[88:91], off
	global_store_dwordx4 v[76:77], v[72:75], off
	global_store_dwordx4 v[76:77], v[68:71], off offset:256
	global_store_dwordx4 v[56:57], v[60:63], off
	global_store_dwordx4 v[46:47], v[40:43], off
	global_store_dwordx4 v[30:31], v[24:27], off
	global_store_dwordx4 v[14:15], v[8:11], off
	global_store_dwordx4 v[12:13], v[4:7], off offset:256
	s_cbranch_vccz .LBB0_286
	s_cmpk_gt_u32 s36, 0xff
	s_cbranch_scc1 .LBB0_297
	s_barrier

; #define PG8_STAGE(bufoff, gbase, voff) do { _Pragma("unroll") for (int _i = 0; _i < 2; ++_i) \
;         __builtin_amdgcn_global_load_lds((const unsigned*)((const char*)(gbase) + (voff)[_i]), (PG8_LAS unsigned*)(lds + (bufoff) + ldsw + _i * 8192), 16, 0, 0); } while (0)
; #define PG8_LDA(dst, b, h) do { _Pragma("unroll") for (int m = 0; m < 4; ++m) _Pragma("unroll") for (int k = 0; k < 2; ++k) dst[m][k] = *(const PG8_LAS bf16x8*)(lds + PG8_SA(b, h) + aoff + m * 2048 + k * 1024); } while (0)
; #define PG8_LDB(dst, b, h) do { _Pragma("unroll") for (int n = 0; n < 2; ++n) _Pragma("unroll") for (int k = 0; k < 2; ++k) dst[n][k] = *(const PG8_LAS bf16x8*)(lds + PG8_SB(b, h) + boff + n * 2048 + k * 1024); } while (0)
; #define PG8_MMA(ai, bj, At, Bt) do { __builtin_amdgcn_s_setprio(1); _Pragma("unroll") for (int m = 0; m < 4; ++m) _Pragma("unroll") for (int n = 0; n < 2; ++n) _Pragma("unroll") for (int k = 0; k < 2; ++k) \
;         acc[ai][bj][m][n] = __builtin_amdgcn_mfma_f32_16x16x32_bf16(Bt[n][k], At[m][k], acc[ai][bj][m][n], 0, 0, 0); __builtin_amdgcn_s_setprio(0); } while (0)
; #define PG8_WAIT_L(n) asm volatile("s_waitcnt lgkmcnt(" #n ")" ::: "memory")
; #define PG8_BAR __builtin_amdgcn_s_barrier()
; #define PG8_SCHED __builtin_amdgcn_sched_barrier(0)
; template <class Epi, class Sched, bool STAMP = false>
; __device__ __forceinline__ void gemm_phase(PG8_LAS unsigned char* lds, const Gemm g, const Sched& S, const Epi& E, unsigned long long* stamps) {
;     ...
;             const bool last = (t == nt - 2);
;             const char* a1 = cA + (size_t)(t + 1) * kstep;
;             const char* a2 = last ? nA : cA + (size_t)(t + 2) * kstep; const char* b2 = last ? nB : cB + (size_t)(t + 2) * kstep;
;             const char* a3 = a2 + kstep; const char* b3 = b2 + kstep;
;             if (last && has_next) S.a_ready(nxt);
;             PG8_LDB(B0, 0, 0); PG8_SCHED; PG8_LDA(At, 0, 0); PG8_STAGE(PG8_SA(1, 1), a1 + hstep, voffA);
;             PG8_WAIT_L(8); PG8_BAR; PG8_WAIT_L(0); PG8_MMA(0, 0, At, B0); PG8_BAR; PG8_SCHED;
;             PG8_LDB(B1, 0, 1); PG8_STAGE(PG8_SB(0, 0), b2, voffB);
;             PG8_BAR; PG8_WAIT_L(0); PG8_MMA(0, 1, At, B1); PG8_BAR;
;             PG8_LDA(At, 0, 1); PG8_STAGE(PG8_SA(0, 0), a2, voffA);
;             PG8_BAR; PG8_WAIT_L(0); PG8_MMA(1, 0, At, B0); PG8_BAR; PG8_SCHED;
.LBB0_313:
	s_add_u32 s12, s4, 0xfffc0080
	s_addc_u32 s13, s5, -1
	s_add_i32 s14, 0, 0x10000
	v_add_u32_e32 v166, s14, v167
	ds_read_b128 v[158:161], v166
	ds_read_b128 v[162:165], v166 offset:1024
	ds_read_b128 v[170:173], v166 offset:2048
	ds_read_b128 v[174:177], v166 offset:3072
	s_cmp_eq_u32 s65, 12
	s_cselect_b32 s27, s31, s13
	s_cselect_b32 s26, s47, s12
	s_cselect_b32 s13, s7, s63
	s_cselect_b32 s12, s53, s62
	v_lshl_add_u64 v[182:183], s[4:5], 0, v[154:155]
	s_add_i32 m0, s3, 0xc000
	ds_read_b128 v[178:181], v169
	ds_read_b128 v[192:195], v169 offset:1024
	ds_read_b128 v[196:199], v169 offset:2048
	ds_read_b128 v[200:203], v169 offset:3072
	ds_read_b128 v[204:207], v169 offset:4096
	ds_read_b128 v[208:211], v169 offset:5120
	ds_read_b128 v[212:215], v169 offset:6144
	ds_read_b128 v[216:219], v169 offset:7168
	global_load_lds_dwordx4 v[182:183], off
	v_lshl_add_u64 v[182:183], s[4:5], 0, v[156:157]
	s_add_i32 m0, s3, 0xe000
	s_nop 0
	global_load_lds_dwordx4 v[182:183], off
	s_waitcnt lgkmcnt(8)
	s_barrier
	s_waitcnt lgkmcnt(0)
	s_setprio 1
	s_waitcnt lgkmcnt(0)
	v_mfma_f32_16x16x32_bf16 v[124:127], v[158:161], v[178:181], v[124:127]
	v_mfma_f32_16x16x32_bf16 v[120:123], v[170:173], v[178:181], v[120:123]
	v_mfma_f32_16x16x32_bf16 v[108:111], v[158:161], v[196:199], v[108:111]
	v_mfma_f32_16x16x32_bf16 v[104:107], v[170:173], v[196:199], v[104:107]
	v_mfma_f32_16x16x32_bf16 v[92:95], v[158:161], v[204:207], v[92:95]
	v_mfma_f32_16x16x32_bf16 v[88:91], v[170:173], v[204:207], v[88:91]
	v_mfma_f32_16x16x32_bf16 v[76:79], v[158:161], v[212:215], v[76:79]
	v_mfma_f32_16x16x32_bf16 v[72:75], v[170:173], v[212:215], v[72:75]
	v_mfma_f32_16x16x32_bf16 v[124:127], v[162:165], v[192:195], v[124:127]
	v_mfma_f32_16x16x32_bf16 v[120:123], v[174:177], v[192:195], v[120:123]
	v_mfma_f32_16x16x32_bf16 v[108:111], v[162:165], v[200:203], v[108:111]
	v_mfma_f32_16x16x32_bf16 v[104:107], v[174:177], v[200:203], v[104:107]
	v_mfma_f32_16x16x32_bf16 v[92:95], v[162:165], v[208:211], v[92:95]
	v_mfma_f32_16x16x32_bf16 v[88:91], v[174:177], v[208:211], v[88:91]
	v_mfma_f32_16x16x32_bf16 v[76:79], v[162:165], v[216:219], v[76:79]
	v_mfma_f32_16x16x32_bf16 v[72:75], v[174:177], v[216:219], v[72:75]
	s_setprio 0
	s_barrier
	s_add_i32 s16, 0, 0x14000
	s_add_i32 s14, s14, s56
	v_add_u32_e32 v166, s16, v167
	v_lshl_add_u64 v[182:183], s[12:13], 0, v[128:129]
	s_mov_b32 m0, s14
	ds_read_b128 v[220:223], v166
	ds_read_b128 v[224:227], v166 offset:1024
	ds_read_b128 v[228:231], v166 offset:2048
	ds_read_b128 v[232:235], v166 offset:3072
	global_load_lds_dwordx4 v[182:183], off
	v_lshl_add_u64 v[236:237], s[12:13], 0, v[152:153]
	s_add_i32 m0, s14, 0x2000
	s_nop 0
	global_load_lds_dwordx4 v[236:237], off
	s_barrier
	s_waitcnt lgkmcnt(0)
	s_setprio 1
	s_waitcnt lgkmcnt(0)
	v_mfma_f32_16x16x32_bf16 v[116:119], v[220:223], v[178:181], v[116:119]
	v_mfma_f32_16x16x32_bf16 v[112:115], v[228:231], v[178:181], v[112:115]
	v_mfma_f32_16x16x32_bf16 v[100:103], v[220:223], v[196:199], v[100:103]
	v_mfma_f32_16x16x32_bf16 v[96:99], v[228:231], v[196:199], v[96:99]
	v_mfma_f32_16x16x32_bf16 v[84:87], v[220:223], v[204:207], v[84:87]
	v_mfma_f32_16x16x32_bf16 v[80:83], v[228:231], v[204:207], v[80:83]
	v_mfma_f32_16x16x32_bf16 v[68:71], v[220:223], v[212:215], v[68:71]
	v_mfma_f32_16x16x32_bf16 v[64:67], v[228:231], v[212:215], v[64:67]
	v_mfma_f32_16x16x32_bf16 v[116:119], v[224:227], v[192:195], v[116:119]
	v_mfma_f32_16x16x32_bf16 v[112:115], v[232:235], v[192:195], v[112:115]
	v_mfma_f32_16x16x32_bf16 v[100:103], v[224:227], v[200:203], v[100:103]
	v_mfma_f32_16x16x32_bf16 v[96:99], v[232:235], v[200:203], v[96:99]
	v_mfma_f32_16x16x32_bf16 v[84:87], v[224:227], v[208:211], v[84:87]
	v_mfma_f32_16x16x32_bf16 v[80:83], v[232:235], v[208:211], v[80:83]
	v_mfma_f32_16x16x32_bf16 v[68:71], v[224:227], v[216:219], v[68:71]
	v_mfma_f32_16x16x32_bf16 v[64:67], v[232:235], v[216:219], v[64:67]
	s_setprio 0
	s_mov_b32 m0, s3
	v_lshl_add_u64 v[238:239], s[26:27], 0, v[148:149]
	s_barrier
	ds_read_b128 v[178:181], v169 offset:16384
	ds_read_b128 v[192:195], v169 offset:17408
	ds_read_b128 v[196:199], v169 offset:18432
	ds_read_b128 v[200:203], v169 offset:19456
	ds_read_b128 v[204:207], v169 offset:20480
	ds_read_b128 v[208:211], v169 offset:21504
	ds_read_b128 v[212:215], v169 offset:22528
	ds_read_b128 v[216:219], v169 offset:23552
	global_load_lds_dwordx4 v[238:239], off
	v_lshl_add_u64 v[240:241], s[26:27], 0, v[150:151]
	s_mov_b32 m0, s57
	s_nop 0
	global_load_lds_dwordx4 v[240:241], off
	s_barrier
	s_waitcnt lgkmcnt(0)
	s_setprio 1
	s_waitcnt lgkmcnt(0)
	v_mfma_f32_16x16x32_bf16 v[60:63], v[158:161], v[178:181], v[60:63]
	v_mfma_f32_16x16x32_bf16 v[56:59], v[170:173], v[178:181], v[56:59]
	v_mfma_f32_16x16x32_bf16 v[44:47], v[158:161], v[196:199], v[44:47]
	v_mfma_f32_16x16x32_bf16 v[40:43], v[170:173], v[196:199], v[40:43]
	v_mfma_f32_16x16x32_bf16 v[28:31], v[158:161], v[204:207], v[28:31]
	v_mfma_f32_16x16x32_bf16 v[24:27], v[170:173], v[204:207], v[24:27]
	v_mfma_f32_16x16x32_bf16 v[12:15], v[158:161], v[212:215], v[12:15]
	v_mfma_f32_16x16x32_bf16 v[8:11], v[170:173], v[212:215], v[8:11]
	v_mfma_f32_16x16x32_bf16 v[60:63], v[162:165], v[192:195], v[60:63]
	v_mfma_f32_16x16x32_bf16 v[56:59], v[174:177], v[192:195], v[56:59]
	v_mfma_f32_16x16x32_bf16 v[44:47], v[162:165], v[200:203], v[44:47]
	v_mfma_f32_16x16x32_bf16 v[40:43], v[174:177], v[200:203], v[40:43]
	v_mfma_f32_16x16x32_bf16 v[28:31], v[162:165], v[208:211], v[28:31]
	v_mfma_f32_16x16x32_bf16 v[24:27], v[174:177], v[208:211], v[24:27]
	v_mfma_f32_16x16x32_bf16 v[12:15], v[162:165], v[216:219], v[12:15]
	v_mfma_f32_16x16x32_bf16 v[8:11], v[174:177], v[216:219], v[8:11]
	s_setprio 0
	s_barrier
; #define PG8_STAGE(bufoff, gbase, voff) do { _Pragma("unroll") for (int _i = 0; _i < 2; ++_i) \
;         __builtin_amdgcn_global_load_lds((const unsigned*)((const char*)(gbase) + (voff)[_i]), (PG8_LAS unsigned*)(lds + (bufoff) + ldsw + _i * 8192), 16, 0, 0); } while (0)
; #define PG8_LDA(dst, b, h) do { _Pragma("unroll") for (int m = 0; m < 4; ++m) _Pragma("unroll") for (int k = 0; k < 2; ++k) dst[m][k] = *(const PG8_LAS bf16x8*)(lds + PG8_SA(b, h) + aoff + m * 2048 + k * 1024); } while (0)
; #define PG8_LDB(dst, b, h) do { _Pragma("unroll") for (int n = 0; n < 2; ++n) _Pragma("unroll") for (int k = 0; k < 2; ++k) dst[n][k] = *(const PG8_LAS bf16x8*)(lds + PG8_SB(b, h) + boff + n * 2048 + k * 1024); } while (0)
; #define PG8_MMA(ai, bj, At, Bt) do { __builtin_amdgcn_s_setprio(1); _Pragma("unroll") for (int m = 0; m < 4; ++m) _Pragma("unroll") for (int n = 0; n < 2; ++n) _Pragma("unroll") for (int k = 0; k < 2; ++k) \
;         acc[ai][bj][m][n] = __builtin_amdgcn_mfma_f32_16x16x32_bf16(Bt[n][k], At[m][k], acc[ai][bj][m][n], 0, 0, 0); __builtin_amdgcn_s_setprio(0); } while (0)
; #define PG8_WAIT_V(n) asm volatile("s_waitcnt vmcnt(" #n ")" ::: "memory")
; #define PG8_WAIT_L(n) asm volatile("s_waitcnt lgkmcnt(" #n ")" ::: "memory")
; #define PG8_BAR __builtin_amdgcn_s_barrier()
; #define PG8_SCHED __builtin_amdgcn_sched_barrier(0)
; template <class Epi, class Sched, bool STAMP = false>
; __device__ __forceinline__ void gemm_phase(PG8_LAS unsigned char* lds, const Gemm g, const Sched& S, const Epi& E, unsigned long long* stamps) {
;     ...
;             PG8_STAGE(PG8_SB(0, 1), b2 + hstep, voffB);
;             PG8_WAIT_V(6); PG8_BAR; PG8_MMA(1, 1, At, B1); PG8_BAR;
;             PG8_LDB(B0, 1, 0); PG8_SCHED; PG8_LDA(At, 1, 0); PG8_STAGE(PG8_SA(0, 1), a2 + hstep, voffA);
;             PG8_WAIT_L(8); PG8_BAR; PG8_WAIT_L(0); PG8_MMA(0, 0, At, B0); PG8_BAR; PG8_SCHED;
;             PG8_LDB(B1, 1, 1); PG8_STAGE(PG8_SB(1, 0), b3, voffB);
;             PG8_BAR; PG8_WAIT_L(0); PG8_MMA(0, 1, At, B1); PG8_BAR;
;             PG8_LDA(At, 1, 1); PG8_STAGE(PG8_SA(1, 0), a3, voffA);
	s_add_u32 s14, s12, 0x40000
	s_addc_u32 s15, s13, 0
	s_add_i32 s16, s16, s56
	v_lshl_add_u64 v[158:159], s[14:15], 0, v[128:129]
	s_mov_b32 m0, s16
	s_nop 0
	global_load_lds_dwordx4 v[158:159], off
	v_lshl_add_u64 v[158:159], s[14:15], 0, v[152:153]
	s_add_i32 m0, s16, 0x2000
	s_nop 0
	global_load_lds_dwordx4 v[158:159], off
	s_waitcnt vmcnt(6)
	s_barrier
	s_setprio 1
	v_mfma_f32_16x16x32_bf16 v[52:55], v[220:223], v[178:181], v[52:55]
	v_mfma_f32_16x16x32_bf16 v[48:51], v[228:231], v[178:181], v[48:51]
	v_mfma_f32_16x16x32_bf16 v[36:39], v[220:223], v[196:199], v[36:39]
	v_mfma_f32_16x16x32_bf16 v[32:35], v[228:231], v[196:199], v[32:35]
	v_mfma_f32_16x16x32_bf16 v[20:23], v[220:223], v[204:207], v[20:23]
	v_mfma_f32_16x16x32_bf16 v[16:19], v[228:231], v[204:207], v[16:19]
	v_mfma_f32_16x16x32_bf16 v[4:7], v[220:223], v[212:215], v[4:7]
	v_mfma_f32_16x16x32_bf16 v[0:3], v[228:231], v[212:215], v[0:3]
	v_mfma_f32_16x16x32_bf16 v[52:55], v[224:227], v[192:195], v[52:55]
	v_mfma_f32_16x16x32_bf16 v[48:51], v[232:235], v[192:195], v[48:51]
	v_mfma_f32_16x16x32_bf16 v[36:39], v[224:227], v[200:203], v[36:39]
	v_mfma_f32_16x16x32_bf16 v[32:35], v[232:235], v[200:203], v[32:35]
	v_mfma_f32_16x16x32_bf16 v[20:23], v[224:227], v[208:211], v[20:23]
	v_mfma_f32_16x16x32_bf16 v[16:19], v[232:235], v[208:211], v[16:19]
	v_mfma_f32_16x16x32_bf16 v[4:7], v[224:227], v[216:219], v[4:7]
	v_mfma_f32_16x16x32_bf16 v[0:3], v[232:235], v[216:219], v[0:3]
	s_setprio 0
	s_add_i32 s16, 0, 0x18000
	v_add_u32_e32 v166, s16, v167
	s_barrier
	ds_read_b128 v[158:161], v166
	ds_read_b128 v[162:165], v166 offset:1024
	ds_read_b128 v[170:173], v166 offset:2048
	ds_read_b128 v[174:177], v166 offset:3072
	s_add_u32 s14, s26, 0x40000
	s_addc_u32 s15, s27, 0
	s_mov_b32 m0, s58
	v_lshl_add_u64 v[220:221], s[14:15], 0, v[148:149]
	ds_read_b128 v[178:181], v169 offset:32768
	ds_read_b128 v[192:195], v169 offset:33792
	ds_read_b128 v[196:199], v169 offset:34816
	ds_read_b128 v[200:203], v169 offset:35840
	ds_read_b128 v[204:207], v169 offset:36864
	ds_read_b128 v[208:211], v169 offset:37888
	ds_read_b128 v[212:215], v169 offset:38912
	ds_read_b128 v[216:219], v169 offset:39936
	global_load_lds_dwordx4 v[220:221], off
	v_lshl_add_u64 v[220:221], s[14:15], 0, v[150:151]
	s_mov_b32 m0, s59
	s_nop 0
	global_load_lds_dwordx4 v[220:221], off
	s_waitcnt lgkmcnt(8)
	s_barrier
	s_waitcnt lgkmcnt(0)
	s_setprio 1
	s_waitcnt lgkmcnt(0)
	v_mfma_f32_16x16x32_bf16 v[124:127], v[158:161], v[178:181], v[124:127]
	v_mfma_f32_16x16x32_bf16 v[120:123], v[170:173], v[178:181], v[120:123]
	v_mfma_f32_16x16x32_bf16 v[108:111], v[158:161], v[196:199], v[108:111]
	v_mfma_f32_16x16x32_bf16 v[104:107], v[170:173], v[196:199], v[104:107]
	v_mfma_f32_16x16x32_bf16 v[92:95], v[158:161], v[204:207], v[92:95]
	v_mfma_f32_16x16x32_bf16 v[88:91], v[170:173], v[204:207], v[88:91]
	v_mfma_f32_16x16x32_bf16 v[76:79], v[158:161], v[212:215], v[76:79]
	v_mfma_f32_16x16x32_bf16 v[72:75], v[170:173], v[212:215], v[72:75]
	v_mfma_f32_16x16x32_bf16 v[124:127], v[162:165], v[192:195], v[124:127]
	v_mfma_f32_16x16x32_bf16 v[120:123], v[174:177], v[192:195], v[120:123]
	v_mfma_f32_16x16x32_bf16 v[108:111], v[162:165], v[200:203], v[108:111]
	v_mfma_f32_16x16x32_bf16 v[104:107], v[174:177], v[200:203], v[104:107]
	v_mfma_f32_16x16x32_bf16 v[92:95], v[162:165], v[208:211], v[92:95]
	v_mfma_f32_16x16x32_bf16 v[88:91], v[174:177], v[208:211], v[88:91]
	v_mfma_f32_16x16x32_bf16 v[76:79], v[162:165], v[216:219], v[76:79]
	v_mfma_f32_16x16x32_bf16 v[72:75], v[174:177], v[216:219], v[72:75]
	s_setprio 0
	s_barrier
	s_add_i32 s14, 0, 0x1c000
	s_add_i32 s15, s16, s56
	v_add_u32_e32 v166, s14, v167
	v_lshl_add_u64 v[182:183], v[182:183], 0, s[18:19]
	s_mov_b32 m0, s15
	ds_read_b128 v[220:223], v166
	ds_read_b128 v[224:227], v166 offset:1024
	ds_read_b128 v[228:231], v166 offset:2048
	ds_read_b128 v[232:235], v166 offset:3072
	global_load_lds_dwordx4 v[182:183], off
	v_lshl_add_u64 v[182:183], v[236:237], 0, s[18:19]
	s_add_i32 m0, s15, 0x2000
	s_nop 0
	global_load_lds_dwordx4 v[182:183], off
	s_barrier
	s_waitcnt lgkmcnt(0)
	s_setprio 1
	s_waitcnt lgkmcnt(0)
	v_mfma_f32_16x16x32_bf16 v[116:119], v[220:223], v[178:181], v[116:119]
	v_mfma_f32_16x16x32_bf16 v[112:115], v[228:231], v[178:181], v[112:115]
	v_mfma_f32_16x16x32_bf16 v[100:103], v[220:223], v[196:199], v[100:103]
	v_mfma_f32_16x16x32_bf16 v[96:99], v[228:231], v[196:199], v[96:99]
	v_mfma_f32_16x16x32_bf16 v[84:87], v[220:223], v[204:207], v[84:87]
	v_mfma_f32_16x16x32_bf16 v[80:83], v[228:231], v[204:207], v[80:83]
	v_mfma_f32_16x16x32_bf16 v[68:71], v[220:223], v[212:215], v[68:71]
	v_mfma_f32_16x16x32_bf16 v[64:67], v[228:231], v[212:215], v[64:67]
	v_mfma_f32_16x16x32_bf16 v[116:119], v[224:227], v[192:195], v[116:119]
	v_mfma_f32_16x16x32_bf16 v[112:115], v[232:235], v[192:195], v[112:115]
	v_mfma_f32_16x16x32_bf16 v[100:103], v[224:227], v[200:203], v[100:103]
	v_mfma_f32_16x16x32_bf16 v[96:99], v[232:235], v[200:203], v[96:99]
	v_mfma_f32_16x16x32_bf16 v[84:87], v[224:227], v[208:211], v[84:87]
	v_mfma_f32_16x16x32_bf16 v[80:83], v[232:235], v[208:211], v[80:83]
	v_mfma_f32_16x16x32_bf16 v[68:71], v[224:227], v[216:219], v[68:71]
	v_mfma_f32_16x16x32_bf16 v[64:67], v[232:235], v[216:219], v[64:67]
	s_setprio 0
	s_mov_b32 m0, s60
	v_lshl_add_u64 v[182:183], v[238:239], 0, s[18:19]
	s_barrier
	ds_read_b128 v[178:181], v169 offset:49152
	ds_read_b128 v[192:195], v169 offset:50176
	ds_read_b128 v[196:199], v169 offset:51200
	ds_read_b128 v[200:203], v169 offset:52224
	ds_read_b128 v[204:207], v169 offset:53248
	ds_read_b128 v[208:211], v169 offset:54272
	ds_read_b128 v[212:215], v169 offset:55296
	ds_read_b128 v[216:219], v169 offset:56320
	global_load_lds_dwordx4 v[182:183], off
	v_lshl_add_u64 v[182:183], v[240:241], 0, s[18:19]
	s_mov_b32 m0, s61
	s_nop 0
	global_load_lds_dwordx4 v[182:183], off
	s_barrier
; #define PG8_STAGE(bufoff, gbase, voff) do { _Pragma("unroll") for (int _i = 0; _i < 2; ++_i) \
;         __builtin_amdgcn_global_load_lds((const unsigned*)((const char*)(gbase) + (voff)[_i]), (PG8_LAS unsigned*)(lds + (bufoff) + ldsw + _i * 8192), 16, 0, 0); } while (0)
; #define PG8_MMA(ai, bj, At, Bt) do { __builtin_amdgcn_s_setprio(1); _Pragma("unroll") for (int m = 0; m < 4; ++m) _Pragma("unroll") for (int n = 0; n < 2; ++n) _Pragma("unroll") for (int k = 0; k < 2; ++k) \
;         acc[ai][bj][m][n] = __builtin_amdgcn_mfma_f32_16x16x32_bf16(Bt[n][k], At[m][k], acc[ai][bj][m][n], 0, 0, 0); __builtin_amdgcn_s_setprio(0); } while (0)
; #define PG8_WAIT_V(n) asm volatile("s_waitcnt vmcnt(" #n ")" ::: "memory")
; #define PG8_WAIT_L(n) asm volatile("s_waitcnt lgkmcnt(" #n ")" ::: "memory")
; #define PG8_BAR __builtin_amdgcn_s_barrier()
; #define PG8_SCHED __builtin_amdgcn_sched_barrier(0)
; __device__ __forceinline__ float rstd_of(const float* rowss, int row) { return rsqrtf(rowss[row] * (1.0f / 1024.0f) + 1e-6f); }
; template <class Epi, class Sched, bool STAMP = false>
; __device__ __forceinline__ void gemm_phase(PG8_LAS unsigned char* lds, const Gemm g, const Sched& S, const Epi& E, unsigned long long* stamps) {
;     ...
;             PG8_BAR; PG8_WAIT_L(0); PG8_MMA(1, 0, At, B0); PG8_BAR; PG8_SCHED;
;             PG8_STAGE(PG8_SB(1, 1), b3 + hstep, voffB);
;             PG8_WAIT_V(6); PG8_BAR; PG8_MMA(1, 1, At, B1); PG8_BAR;
;     __device__ __forceinline__ void operator()(const f32x4 (&acc)[2][2][4][2], const pg8::Unit& u, int wr, int wc, int fr, int fq) const {
;         const int row0 = u.pm * 256 + wr * 64 + fr, col0 = u.pn * 256 + wc * 32 + 8 * fq;
; #pragma unroll
;         for (int ai = 0; ai < 2; ++ai)
; #pragma unroll
;             for (int m = 0; m < 4; ++m) {
;                 const int row = row0 + ai * 128 + m * 16;
;                 const float s = rstd_of(rowss, row);
; #pragma unroll
;                 for (int bj = 0; bj < 2; ++bj) {
;                     const size_t off = (size_t)row * 1024 + col0 + bj * 128;
;                     const u32x4 tv = *(const u32x4*)(Tm + off);
;                     u32x4 pv = (u32x4){0u, 0u, 0u, 0u};
;                     if (ACC) pv = *(const u32x4*)(M + off);
	s_waitcnt lgkmcnt(0)
	s_setprio 1
	s_waitcnt lgkmcnt(0)
	v_mfma_f32_16x16x32_bf16 v[60:63], v[158:161], v[178:181], v[60:63]
	v_mfma_f32_16x16x32_bf16 v[56:59], v[170:173], v[178:181], v[56:59]
	v_mfma_f32_16x16x32_bf16 v[44:47], v[158:161], v[196:199], v[44:47]
	v_mfma_f32_16x16x32_bf16 v[40:43], v[170:173], v[196:199], v[40:43]
	v_mfma_f32_16x16x32_bf16 v[28:31], v[158:161], v[204:207], v[28:31]
	v_mfma_f32_16x16x32_bf16 v[24:27], v[170:173], v[204:207], v[24:27]
	v_mfma_f32_16x16x32_bf16 v[12:15], v[158:161], v[212:215], v[12:15]
	v_mfma_f32_16x16x32_bf16 v[8:11], v[170:173], v[212:215], v[8:11]
	v_mfma_f32_16x16x32_bf16 v[60:63], v[162:165], v[192:195], v[60:63]
	v_mfma_f32_16x16x32_bf16 v[56:59], v[174:177], v[192:195], v[56:59]
	v_mfma_f32_16x16x32_bf16 v[44:47], v[162:165], v[200:203], v[44:47]
	v_mfma_f32_16x16x32_bf16 v[40:43], v[174:177], v[200:203], v[40:43]
	v_mfma_f32_16x16x32_bf16 v[28:31], v[162:165], v[208:211], v[28:31]
	v_mfma_f32_16x16x32_bf16 v[24:27], v[174:177], v[208:211], v[24:27]
	v_mfma_f32_16x16x32_bf16 v[12:15], v[162:165], v[216:219], v[12:15]
	v_mfma_f32_16x16x32_bf16 v[8:11], v[174:177], v[216:219], v[8:11]
	s_setprio 0
	s_barrier
	s_add_u32 s12, s12, 0x40080
	s_addc_u32 s13, s13, 0
	s_add_i32 s14, s14, s56
	v_lshl_add_u64 v[158:159], s[12:13], 0, v[128:129]
	s_mov_b32 m0, s14
	s_nop 0
	global_load_lds_dwordx4 v[158:159], off
	v_lshl_add_u64 v[158:159], s[12:13], 0, v[152:153]
	s_add_i32 m0, s14, 0x2000
	s_nop 0
	global_load_lds_dwordx4 v[158:159], off
	s_waitcnt vmcnt(6)
	s_barrier
	s_setprio 1
	v_mfma_f32_16x16x32_bf16 v[52:55], v[220:223], v[178:181], v[52:55]
	v_mfma_f32_16x16x32_bf16 v[48:51], v[228:231], v[178:181], v[48:51]
	v_mfma_f32_16x16x32_bf16 v[36:39], v[220:223], v[196:199], v[36:39]
	v_mfma_f32_16x16x32_bf16 v[32:35], v[228:231], v[196:199], v[32:35]
	v_mfma_f32_16x16x32_bf16 v[20:23], v[220:223], v[204:207], v[20:23]
	v_mfma_f32_16x16x32_bf16 v[16:19], v[228:231], v[204:207], v[16:19]
	v_mfma_f32_16x16x32_bf16 v[4:7], v[220:223], v[212:215], v[4:7]
	v_mfma_f32_16x16x32_bf16 v[0:3], v[228:231], v[212:215], v[0:3]
	v_mfma_f32_16x16x32_bf16 v[52:55], v[224:227], v[192:195], v[52:55]
	v_mfma_f32_16x16x32_bf16 v[48:51], v[232:235], v[192:195], v[48:51]
	v_mfma_f32_16x16x32_bf16 v[36:39], v[224:227], v[200:203], v[36:39]
	v_mfma_f32_16x16x32_bf16 v[32:35], v[232:235], v[200:203], v[32:35]
	v_mfma_f32_16x16x32_bf16 v[20:23], v[224:227], v[208:211], v[20:23]
	v_mfma_f32_16x16x32_bf16 v[16:19], v[232:235], v[208:211], v[16:19]
	v_mfma_f32_16x16x32_bf16 v[4:7], v[224:227], v[216:219], v[4:7]
	v_mfma_f32_16x16x32_bf16 v[0:3], v[232:235], v[216:219], v[0:3]
	s_setprio 0
	s_add_i32 s65, s65, 2
	s_add_u32 s4, s4, 0x100
	s_addc_u32 s5, s5, 0
	s_add_u32 s62, s62, 0x100
	s_addc_u32 s63, s63, 0
	s_cmp_gt_u32 s65, 13
	s_barrier
	s_cbranch_scc0 .LBB0_313
	v_lshl_add_u32 v162, s2, 8, v139
	v_ashrrev_i32_e32 v163, 31, v162
	v_lshl_add_u64 v[160:161], v[162:163], 2, s[40:41]
	global_load_dword v164, v[160:161], off
	v_lshl_or_b32 v158, s46, 8, v168
	v_ashrrev_i32_e32 v159, 31, v158
	s_mov_b32 s2, 0x40000
	s_mov_b64 s[4:5], 0x40000
	s_mov_b32 s46, s6
	s_mov_b64 s[12:13], s[24:25]
	s_mov_b32 s62, 0x1800000
	s_waitcnt vmcnt(0)
	v_fmamk_f32 v164, v164, 0x3a800000, v187
	v_cmp_gt_f32_e32 vcc, s67, v164
	v_mul_f32_e32 v165, 0x4b800000, v164
	s_nop 0
	v_cndmask_b32_e32 v164, v164, v165, vcc
	v_rsq_f32_e32 v164, v164
	s_nop 0
	v_mul_f32_e32 v165, 0x45800000, v164
	v_cndmask_b32_e32 v166, v164, v165, vcc
	v_lshlrev_b64 v[164:165], 11, v[162:163]
	v_lshl_add_u64 v[170:171], s[0:1], 0, v[164:165]
	v_lshlrev_b64 v[164:165], 1, v[158:159]
	v_lshl_add_u64 v[158:159], v[170:171], 0, v[164:165]
	v_mov_b32_e32 v170, v158
	v_mov_b32_e32 v171, v159
	global_load_dwordx4 v[192:195], v[170:171], off
	global_load_dwordx4 v[196:199], v[170:171], off offset:256
	v_add_co_u32_e32 v170, vcc, 0x8000, v170
	s_nop 1
	v_addc_co_u32_e32 v171, vcc, 0, v171, vcc
	global_load_dwordx4 v[200:203], v[170:171], off
	global_load_dwordx4 v[204:207], v[170:171], off offset:256
	v_add_co_u32_e32 v170, vcc, 0x8000, v170
	s_nop 1
	v_addc_co_u32_e32 v171, vcc, 0, v171, vcc
	global_load_dwordx4 v[208:211], v[170:171], off
	global_load_dwordx4 v[212:215], v[170:171], off offset:256
	v_add_co_u32_e32 v170, vcc, 0x8000, v170
	s_nop 1
	v_addc_co_u32_e32 v171, vcc, 0, v171, vcc
	global_load_dwordx4 v[216:219], v[170:171], off
	global_load_dwordx4 v[220:223], v[170:171], off offset:256
	v_lshl_add_u64 v[170:171], v[158:159], 0, s[4:5]
	global_load_dwordx4 v[224:227], v[170:171], off
	global_load_dwordx4 v[228:231], v[170:171], off offset:256
	v_add_co_u32_e32 v170, vcc, 0x8000, v170
	s_nop 1
	v_addc_co_u32_e32 v171, vcc, 0, v171, vcc
	global_load_dwordx4 v[232:235], v[170:171], off
	global_load_dwordx4 v[236:239], v[170:171], off offset:256
	v_add_co_u32_e32 v170, vcc, 0x8000, v170
	s_nop 1
	v_addc_co_u32_e32 v171, vcc, 0, v171, vcc
	global_load_dwordx4 v[244:247], v[170:171], off
	global_load_dwordx4 v[248:251], v[170:171], off offset:256
	v_add_co_u32_e32 v170, vcc, 0x8000, v170
	s_nop 1
	v_addc_co_u32_e32 v171, vcc, 0, v171, vcc
	global_load_dwordx4 v[176:179], v[170:171], off
	global_load_dwordx4 v[252:255], v[170:171], off offset:256
	global_load_dword v180, v[160:161], off offset:64
	global_load_dword v181, v[160:161], off offset:128
	global_load_dword v182, v[160:161], off offset:192
	global_load_dword v183, v[160:161], off offset:512
	global_load_dword v240, v[160:161], off offset:576
	global_load_dword v241, v[160:161], off offset:640
	global_load_dword v169, v[160:161], off offset:704
	v_pk_mul_f32 v[126:127], v[126:127], v[166:167] op_sel_hi:[1,0]
; __device__ __forceinline__ unsigned cvt_pk_bf16(float lo, float hi) { const f32x2_cv v = {lo, hi}; const bf16x2_cv b = __builtin_convertvector(v, bf16x2_cv); return __builtin_bit_cast(unsigned, b); }
; __device__ __forceinline__ float sigm(float x) { return __builtin_amdgcn_rcpf(1.0f + __expf(-x)); }
; __device__ __forceinline__ float lo16(unsigned w) { return __uint_as_float(w << 16); }
; __device__ __forceinline__ float hi16(unsigned w) { return __uint_as_float(w & 0xffff0000u); }
; __device__ __forceinline__ float rstd_of(const float* rowss, int row) { return rsqrtf(rowss[row] * (1.0f / 1024.0f) + 1e-6f); }
;     __device__ __forceinline__ void operator()(const f32x4 (&acc)[2][2][4][2], const pg8::Unit& u, int wr, int wc, int fr, int fq) const {
;         const int row0 = u.pm * 256 + wr * 64 + fr, col0 = u.pn * 256 + wc * 32 + 8 * fq;
; #pragma unroll
;         for (int ai = 0; ai < 2; ++ai)
; #pragma unroll
;             for (int m = 0; m < 4; ++m) {
;                 const int row = row0 + ai * 128 + m * 16;
;                 const float s = rstd_of(rowss, row);
; #pragma unroll
;                 for (int bj = 0; bj < 2; ++bj) {
;                     const size_t off = (size_t)row * 1024 + col0 + bj * 128;
;                     const u32x4 tv = *(const u32x4*)(Tm + off);
;                     u32x4 pv = (u32x4){0u, 0u, 0u, 0u};
;                     if (ACC) pv = *(const u32x4*)(M + off);
;                     const f32x4 a0 = acc[ai][bj][m][0] * s, a1 = acc[ai][bj][m][1] * s;
;                     float o[8];
;                     o[0] = sigm(a0[0]) * lo16(tv.x); o[1] = sigm(a0[1]) * hi16(tv.x); o[2] = sigm(a0[2]) * lo16(tv.y); o[3] = sigm(a0[3]) * hi16(tv.y);
;                     o[4] = sigm(a1[0]) * lo16(tv.z); o[5] = sigm(a1[1]) * hi16(tv.z); o[6] = sigm(a1[2]) * lo16(tv.w); o[7] = sigm(a1[3]) * hi16(tv.w);
;                     if (ACC) { o[0] += lo16(pv.x); o[1] += hi16(pv.x); o[2] += lo16(pv.y); o[3] += hi16(pv.y); o[4] += lo16(pv.z); o[5] += hi16(pv.z); o[6] += lo16(pv.w); o[7] += hi16(pv.w); }
;                     u32x4 w; w.x = cvt_pk_bf16(o[0], o[1]); w.y = cvt_pk_bf16(o[2], o[3]); w.z = cvt_pk_bf16(o[4], o[5]); w.w = cvt_pk_bf16(o[6], o[7]);
;                     *(u32x4*)(M + off) = w; } }
	v_pk_mul_f32 v[120:121], v[120:121], v[166:167] op_sel_hi:[1,0]
	v_mul_f32_e32 v126, 0xbfb8aa3b, v126
	v_mul_f32_e32 v127, 0xbfb8aa3b, v127
	v_exp_f32_e32 v126, v126
	v_exp_f32_e32 v127, v127
	v_mul_f32_e32 v120, 0xbfb8aa3b, v120
	v_mul_f32_e32 v121, 0xbfb8aa3b, v121
	v_exp_f32_e32 v120, v120
	v_exp_f32_e32 v121, v121
	v_add_f32_e32 v126, 1.0, v126
	v_add_f32_e32 v127, 1.0, v127
	v_rcp_f32_e32 v126, v126
	v_rcp_f32_e32 v127, v127
	v_add_f32_e32 v120, 1.0, v120
	v_add_f32_e32 v121, 1.0, v121
	v_rcp_f32_e32 v120, v120
	v_rcp_f32_e32 v121, v121
	v_pk_mul_f32 v[124:125], v[124:125], v[166:167] op_sel_hi:[1,0]
	v_pk_mul_f32 v[122:123], v[122:123], v[166:167] op_sel_hi:[1,0]
	v_mul_f32_e32 v124, 0xbfb8aa3b, v124
	v_mul_f32_e32 v125, 0xbfb8aa3b, v125
	v_exp_f32_e32 v124, v124
	v_exp_f32_e32 v125, v125
	v_pk_mul_f32 v[118:119], v[118:119], v[166:167] op_sel_hi:[1,0]
	v_pk_mul_f32 v[112:113], v[112:113], v[166:167] op_sel_hi:[1,0]
	v_add_f32_e32 v124, 1.0, v124
	v_add_f32_e32 v125, 1.0, v125
	v_rcp_f32_e32 v124, v124
	v_rcp_f32_e32 v125, v125
	v_mul_f32_e32 v118, 0xbfb8aa3b, v118
	v_mul_f32_e32 v119, 0xbfb8aa3b, v119
	v_exp_f32_e32 v118, v118
	v_exp_f32_e32 v119, v119
	v_mul_f32_e32 v112, 0xbfb8aa3b, v112
	v_mul_f32_e32 v113, 0xbfb8aa3b, v113
	v_exp_f32_e32 v112, v112
	v_exp_f32_e32 v113, v113
	v_add_f32_e32 v118, 1.0, v118
	v_add_f32_e32 v119, 1.0, v119
	v_rcp_f32_e32 v118, v118
	v_rcp_f32_e32 v119, v119
	v_add_f32_e32 v112, 1.0, v112
	v_add_f32_e32 v113, 1.0, v113
	v_rcp_f32_e32 v112, v112
	v_rcp_f32_e32 v113, v113
	v_pk_mul_f32 v[116:117], v[116:117], v[166:167] op_sel_hi:[1,0]
	v_pk_mul_f32 v[114:115], v[114:115], v[166:167] op_sel_hi:[1,0]
	v_mul_f32_e32 v116, 0xbfb8aa3b, v116
	v_mul_f32_e32 v117, 0xbfb8aa3b, v117
	v_exp_f32_e32 v116, v116
	v_exp_f32_e32 v117, v117
	v_add_f32_e32 v116, 1.0, v116
	v_add_f32_e32 v117, 1.0, v117
	v_rcp_f32_e32 v116, v116
	v_rcp_f32_e32 v117, v117
	s_waitcnt vmcnt(0)
	v_mov_b32_e32 v170, v192
	v_mov_b32_e32 v171, v193
	v_mov_b32_e32 v172, v194
	v_mov_b32_e32 v173, v195
	v_lshlrev_b32_e32 v174, 16, v170
	v_and_b32_e32 v175, 0xffff0000, v170
	v_lshlrev_b32_e32 v170, 16, v171
	v_and_b32_e32 v171, 0xffff0000, v171
	v_pk_mul_f32 v[126:127], v[126:127], v[170:171]
	v_lshlrev_b32_e32 v170, 16, v172
	v_and_b32_e32 v171, 0xffff0000, v172
	v_pk_mul_f32 v[170:171], v[120:121], v[170:171]
	v_mul_f32_e32 v120, 0xbfb8aa3b, v122
	v_mul_f32_e32 v121, 0xbfb8aa3b, v123
	v_exp_f32_e32 v120, v120
	v_exp_f32_e32 v121, v121
	v_lshlrev_b32_e32 v122, 16, v173
	v_and_b32_e32 v123, 0xffff0000, v173
	v_add_f32_e32 v120, 1.0, v120
	v_add_f32_e32 v121, 1.0, v121
	v_rcp_f32_e32 v120, v120
	v_rcp_f32_e32 v121, v121
	v_pk_mul_f32 v[124:125], v[124:125], v[174:175]
	v_pk_mul_f32 v[172:173], v[120:121], v[122:123]
	v_cvt_pk_bf16_f32 v120, v124, v125
	v_cvt_pk_bf16_f32 v121, v126, v127
	v_cvt_pk_bf16_f32 v122, v170, v171
	v_cvt_pk_bf16_f32 v123, v172, v173
	global_store_dwordx4 v[158:159], v[120:123], off
	s_nop 1
	v_mov_b32_e32 v120, v196
	v_mov_b32_e32 v121, v197
	v_mov_b32_e32 v122, v198
	v_mov_b32_e32 v123, v199
	v_lshlrev_b32_e32 v124, 16, v120
	v_and_b32_e32 v125, 0xffff0000, v120
	v_lshlrev_b32_e32 v120, 16, v121
	v_and_b32_e32 v121, 0xffff0000, v121
	v_pk_mul_f32 v[118:119], v[118:119], v[120:121]
	v_lshlrev_b32_e32 v120, 16, v122
	v_and_b32_e32 v121, 0xffff0000, v122
	v_pk_mul_f32 v[120:121], v[112:113], v[120:121]
	v_mul_f32_e32 v112, 0xbfb8aa3b, v114
	v_mul_f32_e32 v113, 0xbfb8aa3b, v115
	v_exp_f32_e32 v112, v112
	v_exp_f32_e32 v113, v113
	v_lshlrev_b32_e32 v114, 16, v123
	v_and_b32_e32 v115, 0xffff0000, v123
	v_add_f32_e32 v112, 1.0, v112
	v_add_f32_e32 v113, 1.0, v113
	v_rcp_f32_e32 v112, v112
	v_rcp_f32_e32 v113, v113
	v_pk_mul_f32 v[116:117], v[116:117], v[124:125]
	v_pk_mul_f32 v[122:123], v[112:113], v[114:115]
	v_cvt_pk_bf16_f32 v112, v116, v117
	v_cvt_pk_bf16_f32 v113, v118, v119
	v_cvt_pk_bf16_f32 v114, v120, v121
	v_cvt_pk_bf16_f32 v115, v122, v123
	global_store_dwordx4 v[158:159], v[112:115], off offset:256
	s_nop 1
	v_mov_b32_e32 v114, v180
	s_nop 0
	v_or_b32_e32 v112, 16, v162
	v_ashrrev_i32_e32 v113, 31, v112
	v_lshlrev_b64 v[112:113], 11, v[112:113]
	v_lshl_add_u64 v[112:113], s[0:1], 0, v[112:113]
	v_lshl_add_u64 v[112:113], v[112:113], 0, v[164:165]
	s_nop 1
	v_mov_b32_e32 v116, v200
	v_mov_b32_e32 v117, v201
	v_mov_b32_e32 v118, v202
	v_mov_b32_e32 v119, v203
	v_fmamk_f32 v114, v114, 0x3a800000, v187
	v_cmp_gt_f32_e32 vcc, s67, v114
	v_mul_f32_e32 v115, 0x4b800000, v114
	v_lshlrev_b32_e32 v120, 16, v116
	v_cndmask_b32_e32 v114, v114, v115, vcc
	v_rsq_f32_e32 v114, v114
	v_and_b32_e32 v121, 0xffff0000, v116
	v_lshlrev_b32_e32 v116, 16, v117
	v_and_b32_e32 v117, 0xffff0000, v117
	v_mul_f32_e32 v115, 0x45800000, v114
	v_cndmask_b32_e32 v114, v114, v115, vcc
	v_pk_mul_f32 v[110:111], v[110:111], v[114:115] op_sel_hi:[1,0]
	v_pk_mul_f32 v[104:105], v[104:105], v[114:115] op_sel_hi:[1,0]
	v_mul_f32_e32 v110, 0xbfb8aa3b, v110
	v_mul_f32_e32 v111, 0xbfb8aa3b, v111
	v_exp_f32_e32 v110, v110
	v_exp_f32_e32 v111, v111
	v_mul_f32_e32 v104, 0xbfb8aa3b, v104
	v_mul_f32_e32 v105, 0xbfb8aa3b, v105
	v_exp_f32_e32 v104, v104
	v_exp_f32_e32 v105, v105
	v_add_f32_e32 v110, 1.0, v110
	v_add_f32_e32 v111, 1.0, v111
	v_rcp_f32_e32 v110, v110
	v_rcp_f32_e32 v111, v111
	v_add_f32_e32 v104, 1.0, v104
	v_add_f32_e32 v105, 1.0, v105
	v_rcp_f32_e32 v104, v104
	v_rcp_f32_e32 v105, v105
	v_pk_mul_f32 v[108:109], v[108:109], v[114:115] op_sel_hi:[1,0]
	v_pk_mul_f32 v[106:107], v[106:107], v[114:115] op_sel_hi:[1,0]
	v_pk_mul_f32 v[110:111], v[110:111], v[116:117]
	v_lshlrev_b32_e32 v116, 16, v118
	v_and_b32_e32 v117, 0xffff0000, v118
; __device__ __forceinline__ unsigned cvt_pk_bf16(float lo, float hi) { const f32x2_cv v = {lo, hi}; const bf16x2_cv b = __builtin_convertvector(v, bf16x2_cv); return __builtin_bit_cast(unsigned, b); }
; __device__ __forceinline__ float sigm(float x) { return __builtin_amdgcn_rcpf(1.0f + __expf(-x)); }
; __device__ __forceinline__ float lo16(unsigned w) { return __uint_as_float(w << 16); }
; __device__ __forceinline__ float hi16(unsigned w) { return __uint_as_float(w & 0xffff0000u); }
; __device__ __forceinline__ float rstd_of(const float* rowss, int row) { return rsqrtf(rowss[row] * (1.0f / 1024.0f) + 1e-6f); }
;     __device__ __forceinline__ void operator()(const f32x4 (&acc)[2][2][4][2], const pg8::Unit& u, int wr, int wc, int fr, int fq) const {
;         const int row0 = u.pm * 256 + wr * 64 + fr, col0 = u.pn * 256 + wc * 32 + 8 * fq;
; #pragma unroll
;         for (int ai = 0; ai < 2; ++ai)
; #pragma unroll
;             for (int m = 0; m < 4; ++m) {
;                 const int row = row0 + ai * 128 + m * 16;
;                 const float s = rstd_of(rowss, row);
; #pragma unroll
;                 for (int bj = 0; bj < 2; ++bj) {
;                     const size_t off = (size_t)row * 1024 + col0 + bj * 128;
;                     const u32x4 tv = *(const u32x4*)(Tm + off);
;                     u32x4 pv = (u32x4){0u, 0u, 0u, 0u};
;                     if (ACC) pv = *(const u32x4*)(M + off);
;                     const f32x4 a0 = acc[ai][bj][m][0] * s, a1 = acc[ai][bj][m][1] * s;
;                     float o[8];
;                     o[0] = sigm(a0[0]) * lo16(tv.x); o[1] = sigm(a0[1]) * hi16(tv.x); o[2] = sigm(a0[2]) * lo16(tv.y); o[3] = sigm(a0[3]) * hi16(tv.y);
;                     o[4] = sigm(a1[0]) * lo16(tv.z); o[5] = sigm(a1[1]) * hi16(tv.z); o[6] = sigm(a1[2]) * lo16(tv.w); o[7] = sigm(a1[3]) * hi16(tv.w);
;                     if (ACC) { o[0] += lo16(pv.x); o[1] += hi16(pv.x); o[2] += lo16(pv.y); o[3] += hi16(pv.y); o[4] += lo16(pv.z); o[5] += hi16(pv.z); o[6] += lo16(pv.w); o[7] += hi16(pv.w); }
;                     u32x4 w; w.x = cvt_pk_bf16(o[0], o[1]); w.y = cvt_pk_bf16(o[2], o[3]); w.z = cvt_pk_bf16(o[4], o[5]); w.w = cvt_pk_bf16(o[6], o[7]);
;                     *(u32x4*)(M + off) = w; } }
	v_mul_f32_e32 v108, 0xbfb8aa3b, v108
	v_mul_f32_e32 v109, 0xbfb8aa3b, v109
	v_pk_mul_f32 v[116:117], v[104:105], v[116:117]
	v_mul_f32_e32 v104, 0xbfb8aa3b, v106
	v_mul_f32_e32 v105, 0xbfb8aa3b, v107
	v_exp_f32_e32 v108, v108
	v_exp_f32_e32 v109, v109
	v_exp_f32_e32 v104, v104
	v_exp_f32_e32 v105, v105
	v_add_f32_e32 v108, 1.0, v108
	v_add_f32_e32 v109, 1.0, v109
	v_add_f32_e32 v104, 1.0, v104
	v_add_f32_e32 v105, 1.0, v105
	v_rcp_f32_e32 v108, v108
	v_rcp_f32_e32 v109, v109
	v_rcp_f32_e32 v104, v104
	v_rcp_f32_e32 v105, v105
	v_lshlrev_b32_e32 v106, 16, v119
	v_and_b32_e32 v107, 0xffff0000, v119
	v_pk_mul_f32 v[108:109], v[108:109], v[120:121]
	v_pk_mul_f32 v[118:119], v[104:105], v[106:107]
	v_cvt_pk_bf16_f32 v104, v108, v109
	v_cvt_pk_bf16_f32 v105, v110, v111
	v_cvt_pk_bf16_f32 v106, v116, v117
	v_cvt_pk_bf16_f32 v107, v118, v119
	global_store_dwordx4 v[112:113], v[104:107], off
	s_nop 1
	v_mov_b32_e32 v104, v204
	v_mov_b32_e32 v105, v205
	v_mov_b32_e32 v106, v206
	v_mov_b32_e32 v107, v207
	v_pk_mul_f32 v[102:103], v[102:103], v[114:115] op_sel_hi:[1,0]
	v_pk_mul_f32 v[96:97], v[96:97], v[114:115] op_sel_hi:[1,0]
	v_mul_f32_e32 v102, 0xbfb8aa3b, v102
	v_mul_f32_e32 v103, 0xbfb8aa3b, v103
	v_exp_f32_e32 v102, v102
	v_exp_f32_e32 v103, v103
	v_mul_f32_e32 v96, 0xbfb8aa3b, v96
	v_mul_f32_e32 v97, 0xbfb8aa3b, v97
	v_exp_f32_e32 v96, v96
	v_exp_f32_e32 v97, v97
	v_add_f32_e32 v102, 1.0, v102
	v_add_f32_e32 v103, 1.0, v103
	v_rcp_f32_e32 v102, v102
	v_rcp_f32_e32 v103, v103
	v_add_f32_e32 v96, 1.0, v96
	v_add_f32_e32 v97, 1.0, v97
	v_rcp_f32_e32 v96, v96
	v_rcp_f32_e32 v97, v97
	v_pk_mul_f32 v[100:101], v[100:101], v[114:115] op_sel_hi:[1,0]
	v_pk_mul_f32 v[98:99], v[98:99], v[114:115] op_sel_hi:[1,0]
	v_mul_f32_e32 v100, 0xbfb8aa3b, v100
	v_mul_f32_e32 v101, 0xbfb8aa3b, v101
	v_exp_f32_e32 v100, v100
	v_exp_f32_e32 v101, v101
	v_add_f32_e32 v100, 1.0, v100
	v_add_f32_e32 v101, 1.0, v101
	v_rcp_f32_e32 v100, v100
	v_rcp_f32_e32 v101, v101
	v_lshlrev_b32_e32 v108, 16, v104
	v_and_b32_e32 v109, 0xffff0000, v104
	v_lshlrev_b32_e32 v104, 16, v105
	v_and_b32_e32 v105, 0xffff0000, v105
	v_pk_mul_f32 v[102:103], v[102:103], v[104:105]
	v_lshlrev_b32_e32 v104, 16, v106
	v_and_b32_e32 v105, 0xffff0000, v106
	v_pk_mul_f32 v[104:105], v[96:97], v[104:105]
	v_mul_f32_e32 v96, 0xbfb8aa3b, v98
	v_mul_f32_e32 v97, 0xbfb8aa3b, v99
	v_exp_f32_e32 v96, v96
	v_exp_f32_e32 v97, v97
	v_lshlrev_b32_e32 v98, 16, v107
	v_and_b32_e32 v99, 0xffff0000, v107
	v_add_f32_e32 v96, 1.0, v96
	v_add_f32_e32 v97, 1.0, v97
	v_rcp_f32_e32 v96, v96
	v_rcp_f32_e32 v97, v97
	v_pk_mul_f32 v[100:101], v[100:101], v[108:109]
	v_pk_mul_f32 v[106:107], v[96:97], v[98:99]
	v_cvt_pk_bf16_f32 v96, v100, v101
	v_cvt_pk_bf16_f32 v97, v102, v103
	v_cvt_pk_bf16_f32 v98, v104, v105
	v_cvt_pk_bf16_f32 v99, v106, v107
	global_store_dwordx4 v[112:113], v[96:99], off offset:256
	s_nop 1
	v_mov_b32_e32 v98, v181
	s_nop 0
	v_or_b32_e32 v96, 32, v162
	v_ashrrev_i32_e32 v97, 31, v96
	v_lshlrev_b64 v[96:97], 11, v[96:97]
	v_lshl_add_u64 v[96:97], s[0:1], 0, v[96:97]
	v_lshl_add_u64 v[96:97], v[96:97], 0, v[164:165]
	s_nop 1
	v_mov_b32_e32 v100, v208
	v_mov_b32_e32 v101, v209
	v_mov_b32_e32 v102, v210
	v_mov_b32_e32 v103, v211
	v_fmamk_f32 v98, v98, 0x3a800000, v187
	v_cmp_gt_f32_e32 vcc, s67, v98
	v_mul_f32_e32 v99, 0x4b800000, v98
	v_lshlrev_b32_e32 v104, 16, v100
	v_cndmask_b32_e32 v98, v98, v99, vcc
	v_rsq_f32_e32 v98, v98
	v_and_b32_e32 v105, 0xffff0000, v100
	v_lshlrev_b32_e32 v100, 16, v101
	v_and_b32_e32 v101, 0xffff0000, v101
	v_mul_f32_e32 v99, 0x45800000, v98
	v_cndmask_b32_e32 v98, v98, v99, vcc
	v_pk_mul_f32 v[94:95], v[94:95], v[98:99] op_sel_hi:[1,0]
	v_pk_mul_f32 v[88:89], v[88:89], v[98:99] op_sel_hi:[1,0]
	v_mul_f32_e32 v94, 0xbfb8aa3b, v94
	v_mul_f32_e32 v95, 0xbfb8aa3b, v95
	v_exp_f32_e32 v94, v94
	v_exp_f32_e32 v95, v95
	v_mul_f32_e32 v88, 0xbfb8aa3b, v88
	v_mul_f32_e32 v89, 0xbfb8aa3b, v89
	v_exp_f32_e32 v88, v88
	v_exp_f32_e32 v89, v89
	v_add_f32_e32 v94, 1.0, v94
	v_add_f32_e32 v95, 1.0, v95
	v_rcp_f32_e32 v94, v94
	v_rcp_f32_e32 v95, v95
	v_add_f32_e32 v88, 1.0, v88
	v_add_f32_e32 v89, 1.0, v89
	v_rcp_f32_e32 v88, v88
	v_rcp_f32_e32 v89, v89
	v_pk_mul_f32 v[92:93], v[92:93], v[98:99] op_sel_hi:[1,0]
	v_pk_mul_f32 v[90:91], v[90:91], v[98:99] op_sel_hi:[1,0]
	v_pk_mul_f32 v[94:95], v[94:95], v[100:101]
	v_lshlrev_b32_e32 v100, 16, v102
	v_and_b32_e32 v101, 0xffff0000, v102
	v_mul_f32_e32 v92, 0xbfb8aa3b, v92
	v_mul_f32_e32 v93, 0xbfb8aa3b, v93
	v_pk_mul_f32 v[100:101], v[88:89], v[100:101]
	v_mul_f32_e32 v88, 0xbfb8aa3b, v90
	v_mul_f32_e32 v89, 0xbfb8aa3b, v91
	v_exp_f32_e32 v92, v92
	v_exp_f32_e32 v93, v93
	v_exp_f32_e32 v88, v88
	v_exp_f32_e32 v89, v89
	v_add_f32_e32 v92, 1.0, v92
	v_add_f32_e32 v93, 1.0, v93
	v_add_f32_e32 v88, 1.0, v88
	v_add_f32_e32 v89, 1.0, v89
	v_rcp_f32_e32 v92, v92
	v_rcp_f32_e32 v93, v93
	v_rcp_f32_e32 v88, v88
	v_rcp_f32_e32 v89, v89
	v_lshlrev_b32_e32 v90, 16, v103
	v_and_b32_e32 v91, 0xffff0000, v103
	v_pk_mul_f32 v[92:93], v[92:93], v[104:105]
	v_pk_mul_f32 v[102:103], v[88:89], v[90:91]
	v_cvt_pk_bf16_f32 v88, v92, v93
	v_cvt_pk_bf16_f32 v89, v94, v95
	v_cvt_pk_bf16_f32 v90, v100, v101
	v_cvt_pk_bf16_f32 v91, v102, v103
	global_store_dwordx4 v[96:97], v[88:91], off
	s_nop 1
	v_mov_b32_e32 v88, v212
	v_mov_b32_e32 v89, v213
	v_mov_b32_e32 v90, v214
	v_mov_b32_e32 v91, v215
	v_pk_mul_f32 v[86:87], v[86:87], v[98:99] op_sel_hi:[1,0]
	v_pk_mul_f32 v[80:81], v[80:81], v[98:99] op_sel_hi:[1,0]
	v_mul_f32_e32 v86, 0xbfb8aa3b, v86
	v_mul_f32_e32 v87, 0xbfb8aa3b, v87
	v_exp_f32_e32 v86, v86
	v_exp_f32_e32 v87, v87
	v_mul_f32_e32 v80, 0xbfb8aa3b, v80
; __device__ __forceinline__ unsigned cvt_pk_bf16(float lo, float hi) { const f32x2_cv v = {lo, hi}; const bf16x2_cv b = __builtin_convertvector(v, bf16x2_cv); return __builtin_bit_cast(unsigned, b); }
; __device__ __forceinline__ float sigm(float x) { return __builtin_amdgcn_rcpf(1.0f + __expf(-x)); }
; __device__ __forceinline__ float lo16(unsigned w) { return __uint_as_float(w << 16); }
; __device__ __forceinline__ float hi16(unsigned w) { return __uint_as_float(w & 0xffff0000u); }
; __device__ __forceinline__ float rstd_of(const float* rowss, int row) { return rsqrtf(rowss[row] * (1.0f / 1024.0f) + 1e-6f); }
;     __device__ __forceinline__ void operator()(const f32x4 (&acc)[2][2][4][2], const pg8::Unit& u, int wr, int wc, int fr, int fq) const {
;         const int row0 = u.pm * 256 + wr * 64 + fr, col0 = u.pn * 256 + wc * 32 + 8 * fq;
; #pragma unroll
;         for (int ai = 0; ai < 2; ++ai)
; #pragma unroll
;             for (int m = 0; m < 4; ++m) {
;                 const int row = row0 + ai * 128 + m * 16;
;                 const float s = rstd_of(rowss, row);
; #pragma unroll
;                 for (int bj = 0; bj < 2; ++bj) {
;                     const size_t off = (size_t)row * 1024 + col0 + bj * 128;
;                     const u32x4 tv = *(const u32x4*)(Tm + off);
;                     u32x4 pv = (u32x4){0u, 0u, 0u, 0u};
;                     if (ACC) pv = *(const u32x4*)(M + off);
;                     const f32x4 a0 = acc[ai][bj][m][0] * s, a1 = acc[ai][bj][m][1] * s;
;                     float o[8];
;                     o[0] = sigm(a0[0]) * lo16(tv.x); o[1] = sigm(a0[1]) * hi16(tv.x); o[2] = sigm(a0[2]) * lo16(tv.y); o[3] = sigm(a0[3]) * hi16(tv.y);
;                     o[4] = sigm(a1[0]) * lo16(tv.z); o[5] = sigm(a1[1]) * hi16(tv.z); o[6] = sigm(a1[2]) * lo16(tv.w); o[7] = sigm(a1[3]) * hi16(tv.w);
;                     if (ACC) { o[0] += lo16(pv.x); o[1] += hi16(pv.x); o[2] += lo16(pv.y); o[3] += hi16(pv.y); o[4] += lo16(pv.z); o[5] += hi16(pv.z); o[6] += lo16(pv.w); o[7] += hi16(pv.w); }
;                     u32x4 w; w.x = cvt_pk_bf16(o[0], o[1]); w.y = cvt_pk_bf16(o[2], o[3]); w.z = cvt_pk_bf16(o[4], o[5]); w.w = cvt_pk_bf16(o[6], o[7]);
;                     *(u32x4*)(M + off) = w; } }
	v_mul_f32_e32 v81, 0xbfb8aa3b, v81
	v_exp_f32_e32 v80, v80
	v_exp_f32_e32 v81, v81
	v_add_f32_e32 v86, 1.0, v86
	v_add_f32_e32 v87, 1.0, v87
	v_rcp_f32_e32 v86, v86
	v_rcp_f32_e32 v87, v87
	v_add_f32_e32 v80, 1.0, v80
	v_add_f32_e32 v81, 1.0, v81
	v_rcp_f32_e32 v80, v80
	v_rcp_f32_e32 v81, v81
	v_pk_mul_f32 v[84:85], v[84:85], v[98:99] op_sel_hi:[1,0]
	v_pk_mul_f32 v[82:83], v[82:83], v[98:99] op_sel_hi:[1,0]
	v_mul_f32_e32 v84, 0xbfb8aa3b, v84
	v_mul_f32_e32 v85, 0xbfb8aa3b, v85
	v_exp_f32_e32 v84, v84
	v_exp_f32_e32 v85, v85
	v_add_f32_e32 v84, 1.0, v84
	v_add_f32_e32 v85, 1.0, v85
	v_rcp_f32_e32 v84, v84
	v_rcp_f32_e32 v85, v85
	v_lshlrev_b32_e32 v92, 16, v88
	v_and_b32_e32 v93, 0xffff0000, v88
	v_lshlrev_b32_e32 v88, 16, v89
	v_and_b32_e32 v89, 0xffff0000, v89
	v_pk_mul_f32 v[86:87], v[86:87], v[88:89]
	v_lshlrev_b32_e32 v88, 16, v90
	v_and_b32_e32 v89, 0xffff0000, v90
	v_pk_mul_f32 v[88:89], v[80:81], v[88:89]
	v_mul_f32_e32 v80, 0xbfb8aa3b, v82
	v_mul_f32_e32 v81, 0xbfb8aa3b, v83
	v_exp_f32_e32 v80, v80
	v_exp_f32_e32 v81, v81
	v_lshlrev_b32_e32 v82, 16, v91
	v_and_b32_e32 v83, 0xffff0000, v91
	v_add_f32_e32 v80, 1.0, v80
	v_add_f32_e32 v81, 1.0, v81
	v_rcp_f32_e32 v80, v80
	v_rcp_f32_e32 v81, v81
	v_pk_mul_f32 v[84:85], v[84:85], v[92:93]
	v_pk_mul_f32 v[90:91], v[80:81], v[82:83]
	v_cvt_pk_bf16_f32 v80, v84, v85
	v_cvt_pk_bf16_f32 v81, v86, v87
	v_cvt_pk_bf16_f32 v82, v88, v89
	v_cvt_pk_bf16_f32 v83, v90, v91
	global_store_dwordx4 v[96:97], v[80:83], off offset:256
	s_nop 1
	v_mov_b32_e32 v82, v182
	s_nop 0
	v_or_b32_e32 v80, 48, v162
	v_ashrrev_i32_e32 v81, 31, v80
	v_lshlrev_b64 v[80:81], 11, v[80:81]
	v_lshl_add_u64 v[80:81], s[0:1], 0, v[80:81]
	v_lshl_add_u64 v[80:81], v[80:81], 0, v[164:165]
	s_nop 1
	v_mov_b32_e32 v84, v216
	v_mov_b32_e32 v85, v217
	v_mov_b32_e32 v86, v218
	v_mov_b32_e32 v87, v219
	v_fmamk_f32 v82, v82, 0x3a800000, v187
	v_cmp_gt_f32_e32 vcc, s67, v82
	v_mul_f32_e32 v83, 0x4b800000, v82
	v_lshlrev_b32_e32 v88, 16, v84
	v_cndmask_b32_e32 v82, v82, v83, vcc
	v_rsq_f32_e32 v82, v82
	v_and_b32_e32 v89, 0xffff0000, v84
	v_lshlrev_b32_e32 v84, 16, v85
	v_and_b32_e32 v85, 0xffff0000, v85
	v_mul_f32_e32 v83, 0x45800000, v82
	v_cndmask_b32_e32 v82, v82, v83, vcc
	v_pk_mul_f32 v[78:79], v[78:79], v[82:83] op_sel_hi:[1,0]
	v_pk_mul_f32 v[72:73], v[72:73], v[82:83] op_sel_hi:[1,0]
	v_mul_f32_e32 v78, 0xbfb8aa3b, v78
	v_mul_f32_e32 v79, 0xbfb8aa3b, v79
	v_exp_f32_e32 v78, v78
	v_exp_f32_e32 v79, v79
	v_mul_f32_e32 v72, 0xbfb8aa3b, v72
	v_mul_f32_e32 v73, 0xbfb8aa3b, v73
	v_exp_f32_e32 v72, v72
	v_exp_f32_e32 v73, v73
	v_add_f32_e32 v78, 1.0, v78
	v_add_f32_e32 v79, 1.0, v79
	v_rcp_f32_e32 v78, v78
	v_rcp_f32_e32 v79, v79
	v_add_f32_e32 v72, 1.0, v72
	v_add_f32_e32 v73, 1.0, v73
	v_rcp_f32_e32 v72, v72
	v_rcp_f32_e32 v73, v73
	v_pk_mul_f32 v[76:77], v[76:77], v[82:83] op_sel_hi:[1,0]
	v_pk_mul_f32 v[74:75], v[74:75], v[82:83] op_sel_hi:[1,0]
	v_pk_mul_f32 v[78:79], v[78:79], v[84:85]
	v_lshlrev_b32_e32 v84, 16, v86
	v_and_b32_e32 v85, 0xffff0000, v86
	v_mul_f32_e32 v76, 0xbfb8aa3b, v76
	v_mul_f32_e32 v77, 0xbfb8aa3b, v77
	v_pk_mul_f32 v[84:85], v[72:73], v[84:85]
	v_mul_f32_e32 v72, 0xbfb8aa3b, v74
	v_mul_f32_e32 v73, 0xbfb8aa3b, v75
	v_exp_f32_e32 v76, v76
	v_exp_f32_e32 v77, v77
	v_exp_f32_e32 v72, v72
	v_exp_f32_e32 v73, v73
	v_add_f32_e32 v76, 1.0, v76
	v_add_f32_e32 v77, 1.0, v77
	v_add_f32_e32 v72, 1.0, v72
	v_add_f32_e32 v73, 1.0, v73
	v_rcp_f32_e32 v76, v76
	v_rcp_f32_e32 v77, v77
	v_rcp_f32_e32 v72, v72
	v_rcp_f32_e32 v73, v73
	v_lshlrev_b32_e32 v74, 16, v87
	v_and_b32_e32 v75, 0xffff0000, v87
	v_pk_mul_f32 v[76:77], v[76:77], v[88:89]
	v_pk_mul_f32 v[86:87], v[72:73], v[74:75]
	v_cvt_pk_bf16_f32 v72, v76, v77
	v_cvt_pk_bf16_f32 v73, v78, v79
	v_cvt_pk_bf16_f32 v74, v84, v85
	v_cvt_pk_bf16_f32 v75, v86, v87
	global_store_dwordx4 v[80:81], v[72:75], off
	s_nop 1
	v_mov_b32_e32 v72, v220
	v_mov_b32_e32 v73, v221
	v_mov_b32_e32 v74, v222
	v_mov_b32_e32 v75, v223
	v_pk_mul_f32 v[70:71], v[70:71], v[82:83] op_sel_hi:[1,0]
	v_pk_mul_f32 v[64:65], v[64:65], v[82:83] op_sel_hi:[1,0]
	v_mul_f32_e32 v70, 0xbfb8aa3b, v70
	v_mul_f32_e32 v71, 0xbfb8aa3b, v71
	v_exp_f32_e32 v70, v70
	v_exp_f32_e32 v71, v71
	v_mul_f32_e32 v64, 0xbfb8aa3b, v64
	v_mul_f32_e32 v65, 0xbfb8aa3b, v65
	v_exp_f32_e32 v64, v64
	v_exp_f32_e32 v65, v65
	v_add_f32_e32 v70, 1.0, v70
	v_add_f32_e32 v71, 1.0, v71
	v_rcp_f32_e32 v70, v70
	v_rcp_f32_e32 v71, v71
	v_add_f32_e32 v64, 1.0, v64
	v_add_f32_e32 v65, 1.0, v65
	v_rcp_f32_e32 v64, v64
	v_rcp_f32_e32 v65, v65
	v_pk_mul_f32 v[68:69], v[68:69], v[82:83] op_sel_hi:[1,0]
	v_pk_mul_f32 v[66:67], v[66:67], v[82:83] op_sel_hi:[1,0]
	v_mul_f32_e32 v68, 0xbfb8aa3b, v68
	v_mul_f32_e32 v69, 0xbfb8aa3b, v69
	v_exp_f32_e32 v68, v68
	v_exp_f32_e32 v69, v69
	v_add_f32_e32 v68, 1.0, v68
	v_add_f32_e32 v69, 1.0, v69
	v_rcp_f32_e32 v68, v68
	v_rcp_f32_e32 v69, v69
	v_lshlrev_b32_e32 v76, 16, v72
	v_and_b32_e32 v77, 0xffff0000, v72
	v_lshlrev_b32_e32 v72, 16, v73
	v_and_b32_e32 v73, 0xffff0000, v73
	v_pk_mul_f32 v[70:71], v[70:71], v[72:73]
	v_lshlrev_b32_e32 v72, 16, v74
	v_and_b32_e32 v73, 0xffff0000, v74
	v_pk_mul_f32 v[72:73], v[64:65], v[72:73]
	v_mul_f32_e32 v64, 0xbfb8aa3b, v66
	v_mul_f32_e32 v65, 0xbfb8aa3b, v67
	v_exp_f32_e32 v64, v64
	v_exp_f32_e32 v65, v65
	v_lshlrev_b32_e32 v66, 16, v75
	v_and_b32_e32 v67, 0xffff0000, v75
	v_add_f32_e32 v64, 1.0, v64
	v_add_f32_e32 v65, 1.0, v65
	v_rcp_f32_e32 v64, v64
	v_rcp_f32_e32 v65, v65
	v_pk_mul_f32 v[68:69], v[68:69], v[76:77]
	v_pk_mul_f32 v[74:75], v[64:65], v[66:67]
	v_cvt_pk_bf16_f32 v64, v68, v69
	v_cvt_pk_bf16_f32 v65, v70, v71
	v_cvt_pk_bf16_f32 v66, v72, v73
; __device__ __forceinline__ unsigned cvt_pk_bf16(float lo, float hi) { const f32x2_cv v = {lo, hi}; const bf16x2_cv b = __builtin_convertvector(v, bf16x2_cv); return __builtin_bit_cast(unsigned, b); }
; __device__ __forceinline__ float sigm(float x) { return __builtin_amdgcn_rcpf(1.0f + __expf(-x)); }
; __device__ __forceinline__ float lo16(unsigned w) { return __uint_as_float(w << 16); }
; __device__ __forceinline__ float hi16(unsigned w) { return __uint_as_float(w & 0xffff0000u); }
; __device__ __forceinline__ float rstd_of(const float* rowss, int row) { return rsqrtf(rowss[row] * (1.0f / 1024.0f) + 1e-6f); }
;     __device__ __forceinline__ void operator()(const f32x4 (&acc)[2][2][4][2], const pg8::Unit& u, int wr, int wc, int fr, int fq) const {
;         const int row0 = u.pm * 256 + wr * 64 + fr, col0 = u.pn * 256 + wc * 32 + 8 * fq;
; #pragma unroll
;         for (int ai = 0; ai < 2; ++ai)
; #pragma unroll
;             for (int m = 0; m < 4; ++m) {
;                 const int row = row0 + ai * 128 + m * 16;
;                 const float s = rstd_of(rowss, row);
; #pragma unroll
;                 for (int bj = 0; bj < 2; ++bj) {
;                     const size_t off = (size_t)row * 1024 + col0 + bj * 128;
;                     const u32x4 tv = *(const u32x4*)(Tm + off);
;                     u32x4 pv = (u32x4){0u, 0u, 0u, 0u};
;                     if (ACC) pv = *(const u32x4*)(M + off);
;                     const f32x4 a0 = acc[ai][bj][m][0] * s, a1 = acc[ai][bj][m][1] * s;
;                     float o[8];
;                     o[0] = sigm(a0[0]) * lo16(tv.x); o[1] = sigm(a0[1]) * hi16(tv.x); o[2] = sigm(a0[2]) * lo16(tv.y); o[3] = sigm(a0[3]) * hi16(tv.y);
;                     o[4] = sigm(a1[0]) * lo16(tv.z); o[5] = sigm(a1[1]) * hi16(tv.z); o[6] = sigm(a1[2]) * lo16(tv.w); o[7] = sigm(a1[3]) * hi16(tv.w);
;                     if (ACC) { o[0] += lo16(pv.x); o[1] += hi16(pv.x); o[2] += lo16(pv.y); o[3] += hi16(pv.y); o[4] += lo16(pv.z); o[5] += hi16(pv.z); o[6] += lo16(pv.w); o[7] += hi16(pv.w); }
;                     u32x4 w; w.x = cvt_pk_bf16(o[0], o[1]); w.y = cvt_pk_bf16(o[2], o[3]); w.z = cvt_pk_bf16(o[4], o[5]); w.w = cvt_pk_bf16(o[6], o[7]);
;                     *(u32x4*)(M + off) = w; } }
	v_cvt_pk_bf16_f32 v67, v74, v75
	global_store_dwordx4 v[80:81], v[64:67], off offset:256
	s_nop 1
	v_mov_b32_e32 v64, v183
	v_fmamk_f32 v64, v64, 0x3a800000, v187
	v_cmp_gt_f32_e32 vcc, s67, v64
	v_mul_f32_e32 v65, 0x4b800000, v64
	s_nop 0
	v_cndmask_b32_e32 v64, v64, v65, vcc
	v_rsq_f32_e32 v64, v64
	s_nop 0
	v_mul_f32_e32 v65, 0x45800000, v64
	v_cndmask_b32_e32 v66, v64, v65, vcc
	v_add_co_u32_e32 v72, vcc, s2, v158
	v_pk_mul_f32 v[62:63], v[62:63], v[66:67] op_sel_hi:[1,0]
	s_nop 0
	v_addc_co_u32_e32 v73, vcc, 0, v159, vcc
	s_nop 1
	v_mov_b32_e32 v68, v224
	v_mov_b32_e32 v69, v225
	v_mov_b32_e32 v70, v226
	v_mov_b32_e32 v71, v227
	v_pk_mul_f32 v[56:57], v[56:57], v[66:67] op_sel_hi:[1,0]
	v_mul_f32_e32 v62, 0xbfb8aa3b, v62
	v_mul_f32_e32 v63, 0xbfb8aa3b, v63
	v_exp_f32_e32 v62, v62
	v_exp_f32_e32 v63, v63
	v_mul_f32_e32 v56, 0xbfb8aa3b, v56
	v_mul_f32_e32 v57, 0xbfb8aa3b, v57
	v_exp_f32_e32 v56, v56
	v_exp_f32_e32 v57, v57
	v_add_f32_e32 v62, 1.0, v62
	v_add_f32_e32 v63, 1.0, v63
	v_rcp_f32_e32 v62, v62
	v_rcp_f32_e32 v63, v63
	v_add_f32_e32 v56, 1.0, v56
	v_add_f32_e32 v57, 1.0, v57
	v_rcp_f32_e32 v56, v56
	v_rcp_f32_e32 v57, v57
	v_pk_mul_f32 v[60:61], v[60:61], v[66:67] op_sel_hi:[1,0]
	v_pk_mul_f32 v[58:59], v[58:59], v[66:67] op_sel_hi:[1,0]
	v_mul_f32_e32 v60, 0xbfb8aa3b, v60
	v_mul_f32_e32 v61, 0xbfb8aa3b, v61
	v_exp_f32_e32 v60, v60
	v_exp_f32_e32 v61, v61
	v_lshl_add_u64 v[64:65], v[158:159], 0, s[4:5]
	v_pk_mul_f32 v[54:55], v[54:55], v[66:67] op_sel_hi:[1,0]
	v_add_f32_e32 v60, 1.0, v60
	v_add_f32_e32 v61, 1.0, v61
	v_rcp_f32_e32 v60, v60
	v_rcp_f32_e32 v61, v61
	v_pk_mul_f32 v[48:49], v[48:49], v[66:67] op_sel_hi:[1,0]
	v_mul_f32_e32 v54, 0xbfb8aa3b, v54
	v_mul_f32_e32 v55, 0xbfb8aa3b, v55
	v_exp_f32_e32 v54, v54
	v_exp_f32_e32 v55, v55
	v_mul_f32_e32 v48, 0xbfb8aa3b, v48
	v_mul_f32_e32 v49, 0xbfb8aa3b, v49
	v_exp_f32_e32 v48, v48
	v_exp_f32_e32 v49, v49
	v_add_f32_e32 v54, 1.0, v54
	v_add_f32_e32 v55, 1.0, v55
	v_rcp_f32_e32 v54, v54
	v_rcp_f32_e32 v55, v55
	v_add_f32_e32 v48, 1.0, v48
	v_add_f32_e32 v49, 1.0, v49
	v_rcp_f32_e32 v48, v48
	v_rcp_f32_e32 v49, v49
	v_pk_mul_f32 v[52:53], v[52:53], v[66:67] op_sel_hi:[1,0]
	v_pk_mul_f32 v[50:51], v[50:51], v[66:67] op_sel_hi:[1,0]
	v_mul_f32_e32 v52, 0xbfb8aa3b, v52
	v_mul_f32_e32 v53, 0xbfb8aa3b, v53
	v_exp_f32_e32 v52, v52
	v_exp_f32_e32 v53, v53
	s_mov_b32 s2, 0x48000
	s_mov_b64 s[4:5], 0x48000
	v_add_f32_e32 v52, 1.0, v52
	v_add_f32_e32 v53, 1.0, v53
	v_rcp_f32_e32 v52, v52
	v_rcp_f32_e32 v53, v53
	v_lshlrev_b32_e32 v74, 16, v68
	v_and_b32_e32 v75, 0xffff0000, v68
	v_lshlrev_b32_e32 v68, 16, v69
	v_and_b32_e32 v69, 0xffff0000, v69
	v_pk_mul_f32 v[62:63], v[62:63], v[68:69]
	v_lshlrev_b32_e32 v68, 16, v70
	v_and_b32_e32 v69, 0xffff0000, v70
	v_pk_mul_f32 v[68:69], v[56:57], v[68:69]
	v_mul_f32_e32 v56, 0xbfb8aa3b, v58
	v_mul_f32_e32 v57, 0xbfb8aa3b, v59
	v_exp_f32_e32 v56, v56
	v_exp_f32_e32 v57, v57
	v_lshlrev_b32_e32 v58, 16, v71
	v_and_b32_e32 v59, 0xffff0000, v71
	v_add_f32_e32 v56, 1.0, v56
	v_add_f32_e32 v57, 1.0, v57
	v_rcp_f32_e32 v56, v56
	v_rcp_f32_e32 v57, v57
	v_pk_mul_f32 v[60:61], v[60:61], v[74:75]
	v_pk_mul_f32 v[70:71], v[56:57], v[58:59]
	v_cvt_pk_bf16_f32 v56, v60, v61
	v_cvt_pk_bf16_f32 v57, v62, v63
	v_cvt_pk_bf16_f32 v58, v68, v69
	v_cvt_pk_bf16_f32 v59, v70, v71
	global_store_dwordx4 v[72:73], v[56:59], off
	s_nop 1
	v_mov_b32_e32 v56, v228
	v_mov_b32_e32 v57, v229
	v_mov_b32_e32 v58, v230
	v_mov_b32_e32 v59, v231
	v_lshlrev_b32_e32 v60, 16, v56
	v_and_b32_e32 v61, 0xffff0000, v56
	v_lshlrev_b32_e32 v56, 16, v57
	v_and_b32_e32 v57, 0xffff0000, v57
	v_pk_mul_f32 v[54:55], v[54:55], v[56:57]
	v_lshlrev_b32_e32 v56, 16, v58
	v_and_b32_e32 v57, 0xffff0000, v58
	v_pk_mul_f32 v[56:57], v[48:49], v[56:57]
	v_mul_f32_e32 v48, 0xbfb8aa3b, v50
	v_mul_f32_e32 v49, 0xbfb8aa3b, v51
	v_exp_f32_e32 v48, v48
	v_exp_f32_e32 v49, v49
	v_lshlrev_b32_e32 v50, 16, v59
	v_and_b32_e32 v51, 0xffff0000, v59
	v_add_f32_e32 v48, 1.0, v48
	v_add_f32_e32 v49, 1.0, v49
	v_rcp_f32_e32 v48, v48
	v_rcp_f32_e32 v49, v49
	v_pk_mul_f32 v[52:53], v[52:53], v[60:61]
	v_pk_mul_f32 v[58:59], v[48:49], v[50:51]
	v_cvt_pk_bf16_f32 v48, v52, v53
	v_cvt_pk_bf16_f32 v49, v54, v55
	v_cvt_pk_bf16_f32 v50, v56, v57
	v_cvt_pk_bf16_f32 v51, v58, v59
	global_store_dwordx4 v[64:65], v[48:51], off offset:256
	s_nop 1
	v_mov_b32_e32 v48, v240
	v_fmamk_f32 v48, v48, 0x3a800000, v187
	v_cmp_gt_f32_e32 vcc, s67, v48
	v_mul_f32_e32 v49, 0x4b800000, v48
	s_nop 0
	v_cndmask_b32_e32 v48, v48, v49, vcc
	v_rsq_f32_e32 v48, v48
	s_nop 0
	v_mul_f32_e32 v49, 0x45800000, v48
	v_cndmask_b32_e32 v50, v48, v49, vcc
	v_add_co_u32_e32 v56, vcc, s2, v158
	v_pk_mul_f32 v[46:47], v[46:47], v[50:51] op_sel_hi:[1,0]
	s_nop 0
	v_addc_co_u32_e32 v57, vcc, 0, v159, vcc
	s_nop 1
	v_mov_b32_e32 v52, v232
	v_mov_b32_e32 v53, v233
	v_mov_b32_e32 v54, v234
	v_mov_b32_e32 v55, v235
	v_pk_mul_f32 v[40:41], v[40:41], v[50:51] op_sel_hi:[1,0]
	v_mul_f32_e32 v46, 0xbfb8aa3b, v46
	v_mul_f32_e32 v47, 0xbfb8aa3b, v47
	v_exp_f32_e32 v46, v46
	v_exp_f32_e32 v47, v47
	v_mul_f32_e32 v40, 0xbfb8aa3b, v40
	v_mul_f32_e32 v41, 0xbfb8aa3b, v41
	v_exp_f32_e32 v40, v40
	v_exp_f32_e32 v41, v41
	v_add_f32_e32 v46, 1.0, v46
	v_add_f32_e32 v47, 1.0, v47
	v_rcp_f32_e32 v46, v46
	v_rcp_f32_e32 v47, v47
	v_add_f32_e32 v40, 1.0, v40
	v_add_f32_e32 v41, 1.0, v41
	v_rcp_f32_e32 v40, v40
	v_rcp_f32_e32 v41, v41
	v_pk_mul_f32 v[44:45], v[44:45], v[50:51] op_sel_hi:[1,0]
	v_pk_mul_f32 v[42:43], v[42:43], v[50:51] op_sel_hi:[1,0]
	v_mul_f32_e32 v44, 0xbfb8aa3b, v44
	v_mul_f32_e32 v45, 0xbfb8aa3b, v45
	v_exp_f32_e32 v44, v44
	v_exp_f32_e32 v45, v45
; __device__ __forceinline__ unsigned cvt_pk_bf16(float lo, float hi) { const f32x2_cv v = {lo, hi}; const bf16x2_cv b = __builtin_convertvector(v, bf16x2_cv); return __builtin_bit_cast(unsigned, b); }
; __device__ __forceinline__ float sigm(float x) { return __builtin_amdgcn_rcpf(1.0f + __expf(-x)); }
; __device__ __forceinline__ float lo16(unsigned w) { return __uint_as_float(w << 16); }
; __device__ __forceinline__ float hi16(unsigned w) { return __uint_as_float(w & 0xffff0000u); }
; __device__ __forceinline__ float rstd_of(const float* rowss, int row) { return rsqrtf(rowss[row] * (1.0f / 1024.0f) + 1e-6f); }
;     __device__ __forceinline__ void operator()(const f32x4 (&acc)[2][2][4][2], const pg8::Unit& u, int wr, int wc, int fr, int fq) const {
;         const int row0 = u.pm * 256 + wr * 64 + fr, col0 = u.pn * 256 + wc * 32 + 8 * fq;
; #pragma unroll
;         for (int ai = 0; ai < 2; ++ai)
; #pragma unroll
;             for (int m = 0; m < 4; ++m) {
;                 const int row = row0 + ai * 128 + m * 16;
;                 const float s = rstd_of(rowss, row);
; #pragma unroll
;                 for (int bj = 0; bj < 2; ++bj) {
;                     const size_t off = (size_t)row * 1024 + col0 + bj * 128;
;                     const u32x4 tv = *(const u32x4*)(Tm + off);
;                     u32x4 pv = (u32x4){0u, 0u, 0u, 0u};
;                     if (ACC) pv = *(const u32x4*)(M + off);
;                     const f32x4 a0 = acc[ai][bj][m][0] * s, a1 = acc[ai][bj][m][1] * s;
;                     float o[8];
;                     o[0] = sigm(a0[0]) * lo16(tv.x); o[1] = sigm(a0[1]) * hi16(tv.x); o[2] = sigm(a0[2]) * lo16(tv.y); o[3] = sigm(a0[3]) * hi16(tv.y);
;                     o[4] = sigm(a1[0]) * lo16(tv.z); o[5] = sigm(a1[1]) * hi16(tv.z); o[6] = sigm(a1[2]) * lo16(tv.w); o[7] = sigm(a1[3]) * hi16(tv.w);
;                     if (ACC) { o[0] += lo16(pv.x); o[1] += hi16(pv.x); o[2] += lo16(pv.y); o[3] += hi16(pv.y); o[4] += lo16(pv.z); o[5] += hi16(pv.z); o[6] += lo16(pv.w); o[7] += hi16(pv.w); }
;                     u32x4 w; w.x = cvt_pk_bf16(o[0], o[1]); w.y = cvt_pk_bf16(o[2], o[3]); w.z = cvt_pk_bf16(o[4], o[5]); w.w = cvt_pk_bf16(o[6], o[7]);
;                     *(u32x4*)(M + off) = w; } }
	v_lshl_add_u64 v[48:49], v[158:159], 0, s[4:5]
	v_pk_mul_f32 v[38:39], v[38:39], v[50:51] op_sel_hi:[1,0]
	v_add_f32_e32 v44, 1.0, v44
	v_add_f32_e32 v45, 1.0, v45
	v_rcp_f32_e32 v44, v44
	v_rcp_f32_e32 v45, v45
	v_pk_mul_f32 v[32:33], v[32:33], v[50:51] op_sel_hi:[1,0]
	v_mul_f32_e32 v38, 0xbfb8aa3b, v38
	v_mul_f32_e32 v39, 0xbfb8aa3b, v39
	v_exp_f32_e32 v38, v38
	v_exp_f32_e32 v39, v39
	v_mul_f32_e32 v32, 0xbfb8aa3b, v32
	v_mul_f32_e32 v33, 0xbfb8aa3b, v33
	v_exp_f32_e32 v32, v32
	v_exp_f32_e32 v33, v33
	v_add_f32_e32 v38, 1.0, v38
	v_add_f32_e32 v39, 1.0, v39
	v_rcp_f32_e32 v38, v38
	v_rcp_f32_e32 v39, v39
	v_add_f32_e32 v32, 1.0, v32
	v_add_f32_e32 v33, 1.0, v33
	v_rcp_f32_e32 v32, v32
	v_rcp_f32_e32 v33, v33
	v_pk_mul_f32 v[36:37], v[36:37], v[50:51] op_sel_hi:[1,0]
	v_pk_mul_f32 v[34:35], v[34:35], v[50:51] op_sel_hi:[1,0]
	v_mul_f32_e32 v36, 0xbfb8aa3b, v36
	v_mul_f32_e32 v37, 0xbfb8aa3b, v37
	v_exp_f32_e32 v36, v36
	v_exp_f32_e32 v37, v37
	s_mov_b32 s2, 0x50000
	s_mov_b64 s[4:5], 0x50000
	v_add_f32_e32 v36, 1.0, v36
	v_add_f32_e32 v37, 1.0, v37
	v_rcp_f32_e32 v36, v36
	v_rcp_f32_e32 v37, v37
	v_lshlrev_b32_e32 v58, 16, v52
	v_and_b32_e32 v59, 0xffff0000, v52
	v_lshlrev_b32_e32 v52, 16, v53
	v_and_b32_e32 v53, 0xffff0000, v53
	v_pk_mul_f32 v[46:47], v[46:47], v[52:53]
	v_lshlrev_b32_e32 v52, 16, v54
	v_and_b32_e32 v53, 0xffff0000, v54
	v_pk_mul_f32 v[52:53], v[40:41], v[52:53]
	v_mul_f32_e32 v40, 0xbfb8aa3b, v42
	v_mul_f32_e32 v41, 0xbfb8aa3b, v43
	v_exp_f32_e32 v40, v40
	v_exp_f32_e32 v41, v41
	v_lshlrev_b32_e32 v42, 16, v55
	v_and_b32_e32 v43, 0xffff0000, v55
	v_add_f32_e32 v40, 1.0, v40
	v_add_f32_e32 v41, 1.0, v41
	v_rcp_f32_e32 v40, v40
	v_rcp_f32_e32 v41, v41
	v_pk_mul_f32 v[44:45], v[44:45], v[58:59]
	v_pk_mul_f32 v[54:55], v[40:41], v[42:43]
	v_cvt_pk_bf16_f32 v40, v44, v45
	v_cvt_pk_bf16_f32 v41, v46, v47
	v_cvt_pk_bf16_f32 v42, v52, v53
	v_cvt_pk_bf16_f32 v43, v54, v55
	global_store_dwordx4 v[56:57], v[40:43], off
	s_nop 1
	v_mov_b32_e32 v40, v236
	v_mov_b32_e32 v41, v237
	v_mov_b32_e32 v42, v238
	v_mov_b32_e32 v43, v239
	v_lshlrev_b32_e32 v44, 16, v40
	v_and_b32_e32 v45, 0xffff0000, v40
	v_lshlrev_b32_e32 v40, 16, v41
	v_and_b32_e32 v41, 0xffff0000, v41
	v_pk_mul_f32 v[38:39], v[38:39], v[40:41]
	v_lshlrev_b32_e32 v40, 16, v42
	v_and_b32_e32 v41, 0xffff0000, v42
	v_pk_mul_f32 v[40:41], v[32:33], v[40:41]
	v_mul_f32_e32 v32, 0xbfb8aa3b, v34
	v_mul_f32_e32 v33, 0xbfb8aa3b, v35
	v_exp_f32_e32 v32, v32
	v_exp_f32_e32 v33, v33
	v_lshlrev_b32_e32 v34, 16, v43
	v_and_b32_e32 v35, 0xffff0000, v43
	v_add_f32_e32 v32, 1.0, v32
	v_add_f32_e32 v33, 1.0, v33
	v_rcp_f32_e32 v32, v32
	v_rcp_f32_e32 v33, v33
	v_pk_mul_f32 v[36:37], v[36:37], v[44:45]
	v_pk_mul_f32 v[42:43], v[32:33], v[34:35]
	v_cvt_pk_bf16_f32 v32, v36, v37
	v_cvt_pk_bf16_f32 v33, v38, v39
	v_cvt_pk_bf16_f32 v34, v40, v41
	v_cvt_pk_bf16_f32 v35, v42, v43
	global_store_dwordx4 v[48:49], v[32:35], off offset:256
	s_nop 1
	v_mov_b32_e32 v32, v241
	v_fmamk_f32 v32, v32, 0x3a800000, v187
	v_cmp_gt_f32_e32 vcc, s67, v32
	v_mul_f32_e32 v33, 0x4b800000, v32
	s_nop 0
	v_cndmask_b32_e32 v32, v32, v33, vcc
	v_rsq_f32_e32 v32, v32
	s_nop 0
	v_mul_f32_e32 v33, 0x45800000, v32
	v_cndmask_b32_e32 v34, v32, v33, vcc
	v_add_co_u32_e32 v40, vcc, s2, v158
	v_pk_mul_f32 v[30:31], v[30:31], v[34:35] op_sel_hi:[1,0]
	s_nop 0
	v_addc_co_u32_e32 v41, vcc, 0, v159, vcc
	s_nop 1
	v_mov_b32_e32 v36, v244
	v_mov_b32_e32 v37, v245
	v_mov_b32_e32 v38, v246
	v_mov_b32_e32 v39, v247
	v_pk_mul_f32 v[24:25], v[24:25], v[34:35] op_sel_hi:[1,0]
	v_mul_f32_e32 v30, 0xbfb8aa3b, v30
	v_mul_f32_e32 v31, 0xbfb8aa3b, v31
	v_exp_f32_e32 v30, v30
	v_exp_f32_e32 v31, v31
	v_mul_f32_e32 v24, 0xbfb8aa3b, v24
	v_mul_f32_e32 v25, 0xbfb8aa3b, v25
	v_exp_f32_e32 v24, v24
	v_exp_f32_e32 v25, v25
	v_add_f32_e32 v30, 1.0, v30
	v_add_f32_e32 v31, 1.0, v31
	v_rcp_f32_e32 v30, v30
	v_rcp_f32_e32 v31, v31
	v_add_f32_e32 v24, 1.0, v24
	v_add_f32_e32 v25, 1.0, v25
	v_rcp_f32_e32 v24, v24
	v_rcp_f32_e32 v25, v25
	v_pk_mul_f32 v[28:29], v[28:29], v[34:35] op_sel_hi:[1,0]
	v_pk_mul_f32 v[26:27], v[26:27], v[34:35] op_sel_hi:[1,0]
	v_mul_f32_e32 v28, 0xbfb8aa3b, v28
	v_mul_f32_e32 v29, 0xbfb8aa3b, v29
	v_exp_f32_e32 v28, v28
	v_exp_f32_e32 v29, v29
	v_lshl_add_u64 v[32:33], v[158:159], 0, s[4:5]
	v_pk_mul_f32 v[22:23], v[22:23], v[34:35] op_sel_hi:[1,0]
	v_add_f32_e32 v28, 1.0, v28
	v_add_f32_e32 v29, 1.0, v29
	v_rcp_f32_e32 v28, v28
	v_rcp_f32_e32 v29, v29
	v_pk_mul_f32 v[16:17], v[16:17], v[34:35] op_sel_hi:[1,0]
	v_mul_f32_e32 v22, 0xbfb8aa3b, v22
	v_mul_f32_e32 v23, 0xbfb8aa3b, v23
	v_exp_f32_e32 v22, v22
	v_exp_f32_e32 v23, v23
	v_mul_f32_e32 v16, 0xbfb8aa3b, v16
	v_mul_f32_e32 v17, 0xbfb8aa3b, v17
	v_exp_f32_e32 v16, v16
	v_exp_f32_e32 v17, v17
	v_add_f32_e32 v22, 1.0, v22
	v_add_f32_e32 v23, 1.0, v23
	v_rcp_f32_e32 v22, v22
	v_rcp_f32_e32 v23, v23
	v_add_f32_e32 v16, 1.0, v16
	v_add_f32_e32 v17, 1.0, v17
	v_rcp_f32_e32 v16, v16
	v_rcp_f32_e32 v17, v17
	v_pk_mul_f32 v[20:21], v[20:21], v[34:35] op_sel_hi:[1,0]
	v_pk_mul_f32 v[18:19], v[18:19], v[34:35] op_sel_hi:[1,0]
	v_mul_f32_e32 v20, 0xbfb8aa3b, v20
	v_mul_f32_e32 v21, 0xbfb8aa3b, v21
	v_exp_f32_e32 v20, v20
	v_exp_f32_e32 v21, v21
	s_mov_b32 s2, 0x58000
	s_mov_b64 s[4:5], 0x58000
	v_add_f32_e32 v20, 1.0, v20
	v_add_f32_e32 v21, 1.0, v21
	v_rcp_f32_e32 v20, v20
	v_rcp_f32_e32 v21, v21
	v_lshlrev_b32_e32 v42, 16, v36
	v_and_b32_e32 v43, 0xffff0000, v36
	v_lshlrev_b32_e32 v36, 16, v37
	v_and_b32_e32 v37, 0xffff0000, v37
	v_pk_mul_f32 v[30:31], v[30:31], v[36:37]
	v_lshlrev_b32_e32 v36, 16, v38
	v_and_b32_e32 v37, 0xffff0000, v38
	v_pk_mul_f32 v[36:37], v[24:25], v[36:37]
; __device__ __forceinline__ unsigned cvt_pk_bf16(float lo, float hi) { const f32x2_cv v = {lo, hi}; const bf16x2_cv b = __builtin_convertvector(v, bf16x2_cv); return __builtin_bit_cast(unsigned, b); }
; #define PG8_WAIT_V(n) asm volatile("s_waitcnt vmcnt(" #n ")" ::: "memory")
; #define PG8_BAR __builtin_amdgcn_s_barrier()
; template <class Epi, class Sched, bool STAMP = false>
; __device__ __forceinline__ void gemm_phase(PG8_LAS unsigned char* lds, const Gemm g, const Sched& S, const Epi& E, unsigned long long* stamps) {
;     ...
;         if (!has_next) break;
; #pragma unroll
;         for (int a = 0; a < 2; ++a)
; #pragma unroll
;             for (int b = 0; b < 2; ++b)
; #pragma unroll
;                 for (int m = 0; m < 4; ++m)
; #pragma unroll
;                     for (int n = 0; n < 2; ++n) acc[a][b][m][n] = (f32x4){0.f, 0.f, 0.f, 0.f};
;         cur = nxt; cA = nA; cB = nB; ++ui;
;     }
;     PG8_WAIT_V(0);
;     if (wr == 0) PG8_BAR;
;     PG8_BAR;
;     __device__ __forceinline__ void operator()(const f32x4 (&acc)[2][2][4][2], const pg8::Unit& u, int wr, int wc, int fr, int fq) const {
;     ...
;                 const int row = row0 + ai * 128 + m * 16;
;                 const float s = rstd_of(rowss, row);
; #pragma unroll
;                 for (int bj = 0; bj < 2; ++bj) {
;                     const size_t off = (size_t)row * 1024 + col0 + bj * 128;
;                     const u32x4 tv = *(const u32x4*)(Tm + off);
;                     u32x4 pv = (u32x4){0u, 0u, 0u, 0u};
;                     if (ACC) pv = *(const u32x4*)(M + off);
;                     const f32x4 a0 = acc[ai][bj][m][0] * s, a1 = acc[ai][bj][m][1] * s;
;                     float o[8];
;                     o[0] = sigm(a0[0]) * lo16(tv.x); o[1] = sigm(a0[1]) * hi16(tv.x); o[2] = sigm(a0[2]) * lo16(tv.y); o[3] = sigm(a0[3]) * hi16(tv.y);
;                     o[4] = sigm(a1[0]) * lo16(tv.z); o[5] = sigm(a1[1]) * hi16(tv.z); o[6] = sigm(a1[2]) * lo16(tv.w); o[7] = sigm(a1[3]) * hi16(tv.w);
;                     if (ACC) { o[0] += lo16(pv.x); o[1] += hi16(pv.x); o[2] += lo16(pv.y); o[3] += hi16(pv.y); o[4] += lo16(pv.z); o[5] += hi16(pv.z); o[6] += lo16(pv.w); o[7] += hi16(pv.w); }
;                     u32x4 w; w.x = cvt_pk_bf16(o[0], o[1]); w.y = cvt_pk_bf16(o[2], o[3]); w.z = cvt_pk_bf16(o[4], o[5]); w.w = cvt_pk_bf16(o[6], o[7]);
;                     *(u32x4*)(M + off) = w; } }
	v_mul_f32_e32 v24, 0xbfb8aa3b, v26
	v_mul_f32_e32 v25, 0xbfb8aa3b, v27
	v_exp_f32_e32 v24, v24
	v_exp_f32_e32 v25, v25
	v_lshlrev_b32_e32 v26, 16, v39
	v_and_b32_e32 v27, 0xffff0000, v39
	v_add_f32_e32 v24, 1.0, v24
	v_add_f32_e32 v25, 1.0, v25
	v_rcp_f32_e32 v24, v24
	v_rcp_f32_e32 v25, v25
	v_pk_mul_f32 v[28:29], v[28:29], v[42:43]
	v_pk_mul_f32 v[38:39], v[24:25], v[26:27]
	v_cvt_pk_bf16_f32 v24, v28, v29
	v_cvt_pk_bf16_f32 v25, v30, v31
	v_cvt_pk_bf16_f32 v26, v36, v37
	v_cvt_pk_bf16_f32 v27, v38, v39
	global_store_dwordx4 v[40:41], v[24:27], off
	s_nop 1
	v_mov_b32_e32 v24, v248
	v_mov_b32_e32 v25, v249
	v_mov_b32_e32 v26, v250
	v_mov_b32_e32 v27, v251
	v_lshlrev_b32_e32 v28, 16, v24
	v_and_b32_e32 v29, 0xffff0000, v24
	v_lshlrev_b32_e32 v24, 16, v25
	v_and_b32_e32 v25, 0xffff0000, v25
	v_pk_mul_f32 v[22:23], v[22:23], v[24:25]
	v_lshlrev_b32_e32 v24, 16, v26
	v_and_b32_e32 v25, 0xffff0000, v26
	v_pk_mul_f32 v[24:25], v[16:17], v[24:25]
	v_mul_f32_e32 v16, 0xbfb8aa3b, v18
	v_mul_f32_e32 v17, 0xbfb8aa3b, v19
	v_exp_f32_e32 v16, v16
	v_exp_f32_e32 v17, v17
	v_lshlrev_b32_e32 v18, 16, v27
	v_and_b32_e32 v19, 0xffff0000, v27
	v_add_f32_e32 v16, 1.0, v16
	v_add_f32_e32 v17, 1.0, v17
	v_rcp_f32_e32 v16, v16
	v_rcp_f32_e32 v17, v17
	v_pk_mul_f32 v[20:21], v[20:21], v[28:29]
	v_pk_mul_f32 v[26:27], v[16:17], v[18:19]
	v_cvt_pk_bf16_f32 v16, v20, v21
	v_cvt_pk_bf16_f32 v17, v22, v23
	v_cvt_pk_bf16_f32 v18, v24, v25
	v_cvt_pk_bf16_f32 v19, v26, v27
	global_store_dwordx4 v[32:33], v[16:19], off offset:256
	s_nop 1
	v_mov_b32_e32 v16, v169
	v_fmamk_f32 v16, v16, 0x3a800000, v187
	v_cmp_gt_f32_e32 vcc, s67, v16
	v_mul_f32_e32 v17, 0x4b800000, v16
	s_nop 0
	v_cndmask_b32_e32 v16, v16, v17, vcc
	v_rsq_f32_e32 v16, v16
	s_nop 0
	v_mul_f32_e32 v17, 0x45800000, v16
	v_cndmask_b32_e32 v18, v16, v17, vcc
	v_add_co_u32_e32 v24, vcc, s2, v158
	v_pk_mul_f32 v[14:15], v[14:15], v[18:19] op_sel_hi:[1,0]
	s_nop 0
	v_addc_co_u32_e32 v25, vcc, 0, v159, vcc
	s_nop 1
	v_mov_b32_e32 v20, v176
	v_mov_b32_e32 v21, v177
	v_mov_b32_e32 v22, v178
	v_mov_b32_e32 v23, v179
	v_pk_mul_f32 v[8:9], v[8:9], v[18:19] op_sel_hi:[1,0]
	v_mul_f32_e32 v14, 0xbfb8aa3b, v14
	v_mul_f32_e32 v15, 0xbfb8aa3b, v15
	v_exp_f32_e32 v14, v14
	v_exp_f32_e32 v15, v15
	v_mul_f32_e32 v8, 0xbfb8aa3b, v8
	v_mul_f32_e32 v9, 0xbfb8aa3b, v9
	v_exp_f32_e32 v8, v8
	v_exp_f32_e32 v9, v9
	v_add_f32_e32 v14, 1.0, v14
	v_add_f32_e32 v15, 1.0, v15
	v_rcp_f32_e32 v14, v14
	v_rcp_f32_e32 v15, v15
	v_add_f32_e32 v8, 1.0, v8
	v_add_f32_e32 v9, 1.0, v9
	v_rcp_f32_e32 v8, v8
	v_rcp_f32_e32 v9, v9
	v_pk_mul_f32 v[12:13], v[12:13], v[18:19] op_sel_hi:[1,0]
	v_pk_mul_f32 v[10:11], v[10:11], v[18:19] op_sel_hi:[1,0]
	v_mul_f32_e32 v12, 0xbfb8aa3b, v12
	v_mul_f32_e32 v13, 0xbfb8aa3b, v13
	v_exp_f32_e32 v12, v12
	v_exp_f32_e32 v13, v13
	v_lshl_add_u64 v[16:17], v[158:159], 0, s[4:5]
	v_pk_mul_f32 v[6:7], v[6:7], v[18:19] op_sel_hi:[1,0]
	v_add_f32_e32 v12, 1.0, v12
	v_add_f32_e32 v13, 1.0, v13
	v_rcp_f32_e32 v12, v12
	v_rcp_f32_e32 v13, v13
	v_pk_mul_f32 v[0:1], v[0:1], v[18:19] op_sel_hi:[1,0]
	v_mul_f32_e32 v6, 0xbfb8aa3b, v6
	v_mul_f32_e32 v7, 0xbfb8aa3b, v7
	v_exp_f32_e32 v6, v6
	v_exp_f32_e32 v7, v7
	v_mul_f32_e32 v0, 0xbfb8aa3b, v0
	v_mul_f32_e32 v1, 0xbfb8aa3b, v1
	v_exp_f32_e32 v0, v0
	v_exp_f32_e32 v1, v1
	v_add_f32_e32 v6, 1.0, v6
	v_add_f32_e32 v7, 1.0, v7
	v_rcp_f32_e32 v6, v6
	v_rcp_f32_e32 v7, v7
	v_add_f32_e32 v0, 1.0, v0
	v_add_f32_e32 v1, 1.0, v1
	v_rcp_f32_e32 v0, v0
	v_rcp_f32_e32 v1, v1
	v_pk_mul_f32 v[4:5], v[4:5], v[18:19] op_sel_hi:[1,0]
	v_pk_mul_f32 v[2:3], v[2:3], v[18:19] op_sel_hi:[1,0]
	v_mul_f32_e32 v4, 0xbfb8aa3b, v4
	v_mul_f32_e32 v5, 0xbfb8aa3b, v5
	v_exp_f32_e32 v4, v4
	v_exp_f32_e32 v5, v5
	s_and_b64 vcc, exec, s[38:39]
	s_mov_b32 s2, s30
	v_add_f32_e32 v4, 1.0, v4
	v_add_f32_e32 v5, 1.0, v5
	v_rcp_f32_e32 v4, v4
	v_rcp_f32_e32 v5, v5
	s_mov_b64 s[4:5], s[48:49]
	v_lshlrev_b32_e32 v26, 16, v20
	v_and_b32_e32 v27, 0xffff0000, v20
	v_lshlrev_b32_e32 v20, 16, v21
	v_and_b32_e32 v21, 0xffff0000, v21
	v_pk_mul_f32 v[14:15], v[14:15], v[20:21]
	v_lshlrev_b32_e32 v20, 16, v22
	v_and_b32_e32 v21, 0xffff0000, v22
	v_pk_mul_f32 v[20:21], v[8:9], v[20:21]
	v_mul_f32_e32 v8, 0xbfb8aa3b, v10
	v_mul_f32_e32 v9, 0xbfb8aa3b, v11
	v_exp_f32_e32 v8, v8
	v_exp_f32_e32 v9, v9
	v_lshlrev_b32_e32 v10, 16, v23
	v_and_b32_e32 v11, 0xffff0000, v23
	v_add_f32_e32 v8, 1.0, v8
	v_add_f32_e32 v9, 1.0, v9
	v_rcp_f32_e32 v8, v8
	v_rcp_f32_e32 v9, v9
	v_pk_mul_f32 v[12:13], v[12:13], v[26:27]
	v_pk_mul_f32 v[22:23], v[8:9], v[10:11]
	v_cvt_pk_bf16_f32 v8, v12, v13
	v_cvt_pk_bf16_f32 v9, v14, v15
	v_cvt_pk_bf16_f32 v10, v20, v21
	v_cvt_pk_bf16_f32 v11, v22, v23
	global_store_dwordx4 v[24:25], v[8:11], off
	s_nop 1
	v_mov_b32_e32 v8, v252
	v_mov_b32_e32 v9, v253
	v_mov_b32_e32 v10, v254
	v_mov_b32_e32 v11, v255
	v_lshlrev_b32_e32 v12, 16, v8
	v_and_b32_e32 v13, 0xffff0000, v8
	v_lshlrev_b32_e32 v8, 16, v9
	v_and_b32_e32 v9, 0xffff0000, v9
	v_pk_mul_f32 v[6:7], v[6:7], v[8:9]
	v_lshlrev_b32_e32 v8, 16, v10
	v_and_b32_e32 v9, 0xffff0000, v10
	v_pk_mul_f32 v[8:9], v[0:1], v[8:9]
	v_mul_f32_e32 v0, 0xbfb8aa3b, v2
	v_mul_f32_e32 v1, 0xbfb8aa3b, v3
	v_exp_f32_e32 v0, v0
	v_exp_f32_e32 v1, v1
	v_lshlrev_b32_e32 v2, 16, v11
	v_and_b32_e32 v3, 0xffff0000, v11
	v_add_f32_e32 v0, 1.0, v0
	v_add_f32_e32 v1, 1.0, v1
	v_rcp_f32_e32 v0, v0
	v_rcp_f32_e32 v1, v1
	v_pk_mul_f32 v[4:5], v[4:5], v[12:13]
	v_pk_mul_f32 v[10:11], v[0:1], v[2:3]
	v_cvt_pk_bf16_f32 v0, v4, v5
	v_cvt_pk_bf16_f32 v1, v6, v7
	v_cvt_pk_bf16_f32 v2, v8, v9
	v_cvt_pk_bf16_f32 v3, v10, v11
	global_store_dwordx4 v[16:17], v[0:3], off offset:256
	s_cbranch_vccz .LBB0_306
	s_cmpk_gt_u32 s36, 0xff
	s_cbranch_scc1 .LBB0_317
	s_barrier

; #define PG8_STAGE(bufoff, gbase, voff) do { _Pragma("unroll") for (int _i = 0; _i < 2; ++_i) \
;         __builtin_amdgcn_global_load_lds((const unsigned*)((const char*)(gbase) + (voff)[_i]), (PG8_LAS unsigned*)(lds + (bufoff) + ldsw + _i * 8192), 16, 0, 0); } while (0)
; #define PG8_LDA(dst, b, h) do { _Pragma("unroll") for (int m = 0; m < 4; ++m) _Pragma("unroll") for (int k = 0; k < 2; ++k) dst[m][k] = *(const PG8_LAS bf16x8*)(lds + PG8_SA(b, h) + aoff + m * 2048 + k * 1024); } while (0)
; #define PG8_LDB(dst, b, h) do { _Pragma("unroll") for (int n = 0; n < 2; ++n) _Pragma("unroll") for (int k = 0; k < 2; ++k) dst[n][k] = *(const PG8_LAS bf16x8*)(lds + PG8_SB(b, h) + boff + n * 2048 + k * 1024); } while (0)
; #define PG8_MMA(ai, bj, At, Bt) do { __builtin_amdgcn_s_setprio(1); _Pragma("unroll") for (int m = 0; m < 4; ++m) _Pragma("unroll") for (int n = 0; n < 2; ++n) _Pragma("unroll") for (int k = 0; k < 2; ++k) \
;         acc[ai][bj][m][n] = __builtin_amdgcn_mfma_f32_16x16x32_bf16(Bt[n][k], At[m][k], acc[ai][bj][m][n], 0, 0, 0); __builtin_amdgcn_s_setprio(0); } while (0)
; #define PG8_WAIT_L(n) asm volatile("s_waitcnt lgkmcnt(" #n ")" ::: "memory")
; #define PG8_BAR __builtin_amdgcn_s_barrier()
; #define PG8_SCHED __builtin_amdgcn_sched_barrier(0)
; template <class Epi, class Sched, bool STAMP = false>
; __device__ __forceinline__ void gemm_phase(PG8_LAS unsigned char* lds, const Gemm g, const Sched& S, const Epi& E, unsigned long long* stamps) {
;     ...
;             const bool last = (t == nt - 2);
;             const char* a1 = cA + (size_t)(t + 1) * kstep;
;             const char* a2 = last ? nA : cA + (size_t)(t + 2) * kstep; const char* b2 = last ? nB : cB + (size_t)(t + 2) * kstep;
;             const char* a3 = a2 + kstep; const char* b3 = b2 + kstep;
;             if (last && has_next) S.a_ready(nxt);
;             PG8_LDB(B0, 0, 0); PG8_SCHED; PG8_LDA(At, 0, 0); PG8_STAGE(PG8_SA(1, 1), a1 + hstep, voffA);
;             PG8_WAIT_L(8); PG8_BAR; PG8_WAIT_L(0); PG8_MMA(0, 0, At, B0); PG8_BAR; PG8_SCHED;
;             PG8_LDB(B1, 0, 1); PG8_STAGE(PG8_SB(0, 0), b2, voffB);
;             PG8_BAR; PG8_WAIT_L(0); PG8_MMA(0, 1, At, B1); PG8_BAR;
;             PG8_LDA(At, 0, 1); PG8_STAGE(PG8_SA(0, 0), a2, voffA);
;             PG8_BAR; PG8_WAIT_L(0); PG8_MMA(1, 0, At, B0); PG8_BAR; PG8_SCHED;
.LBB0_333:
	s_add_u32 s14, s36, 0xfffe0080
	s_addc_u32 s15, s37, -1
	s_add_i32 s16, 0, 0x10000
	v_add_u32_e32 v161, s16, v158
	ds_read_b128 v[162:165], v161
	ds_read_b128 v[166:169], v161 offset:1024
	ds_read_b128 v[170:173], v161 offset:2048
	ds_read_b128 v[174:177], v161 offset:3072
	s_cmp_eq_u32 s97, 4
	s_cselect_b32 s59, s13, s15
	s_cselect_b32 s58, s77, s14
	s_cselect_b32 s57, s5, s96
	s_cselect_b32 s56, s88, s89
	v_lshl_add_u64 v[182:183], s[36:37], 0, v[154:155]
	s_add_i32 m0, s3, 0xc000
	ds_read_b128 v[178:181], v160
	ds_read_b128 v[192:195], v160 offset:1024
	ds_read_b128 v[196:199], v160 offset:2048
	ds_read_b128 v[200:203], v160 offset:3072
	ds_read_b128 v[204:207], v160 offset:4096
	ds_read_b128 v[208:211], v160 offset:5120
	ds_read_b128 v[212:215], v160 offset:6144
	ds_read_b128 v[216:219], v160 offset:7168
	global_load_lds_dwordx4 v[182:183], off
	v_lshl_add_u64 v[182:183], s[36:37], 0, v[156:157]
	s_add_i32 m0, s3, 0xe000
	s_nop 0
	global_load_lds_dwordx4 v[182:183], off
	s_waitcnt lgkmcnt(8)
	s_barrier
	s_waitcnt lgkmcnt(0)
	s_setprio 1
	s_waitcnt lgkmcnt(0)
	v_mfma_f32_16x16x32_bf16 v[124:127], v[162:165], v[178:181], v[124:127]
	v_mfma_f32_16x16x32_bf16 v[120:123], v[170:173], v[178:181], v[120:123]
	v_mfma_f32_16x16x32_bf16 v[116:119], v[162:165], v[196:199], v[116:119]
	v_mfma_f32_16x16x32_bf16 v[112:115], v[170:173], v[196:199], v[112:115]
	v_mfma_f32_16x16x32_bf16 v[100:103], v[162:165], v[204:207], v[100:103]
	v_mfma_f32_16x16x32_bf16 v[96:99], v[170:173], v[204:207], v[96:99]
	v_mfma_f32_16x16x32_bf16 v[84:87], v[162:165], v[212:215], v[84:87]
	v_mfma_f32_16x16x32_bf16 v[80:83], v[170:173], v[212:215], v[80:83]
	v_mfma_f32_16x16x32_bf16 v[124:127], v[166:169], v[192:195], v[124:127]
	v_mfma_f32_16x16x32_bf16 v[120:123], v[174:177], v[192:195], v[120:123]
	v_mfma_f32_16x16x32_bf16 v[116:119], v[166:169], v[200:203], v[116:119]
	v_mfma_f32_16x16x32_bf16 v[112:115], v[174:177], v[200:203], v[112:115]
	v_mfma_f32_16x16x32_bf16 v[100:103], v[166:169], v[208:211], v[100:103]
	v_mfma_f32_16x16x32_bf16 v[96:99], v[174:177], v[208:211], v[96:99]
	v_mfma_f32_16x16x32_bf16 v[84:87], v[166:169], v[216:219], v[84:87]
	v_mfma_f32_16x16x32_bf16 v[80:83], v[174:177], v[216:219], v[80:83]
	s_setprio 0
	s_barrier
	s_add_i32 s17, 0, 0x14000
	s_add_i32 s14, s16, s53
	v_add_u32_e32 v161, s17, v158
	v_lshl_add_u64 v[182:183], s[56:57], 0, v[128:129]
	s_mov_b32 m0, s14
	ds_read_b128 v[220:223], v161
	ds_read_b128 v[224:227], v161 offset:1024
	ds_read_b128 v[228:231], v161 offset:2048
	ds_read_b128 v[232:235], v161 offset:3072
	global_load_lds_dwordx4 v[182:183], off
	v_lshl_add_u64 v[236:237], s[56:57], 0, v[152:153]
	s_add_i32 m0, s14, 0x2000
	s_nop 0
	global_load_lds_dwordx4 v[236:237], off
	s_barrier
	s_waitcnt lgkmcnt(0)
	s_setprio 1
	s_waitcnt lgkmcnt(0)
	v_mfma_f32_16x16x32_bf16 v[108:111], v[220:223], v[178:181], v[108:111]
	v_mfma_f32_16x16x32_bf16 v[104:107], v[228:231], v[178:181], v[104:107]
	v_mfma_f32_16x16x32_bf16 v[92:95], v[220:223], v[196:199], v[92:95]
	v_mfma_f32_16x16x32_bf16 v[88:91], v[228:231], v[196:199], v[88:91]
	v_mfma_f32_16x16x32_bf16 v[76:79], v[220:223], v[204:207], v[76:79]
	v_mfma_f32_16x16x32_bf16 v[72:75], v[228:231], v[204:207], v[72:75]
	v_mfma_f32_16x16x32_bf16 v[68:71], v[220:223], v[212:215], v[68:71]
	v_mfma_f32_16x16x32_bf16 v[64:67], v[228:231], v[212:215], v[64:67]
	v_mfma_f32_16x16x32_bf16 v[108:111], v[224:227], v[192:195], v[108:111]
	v_mfma_f32_16x16x32_bf16 v[104:107], v[232:235], v[192:195], v[104:107]
	v_mfma_f32_16x16x32_bf16 v[92:95], v[224:227], v[200:203], v[92:95]
	v_mfma_f32_16x16x32_bf16 v[88:91], v[232:235], v[200:203], v[88:91]
	v_mfma_f32_16x16x32_bf16 v[76:79], v[224:227], v[208:211], v[76:79]
	v_mfma_f32_16x16x32_bf16 v[72:75], v[232:235], v[208:211], v[72:75]
	v_mfma_f32_16x16x32_bf16 v[68:71], v[224:227], v[216:219], v[68:71]
	v_mfma_f32_16x16x32_bf16 v[64:67], v[232:235], v[216:219], v[64:67]
	s_setprio 0
	s_mov_b32 m0, s3
	v_lshl_add_u64 v[238:239], s[58:59], 0, v[148:149]
	s_barrier
	ds_read_b128 v[178:181], v160 offset:16384
	ds_read_b128 v[192:195], v160 offset:17408
	ds_read_b128 v[196:199], v160 offset:18432
	ds_read_b128 v[200:203], v160 offset:19456
	ds_read_b128 v[204:207], v160 offset:20480
	ds_read_b128 v[208:211], v160 offset:21504
	ds_read_b128 v[212:215], v160 offset:22528
	ds_read_b128 v[216:219], v160 offset:23552
	global_load_lds_dwordx4 v[238:239], off
	v_lshl_add_u64 v[240:241], s[58:59], 0, v[150:151]
	s_mov_b32 m0, s60
	s_nop 0
	global_load_lds_dwordx4 v[240:241], off
	s_barrier
	s_waitcnt lgkmcnt(0)
	s_setprio 1
	s_waitcnt lgkmcnt(0)
	v_mfma_f32_16x16x32_bf16 v[60:63], v[162:165], v[178:181], v[60:63]
	v_mfma_f32_16x16x32_bf16 v[56:59], v[170:173], v[178:181], v[56:59]
	v_mfma_f32_16x16x32_bf16 v[52:55], v[162:165], v[196:199], v[52:55]
	v_mfma_f32_16x16x32_bf16 v[48:51], v[170:173], v[196:199], v[48:51]
	v_mfma_f32_16x16x32_bf16 v[36:39], v[162:165], v[204:207], v[36:39]
	v_mfma_f32_16x16x32_bf16 v[32:35], v[170:173], v[204:207], v[32:35]
	v_mfma_f32_16x16x32_bf16 v[20:23], v[162:165], v[212:215], v[20:23]
	v_mfma_f32_16x16x32_bf16 v[16:19], v[170:173], v[212:215], v[16:19]
	v_mfma_f32_16x16x32_bf16 v[60:63], v[166:169], v[192:195], v[60:63]
	v_mfma_f32_16x16x32_bf16 v[56:59], v[174:177], v[192:195], v[56:59]
	v_mfma_f32_16x16x32_bf16 v[52:55], v[166:169], v[200:203], v[52:55]
	v_mfma_f32_16x16x32_bf16 v[48:51], v[174:177], v[200:203], v[48:51]
	v_mfma_f32_16x16x32_bf16 v[36:39], v[166:169], v[208:211], v[36:39]
	v_mfma_f32_16x16x32_bf16 v[32:35], v[174:177], v[208:211], v[32:35]
	v_mfma_f32_16x16x32_bf16 v[20:23], v[166:169], v[216:219], v[20:23]
	v_mfma_f32_16x16x32_bf16 v[16:19], v[174:177], v[216:219], v[16:19]
	s_setprio 0
	s_barrier
; #define PG8_STAGE(bufoff, gbase, voff) do { _Pragma("unroll") for (int _i = 0; _i < 2; ++_i) \
;         __builtin_amdgcn_global_load_lds((const unsigned*)((const char*)(gbase) + (voff)[_i]), (PG8_LAS unsigned*)(lds + (bufoff) + ldsw + _i * 8192), 16, 0, 0); } while (0)
; #define PG8_LDA(dst, b, h) do { _Pragma("unroll") for (int m = 0; m < 4; ++m) _Pragma("unroll") for (int k = 0; k < 2; ++k) dst[m][k] = *(const PG8_LAS bf16x8*)(lds + PG8_SA(b, h) + aoff + m * 2048 + k * 1024); } while (0)
; #define PG8_LDB(dst, b, h) do { _Pragma("unroll") for (int n = 0; n < 2; ++n) _Pragma("unroll") for (int k = 0; k < 2; ++k) dst[n][k] = *(const PG8_LAS bf16x8*)(lds + PG8_SB(b, h) + boff + n * 2048 + k * 1024); } while (0)
; #define PG8_MMA(ai, bj, At, Bt) do { __builtin_amdgcn_s_setprio(1); _Pragma("unroll") for (int m = 0; m < 4; ++m) _Pragma("unroll") for (int n = 0; n < 2; ++n) _Pragma("unroll") for (int k = 0; k < 2; ++k) \
;         acc[ai][bj][m][n] = __builtin_amdgcn_mfma_f32_16x16x32_bf16(Bt[n][k], At[m][k], acc[ai][bj][m][n], 0, 0, 0); __builtin_amdgcn_s_setprio(0); } while (0)
; #define PG8_WAIT_V(n) asm volatile("s_waitcnt vmcnt(" #n ")" ::: "memory")
; #define PG8_WAIT_L(n) asm volatile("s_waitcnt lgkmcnt(" #n ")" ::: "memory")
; #define PG8_BAR __builtin_amdgcn_s_barrier()
; #define PG8_SCHED __builtin_amdgcn_sched_barrier(0)
; template <class Epi, class Sched, bool STAMP = false>
; __device__ __forceinline__ void gemm_phase(PG8_LAS unsigned char* lds, const Gemm g, const Sched& S, const Epi& E, unsigned long long* stamps) {
;     ...
;             PG8_STAGE(PG8_SB(0, 1), b2 + hstep, voffB);
;             PG8_WAIT_V(6); PG8_BAR; PG8_MMA(1, 1, At, B1); PG8_BAR;
;             PG8_LDB(B0, 1, 0); PG8_SCHED; PG8_LDA(At, 1, 0); PG8_STAGE(PG8_SA(0, 1), a2 + hstep, voffA);
;             PG8_WAIT_L(8); PG8_BAR; PG8_WAIT_L(0); PG8_MMA(0, 0, At, B0); PG8_BAR; PG8_SCHED;
;             PG8_LDB(B1, 1, 1); PG8_STAGE(PG8_SB(1, 0), b3, voffB);
;             PG8_BAR; PG8_WAIT_L(0); PG8_MMA(0, 1, At, B1); PG8_BAR;
;             PG8_LDA(At, 1, 1); PG8_STAGE(PG8_SA(1, 0), a3, voffA);
	s_add_u32 s14, s56, 0x20000
	s_addc_u32 s15, s57, 0
	s_add_i32 s16, s17, s53
	v_lshl_add_u64 v[162:163], s[14:15], 0, v[128:129]
	s_mov_b32 m0, s16
	s_nop 0
	global_load_lds_dwordx4 v[162:163], off
	v_lshl_add_u64 v[162:163], s[14:15], 0, v[152:153]
	s_add_i32 m0, s16, 0x2000
	s_nop 0
	global_load_lds_dwordx4 v[162:163], off
	s_waitcnt vmcnt(6)
	s_barrier
	s_setprio 1
	v_mfma_f32_16x16x32_bf16 v[44:47], v[220:223], v[178:181], v[44:47]
	v_mfma_f32_16x16x32_bf16 v[40:43], v[228:231], v[178:181], v[40:43]
	v_mfma_f32_16x16x32_bf16 v[28:31], v[220:223], v[196:199], v[28:31]
	v_mfma_f32_16x16x32_bf16 v[24:27], v[228:231], v[196:199], v[24:27]
	v_mfma_f32_16x16x32_bf16 v[12:15], v[220:223], v[204:207], v[12:15]
	v_mfma_f32_16x16x32_bf16 v[8:11], v[228:231], v[204:207], v[8:11]
	v_mfma_f32_16x16x32_bf16 v[4:7], v[220:223], v[212:215], v[4:7]
	v_mfma_f32_16x16x32_bf16 v[0:3], v[228:231], v[212:215], v[0:3]
	v_mfma_f32_16x16x32_bf16 v[44:47], v[224:227], v[192:195], v[44:47]
	v_mfma_f32_16x16x32_bf16 v[40:43], v[232:235], v[192:195], v[40:43]
	v_mfma_f32_16x16x32_bf16 v[28:31], v[224:227], v[200:203], v[28:31]
	v_mfma_f32_16x16x32_bf16 v[24:27], v[232:235], v[200:203], v[24:27]
	v_mfma_f32_16x16x32_bf16 v[12:15], v[224:227], v[208:211], v[12:15]
	v_mfma_f32_16x16x32_bf16 v[8:11], v[232:235], v[208:211], v[8:11]
	v_mfma_f32_16x16x32_bf16 v[4:7], v[224:227], v[216:219], v[4:7]
	v_mfma_f32_16x16x32_bf16 v[0:3], v[232:235], v[216:219], v[0:3]
	s_setprio 0
	s_add_i32 s16, 0, 0x18000
	v_add_u32_e32 v161, s16, v158
	s_barrier
	ds_read_b128 v[162:165], v161
	ds_read_b128 v[166:169], v161 offset:1024
	ds_read_b128 v[170:173], v161 offset:2048
	ds_read_b128 v[174:177], v161 offset:3072
	s_add_u32 s14, s58, 0x20000
	s_addc_u32 s15, s59, 0
	s_mov_b32 m0, s61
	v_lshl_add_u64 v[220:221], s[14:15], 0, v[148:149]
	ds_read_b128 v[178:181], v160 offset:32768
	ds_read_b128 v[192:195], v160 offset:33792
	ds_read_b128 v[196:199], v160 offset:34816
	ds_read_b128 v[200:203], v160 offset:35840
	ds_read_b128 v[204:207], v160 offset:36864
	ds_read_b128 v[208:211], v160 offset:37888
	ds_read_b128 v[212:215], v160 offset:38912
	ds_read_b128 v[216:219], v160 offset:39936
	global_load_lds_dwordx4 v[220:221], off
	v_lshl_add_u64 v[220:221], s[14:15], 0, v[150:151]
	s_mov_b32 m0, s62
	s_nop 0
	global_load_lds_dwordx4 v[220:221], off
	s_waitcnt lgkmcnt(8)
	s_barrier
	s_waitcnt lgkmcnt(0)
	s_setprio 1
	s_waitcnt lgkmcnt(0)
	v_mfma_f32_16x16x32_bf16 v[124:127], v[162:165], v[178:181], v[124:127]
	v_mfma_f32_16x16x32_bf16 v[120:123], v[170:173], v[178:181], v[120:123]
	v_mfma_f32_16x16x32_bf16 v[116:119], v[162:165], v[196:199], v[116:119]
	v_mfma_f32_16x16x32_bf16 v[112:115], v[170:173], v[196:199], v[112:115]
	v_mfma_f32_16x16x32_bf16 v[100:103], v[162:165], v[204:207], v[100:103]
	v_mfma_f32_16x16x32_bf16 v[96:99], v[170:173], v[204:207], v[96:99]
	v_mfma_f32_16x16x32_bf16 v[84:87], v[162:165], v[212:215], v[84:87]
	v_mfma_f32_16x16x32_bf16 v[80:83], v[170:173], v[212:215], v[80:83]
	v_mfma_f32_16x16x32_bf16 v[124:127], v[166:169], v[192:195], v[124:127]
	v_mfma_f32_16x16x32_bf16 v[120:123], v[174:177], v[192:195], v[120:123]
	v_mfma_f32_16x16x32_bf16 v[116:119], v[166:169], v[200:203], v[116:119]
	v_mfma_f32_16x16x32_bf16 v[112:115], v[174:177], v[200:203], v[112:115]
	v_mfma_f32_16x16x32_bf16 v[100:103], v[166:169], v[208:211], v[100:103]
	v_mfma_f32_16x16x32_bf16 v[96:99], v[174:177], v[208:211], v[96:99]
	v_mfma_f32_16x16x32_bf16 v[84:87], v[166:169], v[216:219], v[84:87]
	v_mfma_f32_16x16x32_bf16 v[80:83], v[174:177], v[216:219], v[80:83]
	s_setprio 0
	s_barrier
	s_add_i32 s17, 0, 0x1c000
	s_add_i32 s14, s16, s53
	v_add_u32_e32 v161, s17, v158
	v_lshl_add_u64 v[182:183], v[182:183], 0, s[18:19]
	s_mov_b32 m0, s14
	ds_read_b128 v[220:223], v161
	ds_read_b128 v[224:227], v161 offset:1024
	ds_read_b128 v[228:231], v161 offset:2048
	ds_read_b128 v[232:235], v161 offset:3072
	global_load_lds_dwordx4 v[182:183], off
	v_lshl_add_u64 v[182:183], v[236:237], 0, s[18:19]
	s_add_i32 m0, s14, 0x2000
	s_nop 0
	global_load_lds_dwordx4 v[182:183], off
	s_barrier
	s_waitcnt lgkmcnt(0)
	s_setprio 1
	s_waitcnt lgkmcnt(0)
	v_mfma_f32_16x16x32_bf16 v[108:111], v[220:223], v[178:181], v[108:111]
	v_mfma_f32_16x16x32_bf16 v[104:107], v[228:231], v[178:181], v[104:107]
	v_mfma_f32_16x16x32_bf16 v[92:95], v[220:223], v[196:199], v[92:95]
	v_mfma_f32_16x16x32_bf16 v[88:91], v[228:231], v[196:199], v[88:91]
	v_mfma_f32_16x16x32_bf16 v[76:79], v[220:223], v[204:207], v[76:79]
	v_mfma_f32_16x16x32_bf16 v[72:75], v[228:231], v[204:207], v[72:75]
	v_mfma_f32_16x16x32_bf16 v[68:71], v[220:223], v[212:215], v[68:71]
	v_mfma_f32_16x16x32_bf16 v[64:67], v[228:231], v[212:215], v[64:67]
	v_mfma_f32_16x16x32_bf16 v[108:111], v[224:227], v[192:195], v[108:111]
	v_mfma_f32_16x16x32_bf16 v[104:107], v[232:235], v[192:195], v[104:107]
	v_mfma_f32_16x16x32_bf16 v[92:95], v[224:227], v[200:203], v[92:95]
	v_mfma_f32_16x16x32_bf16 v[88:91], v[232:235], v[200:203], v[88:91]
	v_mfma_f32_16x16x32_bf16 v[76:79], v[224:227], v[208:211], v[76:79]
	v_mfma_f32_16x16x32_bf16 v[72:75], v[232:235], v[208:211], v[72:75]
	v_mfma_f32_16x16x32_bf16 v[68:71], v[224:227], v[216:219], v[68:71]
	v_mfma_f32_16x16x32_bf16 v[64:67], v[232:235], v[216:219], v[64:67]
	s_setprio 0
	s_mov_b32 m0, s63
	v_lshl_add_u64 v[182:183], v[238:239], 0, s[18:19]
	s_barrier
	ds_read_b128 v[178:181], v160 offset:49152
	ds_read_b128 v[192:195], v160 offset:50176
	ds_read_b128 v[196:199], v160 offset:51200
	ds_read_b128 v[200:203], v160 offset:52224
	ds_read_b128 v[204:207], v160 offset:53248
	ds_read_b128 v[208:211], v160 offset:54272
	ds_read_b128 v[212:215], v160 offset:55296
	ds_read_b128 v[216:219], v160 offset:56320
	global_load_lds_dwordx4 v[182:183], off
	v_lshl_add_u64 v[182:183], v[240:241], 0, s[18:19]
	s_mov_b32 m0, s64
	s_nop 0
	global_load_lds_dwordx4 v[182:183], off
	s_barrier
; #define PG8_STAGE(bufoff, gbase, voff) do { _Pragma("unroll") for (int _i = 0; _i < 2; ++_i) \
;         __builtin_amdgcn_global_load_lds((const unsigned*)((const char*)(gbase) + (voff)[_i]), (PG8_LAS unsigned*)(lds + (bufoff) + ldsw + _i * 8192), 16, 0, 0); } while (0)
; #define PG8_MMA(ai, bj, At, Bt) do { __builtin_amdgcn_s_setprio(1); _Pragma("unroll") for (int m = 0; m < 4; ++m) _Pragma("unroll") for (int n = 0; n < 2; ++n) _Pragma("unroll") for (int k = 0; k < 2; ++k) \
;         acc[ai][bj][m][n] = __builtin_amdgcn_mfma_f32_16x16x32_bf16(Bt[n][k], At[m][k], acc[ai][bj][m][n], 0, 0, 0); __builtin_amdgcn_s_setprio(0); } while (0)
; #define PG8_WAIT_V(n) asm volatile("s_waitcnt vmcnt(" #n ")" ::: "memory")
; #define PG8_WAIT_L(n) asm volatile("s_waitcnt lgkmcnt(" #n ")" ::: "memory")
; #define PG8_BAR __builtin_amdgcn_s_barrier()
; #define PG8_SCHED __builtin_amdgcn_sched_barrier(0)
; template <class Epi, class Sched, bool STAMP = false>
; __device__ __forceinline__ void gemm_phase(PG8_LAS unsigned char* lds, const Gemm g, const Sched& S, const Epi& E, unsigned long long* stamps) {
;     ...
;             PG8_BAR; PG8_WAIT_L(0); PG8_MMA(1, 0, At, B0); PG8_BAR; PG8_SCHED;
;             PG8_STAGE(PG8_SB(1, 1), b3 + hstep, voffB);
;             PG8_WAIT_V(6); PG8_BAR; PG8_MMA(1, 1, At, B1); PG8_BAR;
;         }
	s_waitcnt lgkmcnt(0)
	s_setprio 1
	s_waitcnt lgkmcnt(0)
	v_mfma_f32_16x16x32_bf16 v[60:63], v[162:165], v[178:181], v[60:63]
	v_mfma_f32_16x16x32_bf16 v[56:59], v[170:173], v[178:181], v[56:59]
	v_mfma_f32_16x16x32_bf16 v[52:55], v[162:165], v[196:199], v[52:55]
	v_mfma_f32_16x16x32_bf16 v[48:51], v[170:173], v[196:199], v[48:51]
	v_mfma_f32_16x16x32_bf16 v[36:39], v[162:165], v[204:207], v[36:39]
	v_mfma_f32_16x16x32_bf16 v[32:35], v[170:173], v[204:207], v[32:35]
	v_mfma_f32_16x16x32_bf16 v[20:23], v[162:165], v[212:215], v[20:23]
	v_mfma_f32_16x16x32_bf16 v[16:19], v[170:173], v[212:215], v[16:19]
	v_mfma_f32_16x16x32_bf16 v[60:63], v[166:169], v[192:195], v[60:63]
	v_mfma_f32_16x16x32_bf16 v[56:59], v[174:177], v[192:195], v[56:59]
	v_mfma_f32_16x16x32_bf16 v[52:55], v[166:169], v[200:203], v[52:55]
	v_mfma_f32_16x16x32_bf16 v[48:51], v[174:177], v[200:203], v[48:51]
	v_mfma_f32_16x16x32_bf16 v[36:39], v[166:169], v[208:211], v[36:39]
	v_mfma_f32_16x16x32_bf16 v[32:35], v[174:177], v[208:211], v[32:35]
	v_mfma_f32_16x16x32_bf16 v[20:23], v[166:169], v[216:219], v[20:23]
	v_mfma_f32_16x16x32_bf16 v[16:19], v[174:177], v[216:219], v[16:19]
	s_setprio 0
	s_barrier
	s_add_u32 s14, s56, 0x20080
	s_addc_u32 s15, s57, 0
	s_add_i32 s16, s17, s53
	v_lshl_add_u64 v[162:163], s[14:15], 0, v[128:129]
	s_mov_b32 m0, s16
	s_nop 0
	global_load_lds_dwordx4 v[162:163], off
	v_lshl_add_u64 v[162:163], s[14:15], 0, v[152:153]
	s_add_i32 m0, s16, 0x2000
	s_nop 0
	global_load_lds_dwordx4 v[162:163], off
	s_waitcnt vmcnt(6)
	s_barrier
	s_setprio 1
	v_mfma_f32_16x16x32_bf16 v[44:47], v[220:223], v[178:181], v[44:47]
	v_mfma_f32_16x16x32_bf16 v[40:43], v[228:231], v[178:181], v[40:43]
	v_mfma_f32_16x16x32_bf16 v[28:31], v[220:223], v[196:199], v[28:31]
	v_mfma_f32_16x16x32_bf16 v[24:27], v[228:231], v[196:199], v[24:27]
	v_mfma_f32_16x16x32_bf16 v[12:15], v[220:223], v[204:207], v[12:15]
	v_mfma_f32_16x16x32_bf16 v[8:11], v[228:231], v[204:207], v[8:11]
	v_mfma_f32_16x16x32_bf16 v[4:7], v[220:223], v[212:215], v[4:7]
	v_mfma_f32_16x16x32_bf16 v[0:3], v[228:231], v[212:215], v[0:3]
	v_mfma_f32_16x16x32_bf16 v[44:47], v[224:227], v[192:195], v[44:47]
	v_mfma_f32_16x16x32_bf16 v[40:43], v[232:235], v[192:195], v[40:43]
	v_mfma_f32_16x16x32_bf16 v[28:31], v[224:227], v[200:203], v[28:31]
	v_mfma_f32_16x16x32_bf16 v[24:27], v[232:235], v[200:203], v[24:27]
	v_mfma_f32_16x16x32_bf16 v[12:15], v[224:227], v[208:211], v[12:15]
	v_mfma_f32_16x16x32_bf16 v[8:11], v[232:235], v[208:211], v[8:11]
	v_mfma_f32_16x16x32_bf16 v[4:7], v[224:227], v[216:219], v[4:7]
	v_mfma_f32_16x16x32_bf16 v[0:3], v[232:235], v[216:219], v[0:3]
	s_setprio 0
	s_add_i32 s97, s97, 2
	s_add_u32 s36, s36, 0x100
	s_addc_u32 s37, s37, 0
	s_add_u32 s89, s89, 0x100
	s_addc_u32 s96, s96, 0
	s_cmp_gt_u32 s97, 5
	s_barrier
	s_cbranch_scc0 .LBB0_333
; __device__ __forceinline__ unsigned cvt_pk_bf16(float lo, float hi) { const f32x2_cv v = {lo, hi}; const bf16x2_cv b = __builtin_convertvector(v, bf16x2_cv); return __builtin_bit_cast(unsigned, b); }
; #define PG8_WAIT_V(n) asm volatile("s_waitcnt vmcnt(" #n ")" ::: "memory")
; #define PG8_BAR __builtin_amdgcn_s_barrier()
; __device__ __forceinline__ float rstd_of(const float* rowss, int row) { return rsqrtf(rowss[row] * (1.0f / 1024.0f) + 1e-6f); }
; template <class Epi, class Sched, bool STAMP = false>
; __device__ __forceinline__ void gemm_phase(PG8_LAS unsigned char* lds, const Gemm g, const Sched& S, const Epi& E, unsigned long long* stamps) {
;     ...
;         if constexpr (!Epi::AFTER_DRAIN) { E(acc, cur, wr, wc, fr, fq); S.done(cur); }
;         if (!has_next) break;
; #pragma unroll
;         for (int a = 0; a < 2; ++a)
; #pragma unroll
;             for (int b = 0; b < 2; ++b)
; #pragma unroll
;                 for (int m = 0; m < 4; ++m)
; #pragma unroll
;                     for (int n = 0; n < 2; ++n) acc[a][b][m][n] = (f32x4){0.f, 0.f, 0.f, 0.f};
;         cur = nxt; cA = nA; cB = nB; ++ui;
;     }
;     PG8_WAIT_V(0);
;     if (wr == 0) PG8_BAR;
;     PG8_BAR;
;     __device__ __forceinline__ void operator()(const f32x4 (&acc)[2][2][4][2], const pg8::Unit& u, int wr, int wc, int fr, int fq) const {
;         const int row0 = u.pm * 256 + wr * 64 + fr, col0 = u.pn * 256 + wc * 32 + 8 * fq;
; #pragma unroll
;         for (int ai = 0; ai < 2; ++ai)
; #pragma unroll
;             for (int m = 0; m < 4; ++m) {
;                 const int row = row0 + ai * 128 + m * 16;
;                 const float s = (MODE == 2) ? 1.0f : rstd_of(rowss, row);
;                 bf16_t* rowp = O + (size_t)row * ldc + col0;
; #pragma unroll
;                 for (int bj = 0; bj < 2; ++bj) {
;                     f32x4 v0 = acc[ai][bj][m][0] * s, v1 = acc[ai][bj][m][1] * s;
;                     if (MODE == 1) {
; #pragma unroll
;                         for (int j = 0; j < 4; ++j) { const float a = fmaxf(v0[j], 0.f), b = fmaxf(v1[j], 0.f); v0[j] = a * a; v1[j] = b * b; } }
;                     u32x4 w; w.x = cvt_pk_bf16(v0[0], v0[1]); w.y = cvt_pk_bf16(v0[2], v0[3]); w.z = cvt_pk_bf16(v1[0], v1[1]); w.w = cvt_pk_bf16(v1[2], v1[3]);
;                     *(u32x4*)(rowp + bj * 128) = w; } }
;     }
	v_lshl_add_u32 v162, s2, 8, v139
	v_lshl_or_b32 v164, s76, 8, v159
	v_ashrrev_i32_e32 v163, 31, v162
	v_ashrrev_i32_e32 v165, 31, v164
	v_lshlrev_b64 v[166:167], 11, v[162:163]
	v_lshl_add_u64 v[166:167], s[30:31], 0, v[166:167]
	v_lshlrev_b64 v[164:165], 1, v[164:165]
	v_lshl_add_u64 v[166:167], v[166:167], 0, v[164:165]
	s_mov_b32 s2, 0x40000
	s_mov_b64 s[14:15], 0x40000
	v_cvt_pk_bf16_f32 v60, v60, v61
	v_cvt_pk_bf16_f32 v61, v62, v63
	v_cvt_pk_bf16_f32 v62, v56, v57
	v_add_co_u32_e32 v56, vcc, s2, v166
	v_cvt_pk_bf16_f32 v68, v68, v69
	v_cvt_pk_bf16_f32 v69, v70, v71
	v_cvt_pk_bf16_f32 v70, v64, v65
	v_lshl_add_u64 v[64:65], v[166:167], 0, s[14:15]
	v_addc_co_u32_e32 v57, vcc, 0, v167, vcc
	v_cvt_pk_bf16_f32 v44, v44, v45
	v_cvt_pk_bf16_f32 v45, v46, v47
	v_cvt_pk_bf16_f32 v46, v40, v41
	v_cvt_pk_bf16_f32 v47, v42, v43
	s_mov_b32 s2, 0x48000
	v_cvt_pk_bf16_f32 v108, v108, v109
	v_cvt_pk_bf16_f32 v109, v110, v111
	v_cvt_pk_bf16_f32 v110, v104, v105
	v_or_b32_e32 v104, 16, v162
	global_store_dwordx4 v[64:65], v[44:47], off offset:256
	s_mov_b64 s[14:15], 0x48000
	v_ashrrev_i32_e32 v105, 31, v104
	v_add_co_u32_e32 v46, vcc, s2, v166
	v_cvt_pk_bf16_f32 v92, v92, v93
	v_cvt_pk_bf16_f32 v93, v94, v95
	v_cvt_pk_bf16_f32 v94, v88, v89
	v_or_b32_e32 v88, 32, v162
	v_lshl_add_u64 v[44:45], v[166:167], 0, s[14:15]
	v_addc_co_u32_e32 v47, vcc, 0, v167, vcc
	v_cvt_pk_bf16_f32 v28, v28, v29
	v_cvt_pk_bf16_f32 v29, v30, v31
	v_cvt_pk_bf16_f32 v30, v24, v25
	v_cvt_pk_bf16_f32 v31, v26, v27
	s_mov_b32 s2, 0x50000
	v_lshlrev_b64 v[104:105], 11, v[104:105]
	v_ashrrev_i32_e32 v89, 31, v88
	v_cvt_pk_bf16_f32 v76, v76, v77
	v_cvt_pk_bf16_f32 v77, v78, v79
	v_cvt_pk_bf16_f32 v78, v72, v73
	v_or_b32_e32 v72, 48, v162
	global_store_dwordx4 v[44:45], v[28:31], off offset:256
	s_mov_b64 s[14:15], 0x50000
	v_cvt_pk_bf16_f32 v111, v106, v107
	v_add_co_u32_e32 v30, vcc, s2, v166
	v_lshl_add_u64 v[104:105], s[30:31], 0, v[104:105]
	v_lshlrev_b64 v[88:89], 11, v[88:89]
	v_ashrrev_i32_e32 v73, 31, v72
	v_lshl_add_u64 v[28:29], v[166:167], 0, s[14:15]
	v_addc_co_u32_e32 v31, vcc, 0, v167, vcc
	v_cvt_pk_bf16_f32 v12, v12, v13
	v_cvt_pk_bf16_f32 v13, v14, v15
	v_cvt_pk_bf16_f32 v14, v8, v9
	v_cvt_pk_bf16_f32 v15, v10, v11
	s_mov_b32 s2, 0x58000
	global_store_dwordx4 v[166:167], v[108:111], off offset:256
	v_cvt_pk_bf16_f32 v95, v90, v91
	v_lshl_add_u64 v[88:89], s[30:31], 0, v[88:89]
	v_lshl_add_u64 v[108:109], v[104:105], 0, v[164:165]
	v_lshlrev_b64 v[72:73], 11, v[72:73]
	global_store_dwordx4 v[28:29], v[12:15], off offset:256
	global_store_dwordx4 v[108:109], v[92:95], off offset:256
	v_cvt_pk_bf16_f32 v79, v74, v75
	v_add_co_u32_e32 v14, vcc, s2, v166
	v_lshl_add_u64 v[92:93], v[88:89], 0, v[164:165]
	v_lshl_add_u64 v[72:73], s[30:31], 0, v[72:73]
	s_mov_b64 s[14:15], 0x58000
	v_addc_co_u32_e32 v15, vcc, 0, v167, vcc
	v_readlane_b32 s88, v242, 39
	v_cvt_pk_bf16_f32 v124, v124, v125
	v_cvt_pk_bf16_f32 v125, v126, v127
	v_cvt_pk_bf16_f32 v126, v120, v121
	v_cvt_pk_bf16_f32 v127, v122, v123
	v_cvt_pk_bf16_f32 v104, v116, v117
	v_cvt_pk_bf16_f32 v105, v118, v119
	v_cvt_pk_bf16_f32 v106, v112, v113
	v_cvt_pk_bf16_f32 v107, v114, v115
	v_cvt_pk_bf16_f32 v88, v100, v101
	v_cvt_pk_bf16_f32 v89, v102, v103
	v_cvt_pk_bf16_f32 v90, v96, v97
	v_cvt_pk_bf16_f32 v91, v98, v99
	global_store_dwordx4 v[92:93], v[76:79], off offset:256
	v_cvt_pk_bf16_f32 v74, v80, v81
	v_cvt_pk_bf16_f32 v75, v82, v83
	v_lshl_add_u64 v[76:77], v[72:73], 0, v[164:165]
	v_cvt_pk_bf16_f32 v72, v84, v85
	v_cvt_pk_bf16_f32 v73, v86, v87
	v_cvt_pk_bf16_f32 v71, v66, v67
	v_cvt_pk_bf16_f32 v63, v58, v59
	v_cvt_pk_bf16_f32 v40, v52, v53
	v_cvt_pk_bf16_f32 v41, v54, v55
	v_cvt_pk_bf16_f32 v42, v48, v49
	v_cvt_pk_bf16_f32 v43, v50, v51
	v_cvt_pk_bf16_f32 v24, v36, v37
	v_cvt_pk_bf16_f32 v25, v38, v39
	v_cvt_pk_bf16_f32 v26, v32, v33
	v_cvt_pk_bf16_f32 v27, v34, v35
	v_lshl_add_u64 v[12:13], v[166:167], 0, s[14:15]
	v_cvt_pk_bf16_f32 v8, v20, v21
	v_cvt_pk_bf16_f32 v9, v22, v23
	v_cvt_pk_bf16_f32 v10, v16, v17
	v_cvt_pk_bf16_f32 v11, v18, v19
	v_cvt_pk_bf16_f32 v4, v4, v5
	v_cvt_pk_bf16_f32 v5, v6, v7
	v_cvt_pk_bf16_f32 v6, v0, v1
	v_cvt_pk_bf16_f32 v7, v2, v3
	s_and_b64 vcc, exec, s[38:39]
	s_mov_b32 s76, s4
	s_mov_b32 s2, s12
	s_mov_b64 s[56:57], s[26:27]
	s_mov_b64 s[36:37], s[24:25]
	s_movk_i32 s77, 0xa0
	s_movk_i32 s58, 0xff60
	v_readlane_b32 s89, v242, 40
	global_store_dwordx4 v[166:167], v[124:127], off
	global_store_dwordx4 v[108:109], v[104:107], off
	global_store_dwordx4 v[92:93], v[88:91], off
	global_store_dwordx4 v[76:77], v[72:75], off
	global_store_dwordx4 v[76:77], v[68:71], off offset:256
	global_store_dwordx4 v[56:57], v[60:63], off
	global_store_dwordx4 v[46:47], v[40:43], off
	global_store_dwordx4 v[30:31], v[24:27], off
	global_store_dwordx4 v[14:15], v[8:11], off
	global_store_dwordx4 v[12:13], v[4:7], off offset:256
	s_cbranch_vccz .LBB0_326
	s_cmpk_gt_u32 s46, 0xff
	s_cbranch_scc1 .LBB0_337
	s_barrier

; #define PG8_STAGE(bufoff, gbase, voff) do { _Pragma("unroll") for (int _i = 0; _i < 2; ++_i) \
;         __builtin_amdgcn_global_load_lds((const unsigned*)((const char*)(gbase) + (voff)[_i]), (PG8_LAS unsigned*)(lds + (bufoff) + ldsw + _i * 8192), 16, 0, 0); } while (0)
; #define PG8_LDA(dst, b, h) do { _Pragma("unroll") for (int m = 0; m < 4; ++m) _Pragma("unroll") for (int k = 0; k < 2; ++k) dst[m][k] = *(const PG8_LAS bf16x8*)(lds + PG8_SA(b, h) + aoff + m * 2048 + k * 1024); } while (0)
; #define PG8_LDB(dst, b, h) do { _Pragma("unroll") for (int n = 0; n < 2; ++n) _Pragma("unroll") for (int k = 0; k < 2; ++k) dst[n][k] = *(const PG8_LAS bf16x8*)(lds + PG8_SB(b, h) + boff + n * 2048 + k * 1024); } while (0)
; #define PG8_MMA(ai, bj, At, Bt) do { __builtin_amdgcn_s_setprio(1); _Pragma("unroll") for (int m = 0; m < 4; ++m) _Pragma("unroll") for (int n = 0; n < 2; ++n) _Pragma("unroll") for (int k = 0; k < 2; ++k) \
;         acc[ai][bj][m][n] = __builtin_amdgcn_mfma_f32_16x16x32_bf16(Bt[n][k], At[m][k], acc[ai][bj][m][n], 0, 0, 0); __builtin_amdgcn_s_setprio(0); } while (0)
; #define PG8_WAIT_L(n) asm volatile("s_waitcnt lgkmcnt(" #n ")" ::: "memory")
; #define PG8_BAR __builtin_amdgcn_s_barrier()
; #define PG8_SCHED __builtin_amdgcn_sched_barrier(0)
; template <class Epi, class Sched, bool STAMP = false>
; __device__ __forceinline__ void gemm_phase(PG8_LAS unsigned char* lds, const Gemm g, const Sched& S, const Epi& E, unsigned long long* stamps) {
;     ...
;         for (int t = 0; t < nt; t += 2) {
;             const bool last = (t == nt - 2);
;             const char* a1 = cA + (size_t)(t + 1) * kstep;
;             const char* a2 = last ? nA : cA + (size_t)(t + 2) * kstep; const char* b2 = last ? nB : cB + (size_t)(t + 2) * kstep;
;             const char* a3 = a2 + kstep; const char* b3 = b2 + kstep;
;             if (last && has_next) S.a_ready(nxt);
;             PG8_LDB(B0, 0, 0); PG8_SCHED; PG8_LDA(At, 0, 0); PG8_STAGE(PG8_SA(1, 1), a1 + hstep, voffA);
;             PG8_WAIT_L(8); PG8_BAR; PG8_WAIT_L(0); PG8_MMA(0, 0, At, B0); PG8_BAR; PG8_SCHED;
;             PG8_LDB(B1, 0, 1); PG8_STAGE(PG8_SB(0, 0), b2, voffB);
;             PG8_BAR; PG8_WAIT_L(0); PG8_MMA(0, 1, At, B1); PG8_BAR;
;             PG8_LDA(At, 0, 1); PG8_STAGE(PG8_SA(0, 0), a2, voffA);
;             PG8_BAR; PG8_WAIT_L(0); PG8_MMA(1, 0, At, B0); PG8_BAR; PG8_SCHED;
.LBB0_353:
	s_add_u32 s14, s56, 0xfffc0080
	s_addc_u32 s15, s57, -1
	s_add_i32 s16, 0, 0x10000
	v_add_u32_e32 v166, s16, v167
	ds_read_b128 v[158:161], v166
	ds_read_b128 v[162:165], v166 offset:1024
	ds_read_b128 v[172:175], v166 offset:2048
	ds_read_b128 v[176:179], v166 offset:3072
	s_cmp_eq_u32 vcc_lo, 12
	s_cselect_b32 s61, s13, s15
	s_cselect_b32 s60, s47, s14
	s_cselect_b32 s59, s27, s77
	s_cselect_b32 s58, s53, s76
	v_lshl_add_u64 v[168:169], s[56:57], 0, v[154:155]
	s_add_i32 m0, s89, 0xc000
	ds_read_b128 v[180:183], v171
	ds_read_b128 v[192:195], v171 offset:1024
	ds_read_b128 v[196:199], v171 offset:2048
	ds_read_b128 v[200:203], v171 offset:3072
	ds_read_b128 v[204:207], v171 offset:4096
	ds_read_b128 v[208:211], v171 offset:5120
	ds_read_b128 v[212:215], v171 offset:6144
	ds_read_b128 v[216:219], v171 offset:7168
	global_load_lds_dwordx4 v[168:169], off
	v_lshl_add_u64 v[168:169], s[56:57], 0, v[156:157]
	s_add_i32 m0, s89, 0xe000
	s_nop 0
	global_load_lds_dwordx4 v[168:169], off
	s_waitcnt lgkmcnt(8)
	s_barrier
	s_waitcnt lgkmcnt(0)
	s_setprio 1
	s_waitcnt lgkmcnt(0)
	v_mfma_f32_16x16x32_bf16 v[124:127], v[158:161], v[180:183], v[124:127]
	v_mfma_f32_16x16x32_bf16 v[120:123], v[172:175], v[180:183], v[120:123]
	v_mfma_f32_16x16x32_bf16 v[108:111], v[158:161], v[196:199], v[108:111]
	v_mfma_f32_16x16x32_bf16 v[104:107], v[172:175], v[196:199], v[104:107]
	v_mfma_f32_16x16x32_bf16 v[92:95], v[158:161], v[204:207], v[92:95]
	v_mfma_f32_16x16x32_bf16 v[88:91], v[172:175], v[204:207], v[88:91]
	v_mfma_f32_16x16x32_bf16 v[76:79], v[158:161], v[212:215], v[76:79]
	v_mfma_f32_16x16x32_bf16 v[72:75], v[172:175], v[212:215], v[72:75]
	v_mfma_f32_16x16x32_bf16 v[124:127], v[162:165], v[192:195], v[124:127]
	v_mfma_f32_16x16x32_bf16 v[120:123], v[176:179], v[192:195], v[120:123]
	v_mfma_f32_16x16x32_bf16 v[108:111], v[162:165], v[200:203], v[108:111]
	v_mfma_f32_16x16x32_bf16 v[104:107], v[176:179], v[200:203], v[104:107]
	v_mfma_f32_16x16x32_bf16 v[92:95], v[162:165], v[208:211], v[92:95]
	v_mfma_f32_16x16x32_bf16 v[88:91], v[176:179], v[208:211], v[88:91]
	v_mfma_f32_16x16x32_bf16 v[76:79], v[162:165], v[216:219], v[76:79]
	v_mfma_f32_16x16x32_bf16 v[72:75], v[176:179], v[216:219], v[72:75]
	s_setprio 0
	s_barrier
	s_add_i32 s17, 0, 0x14000
	s_add_i32 s14, s16, s88
	v_add_u32_e32 v166, s17, v167
	v_lshl_add_u64 v[168:169], s[58:59], 0, v[128:129]
	s_mov_b32 m0, s14
	ds_read_b128 v[220:223], v166
	ds_read_b128 v[224:227], v166 offset:1024
	ds_read_b128 v[228:231], v166 offset:2048
	ds_read_b128 v[232:235], v166 offset:3072
	global_load_lds_dwordx4 v[168:169], off
	v_lshl_add_u64 v[236:237], s[58:59], 0, v[152:153]
	s_add_i32 m0, s14, 0x2000
	s_nop 0
	global_load_lds_dwordx4 v[236:237], off
	s_barrier
	s_waitcnt lgkmcnt(0)
	s_setprio 1
	s_waitcnt lgkmcnt(0)
	v_mfma_f32_16x16x32_bf16 v[116:119], v[220:223], v[180:183], v[116:119]
	v_mfma_f32_16x16x32_bf16 v[112:115], v[228:231], v[180:183], v[112:115]
	v_mfma_f32_16x16x32_bf16 v[100:103], v[220:223], v[196:199], v[100:103]
	v_mfma_f32_16x16x32_bf16 v[96:99], v[228:231], v[196:199], v[96:99]
	v_mfma_f32_16x16x32_bf16 v[84:87], v[220:223], v[204:207], v[84:87]
	v_mfma_f32_16x16x32_bf16 v[80:83], v[228:231], v[204:207], v[80:83]
	v_mfma_f32_16x16x32_bf16 v[68:71], v[220:223], v[212:215], v[68:71]
	v_mfma_f32_16x16x32_bf16 v[64:67], v[228:231], v[212:215], v[64:67]
	v_mfma_f32_16x16x32_bf16 v[116:119], v[224:227], v[192:195], v[116:119]
	v_mfma_f32_16x16x32_bf16 v[112:115], v[232:235], v[192:195], v[112:115]
	v_mfma_f32_16x16x32_bf16 v[100:103], v[224:227], v[200:203], v[100:103]
	v_mfma_f32_16x16x32_bf16 v[96:99], v[232:235], v[200:203], v[96:99]
	v_mfma_f32_16x16x32_bf16 v[84:87], v[224:227], v[208:211], v[84:87]
	v_mfma_f32_16x16x32_bf16 v[80:83], v[232:235], v[208:211], v[80:83]
	v_mfma_f32_16x16x32_bf16 v[68:71], v[224:227], v[216:219], v[68:71]
	v_mfma_f32_16x16x32_bf16 v[64:67], v[232:235], v[216:219], v[64:67]
	s_setprio 0
	s_mov_b32 m0, s89
	v_lshl_add_u64 v[238:239], s[60:61], 0, v[148:149]
	s_barrier
	ds_read_b128 v[180:183], v171 offset:16384
	ds_read_b128 v[192:195], v171 offset:17408
	ds_read_b128 v[196:199], v171 offset:18432
	ds_read_b128 v[200:203], v171 offset:19456
	ds_read_b128 v[204:207], v171 offset:20480
	ds_read_b128 v[208:211], v171 offset:21504
	ds_read_b128 v[212:215], v171 offset:22528
	ds_read_b128 v[216:219], v171 offset:23552
	global_load_lds_dwordx4 v[238:239], off
	v_lshl_add_u64 v[240:241], s[60:61], 0, v[150:151]
	s_mov_b32 m0, s96
	s_nop 0
	global_load_lds_dwordx4 v[240:241], off
	s_barrier
	s_waitcnt lgkmcnt(0)
	s_setprio 1
	s_waitcnt lgkmcnt(0)
	v_mfma_f32_16x16x32_bf16 v[60:63], v[158:161], v[180:183], v[60:63]
	v_mfma_f32_16x16x32_bf16 v[56:59], v[172:175], v[180:183], v[56:59]
	v_mfma_f32_16x16x32_bf16 v[44:47], v[158:161], v[196:199], v[44:47]
	v_mfma_f32_16x16x32_bf16 v[40:43], v[172:175], v[196:199], v[40:43]
	v_mfma_f32_16x16x32_bf16 v[28:31], v[158:161], v[204:207], v[28:31]
	v_mfma_f32_16x16x32_bf16 v[24:27], v[172:175], v[204:207], v[24:27]
	v_mfma_f32_16x16x32_bf16 v[12:15], v[158:161], v[212:215], v[12:15]
	v_mfma_f32_16x16x32_bf16 v[8:11], v[172:175], v[212:215], v[8:11]
	v_mfma_f32_16x16x32_bf16 v[60:63], v[162:165], v[192:195], v[60:63]
	v_mfma_f32_16x16x32_bf16 v[56:59], v[176:179], v[192:195], v[56:59]
	v_mfma_f32_16x16x32_bf16 v[44:47], v[162:165], v[200:203], v[44:47]
	v_mfma_f32_16x16x32_bf16 v[40:43], v[176:179], v[200:203], v[40:43]
	v_mfma_f32_16x16x32_bf16 v[28:31], v[162:165], v[208:211], v[28:31]
	v_mfma_f32_16x16x32_bf16 v[24:27], v[176:179], v[208:211], v[24:27]
	v_mfma_f32_16x16x32_bf16 v[12:15], v[162:165], v[216:219], v[12:15]
	v_mfma_f32_16x16x32_bf16 v[8:11], v[176:179], v[216:219], v[8:11]
	s_setprio 0
	s_barrier
; #define PG8_STAGE(bufoff, gbase, voff) do { _Pragma("unroll") for (int _i = 0; _i < 2; ++_i) \
;         __builtin_amdgcn_global_load_lds((const unsigned*)((const char*)(gbase) + (voff)[_i]), (PG8_LAS unsigned*)(lds + (bufoff) + ldsw + _i * 8192), 16, 0, 0); } while (0)
; #define PG8_LDA(dst, b, h) do { _Pragma("unroll") for (int m = 0; m < 4; ++m) _Pragma("unroll") for (int k = 0; k < 2; ++k) dst[m][k] = *(const PG8_LAS bf16x8*)(lds + PG8_SA(b, h) + aoff + m * 2048 + k * 1024); } while (0)
; #define PG8_LDB(dst, b, h) do { _Pragma("unroll") for (int n = 0; n < 2; ++n) _Pragma("unroll") for (int k = 0; k < 2; ++k) dst[n][k] = *(const PG8_LAS bf16x8*)(lds + PG8_SB(b, h) + boff + n * 2048 + k * 1024); } while (0)
; #define PG8_MMA(ai, bj, At, Bt) do { __builtin_amdgcn_s_setprio(1); _Pragma("unroll") for (int m = 0; m < 4; ++m) _Pragma("unroll") for (int n = 0; n < 2; ++n) _Pragma("unroll") for (int k = 0; k < 2; ++k) \
;         acc[ai][bj][m][n] = __builtin_amdgcn_mfma_f32_16x16x32_bf16(Bt[n][k], At[m][k], acc[ai][bj][m][n], 0, 0, 0); __builtin_amdgcn_s_setprio(0); } while (0)
; #define PG8_WAIT_V(n) asm volatile("s_waitcnt vmcnt(" #n ")" ::: "memory")
; #define PG8_WAIT_L(n) asm volatile("s_waitcnt lgkmcnt(" #n ")" ::: "memory")
; #define PG8_BAR __builtin_amdgcn_s_barrier()
; #define PG8_SCHED __builtin_amdgcn_sched_barrier(0)
; template <class Epi, class Sched, bool STAMP = false>
; __device__ __forceinline__ void gemm_phase(PG8_LAS unsigned char* lds, const Gemm g, const Sched& S, const Epi& E, unsigned long long* stamps) {
;     ...
;             PG8_STAGE(PG8_SB(0, 1), b2 + hstep, voffB);
;             PG8_WAIT_V(6); PG8_BAR; PG8_MMA(1, 1, At, B1); PG8_BAR;
;             PG8_LDB(B0, 1, 0); PG8_SCHED; PG8_LDA(At, 1, 0); PG8_STAGE(PG8_SA(0, 1), a2 + hstep, voffA);
;             PG8_WAIT_L(8); PG8_BAR; PG8_WAIT_L(0); PG8_MMA(0, 0, At, B0); PG8_BAR; PG8_SCHED;
;             PG8_LDB(B1, 1, 1); PG8_STAGE(PG8_SB(1, 0), b3, voffB);
;             PG8_BAR; PG8_WAIT_L(0); PG8_MMA(0, 1, At, B1); PG8_BAR;
;             PG8_LDA(At, 1, 1); PG8_STAGE(PG8_SA(1, 0), a3, voffA);
	s_add_u32 s14, s58, 0x40000
	s_addc_u32 s15, s59, 0
	s_add_i32 s16, s17, s88
	v_lshl_add_u64 v[158:159], s[14:15], 0, v[128:129]
	s_mov_b32 m0, s16
	s_nop 0
	global_load_lds_dwordx4 v[158:159], off
	v_lshl_add_u64 v[158:159], s[14:15], 0, v[152:153]
	s_add_i32 m0, s16, 0x2000
	s_nop 0
	global_load_lds_dwordx4 v[158:159], off
	s_waitcnt vmcnt(6)
	s_barrier
	s_setprio 1
	v_mfma_f32_16x16x32_bf16 v[52:55], v[220:223], v[180:183], v[52:55]
	v_mfma_f32_16x16x32_bf16 v[48:51], v[228:231], v[180:183], v[48:51]
	v_mfma_f32_16x16x32_bf16 v[36:39], v[220:223], v[196:199], v[36:39]
	v_mfma_f32_16x16x32_bf16 v[32:35], v[228:231], v[196:199], v[32:35]
	v_mfma_f32_16x16x32_bf16 v[20:23], v[220:223], v[204:207], v[20:23]
	v_mfma_f32_16x16x32_bf16 v[16:19], v[228:231], v[204:207], v[16:19]
	v_mfma_f32_16x16x32_bf16 v[4:7], v[220:223], v[212:215], v[4:7]
	v_mfma_f32_16x16x32_bf16 v[0:3], v[228:231], v[212:215], v[0:3]
	v_mfma_f32_16x16x32_bf16 v[52:55], v[224:227], v[192:195], v[52:55]
	v_mfma_f32_16x16x32_bf16 v[48:51], v[232:235], v[192:195], v[48:51]
	v_mfma_f32_16x16x32_bf16 v[36:39], v[224:227], v[200:203], v[36:39]
	v_mfma_f32_16x16x32_bf16 v[32:35], v[232:235], v[200:203], v[32:35]
	v_mfma_f32_16x16x32_bf16 v[20:23], v[224:227], v[208:211], v[20:23]
	v_mfma_f32_16x16x32_bf16 v[16:19], v[232:235], v[208:211], v[16:19]
	v_mfma_f32_16x16x32_bf16 v[4:7], v[224:227], v[216:219], v[4:7]
	v_mfma_f32_16x16x32_bf16 v[0:3], v[232:235], v[216:219], v[0:3]
	s_setprio 0
	s_add_i32 s16, 0, 0x18000
	v_add_u32_e32 v166, s16, v167
	s_barrier
	ds_read_b128 v[158:161], v166
	ds_read_b128 v[162:165], v166 offset:1024
	ds_read_b128 v[172:175], v166 offset:2048
	ds_read_b128 v[176:179], v166 offset:3072
	s_add_u32 s14, s60, 0x40000
	s_addc_u32 s15, s61, 0
	s_mov_b32 m0, s97
	v_lshl_add_u64 v[220:221], s[14:15], 0, v[148:149]
	ds_read_b128 v[180:183], v171 offset:32768
	ds_read_b128 v[192:195], v171 offset:33792
	ds_read_b128 v[196:199], v171 offset:34816
	ds_read_b128 v[200:203], v171 offset:35840
	ds_read_b128 v[204:207], v171 offset:36864
	ds_read_b128 v[208:211], v171 offset:37888
	ds_read_b128 v[212:215], v171 offset:38912
	ds_read_b128 v[216:219], v171 offset:39936
	global_load_lds_dwordx4 v[220:221], off
	v_lshl_add_u64 v[220:221], s[14:15], 0, v[150:151]
	s_mov_b32 m0, s64
	s_nop 0
	global_load_lds_dwordx4 v[220:221], off
	s_waitcnt lgkmcnt(8)
	s_barrier
	s_waitcnt lgkmcnt(0)
	s_setprio 1
	s_waitcnt lgkmcnt(0)
	v_mfma_f32_16x16x32_bf16 v[124:127], v[158:161], v[180:183], v[124:127]
	v_mfma_f32_16x16x32_bf16 v[120:123], v[172:175], v[180:183], v[120:123]
	v_mfma_f32_16x16x32_bf16 v[108:111], v[158:161], v[196:199], v[108:111]
	v_mfma_f32_16x16x32_bf16 v[104:107], v[172:175], v[196:199], v[104:107]
	v_mfma_f32_16x16x32_bf16 v[92:95], v[158:161], v[204:207], v[92:95]
	v_mfma_f32_16x16x32_bf16 v[88:91], v[172:175], v[204:207], v[88:91]
	v_mfma_f32_16x16x32_bf16 v[76:79], v[158:161], v[212:215], v[76:79]
	v_mfma_f32_16x16x32_bf16 v[72:75], v[172:175], v[212:215], v[72:75]
	v_mfma_f32_16x16x32_bf16 v[124:127], v[162:165], v[192:195], v[124:127]
	v_mfma_f32_16x16x32_bf16 v[120:123], v[176:179], v[192:195], v[120:123]
	v_mfma_f32_16x16x32_bf16 v[108:111], v[162:165], v[200:203], v[108:111]
	v_mfma_f32_16x16x32_bf16 v[104:107], v[176:179], v[200:203], v[104:107]
	v_mfma_f32_16x16x32_bf16 v[92:95], v[162:165], v[208:211], v[92:95]
	v_mfma_f32_16x16x32_bf16 v[88:91], v[176:179], v[208:211], v[88:91]
	v_mfma_f32_16x16x32_bf16 v[76:79], v[162:165], v[216:219], v[76:79]
	v_mfma_f32_16x16x32_bf16 v[72:75], v[176:179], v[216:219], v[72:75]
	s_setprio 0
	s_barrier
	s_add_i32 s17, 0, 0x1c000
	s_add_i32 s14, s16, s88
	v_add_u32_e32 v166, s17, v167
	v_lshl_add_u64 v[168:169], v[168:169], 0, s[18:19]
	s_mov_b32 m0, s14
	ds_read_b128 v[220:223], v166
	ds_read_b128 v[224:227], v166 offset:1024
	ds_read_b128 v[228:231], v166 offset:2048
	ds_read_b128 v[232:235], v166 offset:3072
	global_load_lds_dwordx4 v[168:169], off
	v_lshl_add_u64 v[168:169], v[236:237], 0, s[18:19]
	s_add_i32 m0, s14, 0x2000
	s_nop 0
	global_load_lds_dwordx4 v[168:169], off
	s_barrier
	s_waitcnt lgkmcnt(0)
	s_setprio 1
	s_waitcnt lgkmcnt(0)
	v_mfma_f32_16x16x32_bf16 v[116:119], v[220:223], v[180:183], v[116:119]
	v_mfma_f32_16x16x32_bf16 v[112:115], v[228:231], v[180:183], v[112:115]
	v_mfma_f32_16x16x32_bf16 v[100:103], v[220:223], v[196:199], v[100:103]
	v_mfma_f32_16x16x32_bf16 v[96:99], v[228:231], v[196:199], v[96:99]
	v_mfma_f32_16x16x32_bf16 v[84:87], v[220:223], v[204:207], v[84:87]
	v_mfma_f32_16x16x32_bf16 v[80:83], v[228:231], v[204:207], v[80:83]
	v_mfma_f32_16x16x32_bf16 v[68:71], v[220:223], v[212:215], v[68:71]
	v_mfma_f32_16x16x32_bf16 v[64:67], v[228:231], v[212:215], v[64:67]
	v_mfma_f32_16x16x32_bf16 v[116:119], v[224:227], v[192:195], v[116:119]
	v_mfma_f32_16x16x32_bf16 v[112:115], v[232:235], v[192:195], v[112:115]
	v_mfma_f32_16x16x32_bf16 v[100:103], v[224:227], v[200:203], v[100:103]
	v_mfma_f32_16x16x32_bf16 v[96:99], v[232:235], v[200:203], v[96:99]
	v_mfma_f32_16x16x32_bf16 v[84:87], v[224:227], v[208:211], v[84:87]
	v_mfma_f32_16x16x32_bf16 v[80:83], v[232:235], v[208:211], v[80:83]
	v_mfma_f32_16x16x32_bf16 v[68:71], v[224:227], v[216:219], v[68:71]
	v_mfma_f32_16x16x32_bf16 v[64:67], v[232:235], v[216:219], v[64:67]
	s_setprio 0
	s_mov_b32 m0, s62
	v_lshl_add_u64 v[168:169], v[238:239], 0, s[18:19]
	s_barrier
	ds_read_b128 v[180:183], v171 offset:49152
	ds_read_b128 v[192:195], v171 offset:50176
	ds_read_b128 v[196:199], v171 offset:51200
	ds_read_b128 v[200:203], v171 offset:52224
	ds_read_b128 v[204:207], v171 offset:53248
	ds_read_b128 v[208:211], v171 offset:54272
	ds_read_b128 v[212:215], v171 offset:55296
	ds_read_b128 v[216:219], v171 offset:56320
	global_load_lds_dwordx4 v[168:169], off
	v_lshl_add_u64 v[168:169], v[240:241], 0, s[18:19]
	s_mov_b32 m0, s63
	s_nop 0
	global_load_lds_dwordx4 v[168:169], off
	s_barrier
; #define PG8_STAGE(bufoff, gbase, voff) do { _Pragma("unroll") for (int _i = 0; _i < 2; ++_i) \
;         __builtin_amdgcn_global_load_lds((const unsigned*)((const char*)(gbase) + (voff)[_i]), (PG8_LAS unsigned*)(lds + (bufoff) + ldsw + _i * 8192), 16, 0, 0); } while (0)
; #define PG8_MMA(ai, bj, At, Bt) do { __builtin_amdgcn_s_setprio(1); _Pragma("unroll") for (int m = 0; m < 4; ++m) _Pragma("unroll") for (int n = 0; n < 2; ++n) _Pragma("unroll") for (int k = 0; k < 2; ++k) \
;         acc[ai][bj][m][n] = __builtin_amdgcn_mfma_f32_16x16x32_bf16(Bt[n][k], At[m][k], acc[ai][bj][m][n], 0, 0, 0); __builtin_amdgcn_s_setprio(0); } while (0)
; #define PG8_WAIT_V(n) asm volatile("s_waitcnt vmcnt(" #n ")" ::: "memory")
; #define PG8_WAIT_L(n) asm volatile("s_waitcnt lgkmcnt(" #n ")" ::: "memory")
; #define PG8_BAR __builtin_amdgcn_s_barrier()
; #define PG8_SCHED __builtin_amdgcn_sched_barrier(0)
; __device__ __forceinline__ float rstd_of(const float* rowss, int row) { return rsqrtf(rowss[row] * (1.0f / 1024.0f) + 1e-6f); }
; template <class Epi, class Sched, bool STAMP = false>
; __device__ __forceinline__ void gemm_phase(PG8_LAS unsigned char* lds, const Gemm g, const Sched& S, const Epi& E, unsigned long long* stamps) {
;     ...
;             PG8_BAR; PG8_WAIT_L(0); PG8_MMA(1, 0, At, B0); PG8_BAR; PG8_SCHED;
;             PG8_STAGE(PG8_SB(1, 1), b3 + hstep, voffB);
;             PG8_WAIT_V(6); PG8_BAR; PG8_MMA(1, 1, At, B1); PG8_BAR;
;         }
;     __device__ __forceinline__ void operator()(const f32x4 (&acc)[2][2][4][2], const pg8::Unit& u, int wr, int wc, int fr, int fq) const {
;         const int row0 = u.pm * 256 + wr * 64 + fr, col0 = u.pn * 256 + wc * 32 + 8 * fq;
; #pragma unroll
;         for (int ai = 0; ai < 2; ++ai)
; #pragma unroll
;             for (int m = 0; m < 4; ++m) {
;                 const int row = row0 + ai * 128 + m * 16;
;                 const float s = rstd_of(rowss, row);
; #pragma unroll
;                 for (int bj = 0; bj < 2; ++bj) {
;                     const size_t off = (size_t)row * 1024 + col0 + bj * 128;
;                     const u32x4 tv = *(const u32x4*)(Tm + off);
;                     u32x4 pv = (u32x4){0u, 0u, 0u, 0u};
;                     if (ACC) pv = *(const u32x4*)(M + off);
;                     const f32x4 a0 = acc[ai][bj][m][0] * s, a1 = acc[ai][bj][m][1] * s;
	s_waitcnt lgkmcnt(0)
	s_setprio 1
	s_waitcnt lgkmcnt(0)
	v_mfma_f32_16x16x32_bf16 v[60:63], v[158:161], v[180:183], v[60:63]
	v_mfma_f32_16x16x32_bf16 v[56:59], v[172:175], v[180:183], v[56:59]
	v_mfma_f32_16x16x32_bf16 v[44:47], v[158:161], v[196:199], v[44:47]
	v_mfma_f32_16x16x32_bf16 v[40:43], v[172:175], v[196:199], v[40:43]
	v_mfma_f32_16x16x32_bf16 v[28:31], v[158:161], v[204:207], v[28:31]
	v_mfma_f32_16x16x32_bf16 v[24:27], v[172:175], v[204:207], v[24:27]
	v_mfma_f32_16x16x32_bf16 v[12:15], v[158:161], v[212:215], v[12:15]
	v_mfma_f32_16x16x32_bf16 v[8:11], v[172:175], v[212:215], v[8:11]
	v_mfma_f32_16x16x32_bf16 v[60:63], v[162:165], v[192:195], v[60:63]
	v_mfma_f32_16x16x32_bf16 v[56:59], v[176:179], v[192:195], v[56:59]
	v_mfma_f32_16x16x32_bf16 v[44:47], v[162:165], v[200:203], v[44:47]
	v_mfma_f32_16x16x32_bf16 v[40:43], v[176:179], v[200:203], v[40:43]
	v_mfma_f32_16x16x32_bf16 v[28:31], v[162:165], v[208:211], v[28:31]
	v_mfma_f32_16x16x32_bf16 v[24:27], v[176:179], v[208:211], v[24:27]
	v_mfma_f32_16x16x32_bf16 v[12:15], v[162:165], v[216:219], v[12:15]
	v_mfma_f32_16x16x32_bf16 v[8:11], v[176:179], v[216:219], v[8:11]
	s_setprio 0
	s_barrier
	s_add_u32 s14, s58, 0x40080
	s_addc_u32 s15, s59, 0
	s_add_i32 s16, s17, s88
	v_lshl_add_u64 v[158:159], s[14:15], 0, v[128:129]
	s_mov_b32 m0, s16
	s_nop 0
	global_load_lds_dwordx4 v[158:159], off
	v_lshl_add_u64 v[158:159], s[14:15], 0, v[152:153]
	s_add_i32 m0, s16, 0x2000
	s_nop 0
	global_load_lds_dwordx4 v[158:159], off
	s_waitcnt vmcnt(6)
	s_barrier
	s_setprio 1
	v_mfma_f32_16x16x32_bf16 v[52:55], v[220:223], v[180:183], v[52:55]
	v_mfma_f32_16x16x32_bf16 v[48:51], v[228:231], v[180:183], v[48:51]
	v_mfma_f32_16x16x32_bf16 v[36:39], v[220:223], v[196:199], v[36:39]
	v_mfma_f32_16x16x32_bf16 v[32:35], v[228:231], v[196:199], v[32:35]
	v_mfma_f32_16x16x32_bf16 v[20:23], v[220:223], v[204:207], v[20:23]
	v_mfma_f32_16x16x32_bf16 v[16:19], v[228:231], v[204:207], v[16:19]
	v_mfma_f32_16x16x32_bf16 v[4:7], v[220:223], v[212:215], v[4:7]
	v_mfma_f32_16x16x32_bf16 v[0:3], v[228:231], v[212:215], v[0:3]
	v_mfma_f32_16x16x32_bf16 v[52:55], v[224:227], v[192:195], v[52:55]
	v_mfma_f32_16x16x32_bf16 v[48:51], v[232:235], v[192:195], v[48:51]
	v_mfma_f32_16x16x32_bf16 v[36:39], v[224:227], v[200:203], v[36:39]
	v_mfma_f32_16x16x32_bf16 v[32:35], v[232:235], v[200:203], v[32:35]
	v_mfma_f32_16x16x32_bf16 v[20:23], v[224:227], v[208:211], v[20:23]
	v_mfma_f32_16x16x32_bf16 v[16:19], v[232:235], v[208:211], v[16:19]
	v_mfma_f32_16x16x32_bf16 v[4:7], v[224:227], v[216:219], v[4:7]
	v_mfma_f32_16x16x32_bf16 v[0:3], v[232:235], v[216:219], v[0:3]
	s_setprio 0
	s_add_i32 vcc_lo, vcc_lo, 2
	s_add_u32 s56, s56, 0x100
	s_addc_u32 s57, s57, 0
	s_add_u32 s76, s76, 0x100
	s_addc_u32 s77, s77, 0
	s_cmp_gt_u32 vcc_lo, 13
	s_barrier
	s_cbranch_scc0 .LBB0_353
	v_lshl_add_u32 v164, s2, 8, v139
	v_ashrrev_i32_e32 v165, 31, v164
	v_lshl_add_u64 v[160:161], v[164:165], 2, s[40:41]
	global_load_dword v158, v[160:161], off
	v_lshl_or_b32 v162, s3, 8, v170
	v_ashrrev_i32_e32 v163, 31, v162
	s_mov_b64 s[2:3], 0x40000
	s_mov_b64 s[58:59], s[36:37]
	s_mov_b64 s[56:57], s[4:5]
	s_waitcnt vmcnt(0)
	v_fmamk_f32 v158, v158, 0x3a800000, v187
	v_cmp_gt_f32_e32 vcc, s67, v158
	v_mul_f32_e32 v159, 0x4b800000, v158
	s_nop 0
	v_cndmask_b32_e32 v158, v158, v159, vcc
	v_rsq_f32_e32 v158, v158
	s_nop 0
	v_mul_f32_e32 v159, 0x45800000, v158
	v_cndmask_b32_e32 v166, v158, v159, vcc
	v_lshlrev_b64 v[158:159], 10, v[164:165]
	v_lshl_add_u64 v[158:159], v[158:159], 0, v[162:163]
	v_lshlrev_b64 v[158:159], 1, v[158:159]
	v_lshl_add_u64 v[168:169], s[30:31], 0, v[158:159]
	v_mov_b32_e32 v249, v158
	v_mov_b32_e32 v250, v249
	global_load_dwordx4 v[192:195], v250, s[30:31]
	global_load_dwordx4 v[196:199], v250, s[0:1]
	global_load_dwordx4 v[200:203], v250, s[30:31] offset:256
	global_load_dwordx4 v[204:207], v250, s[0:1] offset:256
	v_add_u32_e32 v250, 0x8000, v249
	global_load_dwordx4 v[208:211], v250, s[30:31]
	global_load_dwordx4 v[212:215], v250, s[0:1]
	global_load_dwordx4 v[216:219], v250, s[30:31] offset:256
	global_load_dwordx4 v[220:223], v250, s[0:1] offset:256
	v_add_u32_e32 v250, 0x10000, v249
	global_load_dwordx4 v[224:227], v250, s[30:31]
	global_load_dwordx4 v[228:231], v250, s[0:1]
	global_load_dwordx4 v[232:235], v250, s[30:31] offset:256
	global_load_dwordx4 v[236:239], v250, s[0:1] offset:256
	global_load_dword v240, v[160:161], off offset:64
	global_load_dword v241, v[160:161], off offset:128
	global_load_dword v244, v[160:161], off offset:192
	global_load_dword v245, v[160:161], off offset:512
	global_load_dword v246, v[160:161], off offset:576
	global_load_dword v247, v[160:161], off offset:640
	global_load_dword v248, v[160:161], off offset:704
	v_lshl_add_u64 v[168:169], s[0:1], 0, v[158:159]
	v_pk_mul_f32 v[126:127], v[126:127], v[166:167] op_sel_hi:[1,0]
	v_pk_mul_f32 v[120:121], v[120:121], v[166:167] op_sel_hi:[1,0]
	v_mul_f32_e32 v126, 0xbfb8aa3b, v126
	v_mul_f32_e32 v127, 0xbfb8aa3b, v127
	v_pk_mul_f32 v[124:125], v[124:125], v[166:167] op_sel_hi:[1,0]
	v_pk_mul_f32 v[122:123], v[122:123], v[166:167] op_sel_hi:[1,0]
	v_exp_f32_e32 v126, v126
	v_exp_f32_e32 v127, v127
	v_mul_f32_e32 v120, 0xbfb8aa3b, v120
	v_mul_f32_e32 v121, 0xbfb8aa3b, v121
	v_mul_f32_e32 v124, 0xbfb8aa3b, v124
	v_mul_f32_e32 v125, 0xbfb8aa3b, v125
	v_exp_f32_e32 v120, v120
	v_exp_f32_e32 v121, v121
	v_mul_f32_e32 v122, 0xbfb8aa3b, v122
	v_mul_f32_e32 v123, 0xbfb8aa3b, v123
	v_exp_f32_e32 v124, v124
	v_exp_f32_e32 v125, v125
	v_exp_f32_e32 v122, v122
	v_exp_f32_e32 v123, v123
	v_add_f32_e32 v126, 1.0, v126
	v_add_f32_e32 v127, 1.0, v127
	v_rcp_f32_e32 v126, v126
	v_rcp_f32_e32 v127, v127
	v_add_f32_e32 v120, 1.0, v120
	v_add_f32_e32 v121, 1.0, v121
	v_add_f32_e32 v124, 1.0, v124
	v_add_f32_e32 v125, 1.0, v125
	v_rcp_f32_e32 v120, v120
	v_rcp_f32_e32 v121, v121
	v_add_f32_e32 v122, 1.0, v122
	v_add_f32_e32 v123, 1.0, v123
	v_rcp_f32_e32 v124, v124
	v_rcp_f32_e32 v125, v125
	v_rcp_f32_e32 v122, v122
	v_rcp_f32_e32 v123, v123
	v_pk_mul_f32 v[116:117], v[116:117], v[166:167] op_sel_hi:[1,0]
	v_pk_mul_f32 v[114:115], v[114:115], v[166:167] op_sel_hi:[1,0]
	s_waitcnt vmcnt(0)
; __device__ __forceinline__ unsigned cvt_pk_bf16(float lo, float hi) { const f32x2_cv v = {lo, hi}; const bf16x2_cv b = __builtin_convertvector(v, bf16x2_cv); return __builtin_bit_cast(unsigned, b); }
; __device__ __forceinline__ float sigm(float x) { return __builtin_amdgcn_rcpf(1.0f + __expf(-x)); }
; __device__ __forceinline__ float lo16(unsigned w) { return __uint_as_float(w << 16); }
; __device__ __forceinline__ float hi16(unsigned w) { return __uint_as_float(w & 0xffff0000u); }
; __device__ __forceinline__ float rstd_of(const float* rowss, int row) { return rsqrtf(rowss[row] * (1.0f / 1024.0f) + 1e-6f); }
;     __device__ __forceinline__ void operator()(const f32x4 (&acc)[2][2][4][2], const pg8::Unit& u, int wr, int wc, int fr, int fq) const {
;     ...
;                 const float s = rstd_of(rowss, row);
; #pragma unroll
;                 for (int bj = 0; bj < 2; ++bj) {
;                     const size_t off = (size_t)row * 1024 + col0 + bj * 128;
;                     const u32x4 tv = *(const u32x4*)(Tm + off);
;                     u32x4 pv = (u32x4){0u, 0u, 0u, 0u};
;                     if (ACC) pv = *(const u32x4*)(M + off);
;                     const f32x4 a0 = acc[ai][bj][m][0] * s, a1 = acc[ai][bj][m][1] * s;
;                     float o[8];
;                     o[0] = sigm(a0[0]) * lo16(tv.x); o[1] = sigm(a0[1]) * hi16(tv.x); o[2] = sigm(a0[2]) * lo16(tv.y); o[3] = sigm(a0[3]) * hi16(tv.y);
;                     o[4] = sigm(a1[0]) * lo16(tv.z); o[5] = sigm(a1[1]) * hi16(tv.z); o[6] = sigm(a1[2]) * lo16(tv.w); o[7] = sigm(a1[3]) * hi16(tv.w);
;                     if (ACC) { o[0] += lo16(pv.x); o[1] += hi16(pv.x); o[2] += lo16(pv.y); o[3] += hi16(pv.y); o[4] += lo16(pv.z); o[5] += hi16(pv.z); o[6] += lo16(pv.w); o[7] += hi16(pv.w); }
;                     u32x4 w; w.x = cvt_pk_bf16(o[0], o[1]); w.y = cvt_pk_bf16(o[2], o[3]); w.z = cvt_pk_bf16(o[4], o[5]); w.w = cvt_pk_bf16(o[6], o[7]);
;                     *(u32x4*)(M + off) = w; } }
	v_mov_b32_e32 v172, v192
	v_mov_b32_e32 v173, v193
	v_mov_b32_e32 v174, v194
	v_mov_b32_e32 v175, v195
	v_mov_b32_e32 v176, v196
	v_mov_b32_e32 v177, v197
	v_mov_b32_e32 v178, v198
	v_mov_b32_e32 v179, v199
	v_lshlrev_b32_e32 v180, 16, v172
	v_and_b32_e32 v181, 0xffff0000, v172
	v_lshlrev_b32_e32 v182, 16, v176
	v_and_b32_e32 v183, 0xffff0000, v176
	v_lshlrev_b32_e32 v172, 16, v173
	v_and_b32_e32 v173, 0xffff0000, v173
	v_lshlrev_b32_e32 v176, 16, v177
	v_and_b32_e32 v177, 0xffff0000, v177
	v_pk_fma_f32 v[126:127], v[126:127], v[172:173], v[176:177]
	v_lshlrev_b32_e32 v172, 16, v174
	v_and_b32_e32 v173, 0xffff0000, v174
	v_lshlrev_b32_e32 v176, 16, v178
	v_and_b32_e32 v177, 0xffff0000, v178
	v_pk_fma_f32 v[172:173], v[120:121], v[172:173], v[176:177]
	v_lshlrev_b32_e32 v120, 16, v175
	v_and_b32_e32 v121, 0xffff0000, v175
	v_lshlrev_b32_e32 v174, 16, v179
	v_and_b32_e32 v175, 0xffff0000, v179
	v_pk_fma_f32 v[124:125], v[124:125], v[180:181], v[182:183]
	v_pk_fma_f32 v[174:175], v[122:123], v[120:121], v[174:175]
	v_cvt_pk_bf16_f32 v120, v124, v125
	v_cvt_pk_bf16_f32 v121, v126, v127
	v_cvt_pk_bf16_f32 v122, v172, v173
	v_cvt_pk_bf16_f32 v123, v174, v175
	v_or_b32_e32 v124, 0x100, v158
	v_mov_b32_e32 v125, v159
	global_store_dwordx4 v[168:169], v[120:123], off
	v_lshl_add_u64 v[168:169], s[0:1], 0, v[124:125]
	v_pk_mul_f32 v[172:173], v[118:119], v[166:167] op_sel_hi:[1,0]
	v_lshl_add_u64 v[120:121], s[30:31], 0, v[124:125]
	s_nop 1
	v_mov_b32_e32 v120, v200
	v_mov_b32_e32 v121, v201
	v_mov_b32_e32 v122, v202
	v_mov_b32_e32 v123, v203
	v_pk_mul_f32 v[118:119], v[112:113], v[166:167] op_sel_hi:[1,0]
	s_nop 1
	v_mov_b32_e32 v124, v204
	v_mov_b32_e32 v125, v205
	v_mov_b32_e32 v126, v206
	v_mov_b32_e32 v127, v207
	v_add_u32_e32 v250, 0x18000, v249
	global_load_dwordx4 v[192:195], v250, s[30:31]
	global_load_dwordx4 v[196:199], v250, s[0:1]
	global_load_dwordx4 v[200:203], v250, s[30:31] offset:256
	global_load_dwordx4 v[204:207], v250, s[0:1] offset:256
	v_mul_f32_e32 v112, 0xbfb8aa3b, v116
	v_mul_f32_e32 v113, 0xbfb8aa3b, v117
	v_mul_f32_e32 v116, 0xbfb8aa3b, v172
	v_mul_f32_e32 v117, 0xbfb8aa3b, v173
	v_exp_f32_e32 v116, v116
	v_exp_f32_e32 v117, v117
	v_mul_f32_e32 v118, 0xbfb8aa3b, v118
	v_mul_f32_e32 v119, 0xbfb8aa3b, v119
	v_exp_f32_e32 v118, v118
	v_exp_f32_e32 v119, v119
	v_mul_f32_e32 v114, 0xbfb8aa3b, v114
	v_mul_f32_e32 v115, 0xbfb8aa3b, v115
	v_exp_f32_e32 v112, v112
	v_exp_f32_e32 v113, v113
	v_exp_f32_e32 v114, v114
	v_exp_f32_e32 v115, v115
	v_add_f32_e32 v116, 1.0, v116
	v_add_f32_e32 v117, 1.0, v117
	v_rcp_f32_e32 v116, v116
	v_rcp_f32_e32 v117, v117
	v_add_f32_e32 v118, 1.0, v118
	v_add_f32_e32 v119, 1.0, v119
	v_add_f32_e32 v112, 1.0, v112
	v_add_f32_e32 v113, 1.0, v113
	v_rcp_f32_e32 v118, v118
	v_rcp_f32_e32 v119, v119
	v_add_f32_e32 v114, 1.0, v114
	v_add_f32_e32 v115, 1.0, v115
	v_rcp_f32_e32 v112, v112
	v_rcp_f32_e32 v113, v113
	v_rcp_f32_e32 v114, v114
	v_rcp_f32_e32 v115, v115
	v_lshlrev_b32_e32 v172, 16, v120
	v_and_b32_e32 v173, 0xffff0000, v120
	v_lshlrev_b32_e32 v174, 16, v124
	v_and_b32_e32 v175, 0xffff0000, v124
	v_lshlrev_b32_e32 v120, 16, v121
	v_and_b32_e32 v121, 0xffff0000, v121
	v_lshlrev_b32_e32 v124, 16, v125
	v_and_b32_e32 v125, 0xffff0000, v125
	v_pk_fma_f32 v[116:117], v[116:117], v[120:121], v[124:125]
	v_lshlrev_b32_e32 v120, 16, v122
	v_and_b32_e32 v121, 0xffff0000, v122
	v_lshlrev_b32_e32 v124, 16, v126
	v_and_b32_e32 v125, 0xffff0000, v126
	v_pk_fma_f32 v[118:119], v[118:119], v[120:121], v[124:125]
	v_lshlrev_b32_e32 v120, 16, v123
	v_and_b32_e32 v121, 0xffff0000, v123
	v_lshlrev_b32_e32 v122, 16, v127
	v_and_b32_e32 v123, 0xffff0000, v127
	v_pk_fma_f32 v[112:113], v[112:113], v[172:173], v[174:175]
	v_pk_fma_f32 v[120:121], v[114:115], v[120:121], v[122:123]
	v_cvt_pk_bf16_f32 v112, v112, v113
	v_cvt_pk_bf16_f32 v113, v116, v117
	v_cvt_pk_bf16_f32 v114, v118, v119
	v_cvt_pk_bf16_f32 v115, v120, v121
	global_store_dwordx4 v[168:169], v[112:115], off
	s_nop 1
	v_mov_b32_e32 v112, v240
	s_nop 0
	v_or_b32_e32 v114, 16, v164
	v_ashrrev_i32_e32 v115, 31, v114
	v_lshlrev_b64 v[114:115], 10, v[114:115]
	v_lshl_add_u64 v[114:115], v[114:115], 0, v[162:163]
	v_lshlrev_b64 v[114:115], 1, v[114:115]
	v_lshl_add_u64 v[116:117], s[30:31], 0, v[114:115]
	v_lshl_add_u64 v[124:125], s[0:1], 0, v[114:115]
	s_nop 1
	v_mov_b32_e32 v116, v208
	v_mov_b32_e32 v117, v209
	v_mov_b32_e32 v118, v210
	v_mov_b32_e32 v119, v211
	v_or_b32_e32 v114, 0x100, v114
	s_nop 1
	v_mov_b32_e32 v120, v212
	v_mov_b32_e32 v121, v213
	v_mov_b32_e32 v122, v214
	v_mov_b32_e32 v123, v215
	v_fmamk_f32 v112, v112, 0x3a800000, v187
	v_cmp_gt_f32_e32 vcc, s67, v112
	v_mul_f32_e32 v113, 0x4b800000, v112
	v_lshlrev_b32_e32 v126, 16, v116
	v_cndmask_b32_e32 v112, v112, v113, vcc
	v_rsq_f32_e32 v112, v112
	v_and_b32_e32 v127, 0xffff0000, v116
	v_lshlrev_b32_e32 v168, 16, v120
	v_and_b32_e32 v169, 0xffff0000, v120
	v_mul_f32_e32 v113, 0x45800000, v112
	v_cndmask_b32_e32 v112, v112, v113, vcc
	v_pk_mul_f32 v[110:111], v[110:111], v[112:113] op_sel_hi:[1,0]
	v_pk_mul_f32 v[104:105], v[104:105], v[112:113] op_sel_hi:[1,0]
	v_mul_f32_e32 v110, 0xbfb8aa3b, v110
	v_mul_f32_e32 v111, 0xbfb8aa3b, v111
	v_pk_mul_f32 v[108:109], v[108:109], v[112:113] op_sel_hi:[1,0]
	v_pk_mul_f32 v[106:107], v[106:107], v[112:113] op_sel_hi:[1,0]
	v_exp_f32_e32 v110, v110
	v_exp_f32_e32 v111, v111
	v_mul_f32_e32 v104, 0xbfb8aa3b, v104
	v_mul_f32_e32 v105, 0xbfb8aa3b, v105
	v_mul_f32_e32 v108, 0xbfb8aa3b, v108
	v_mul_f32_e32 v109, 0xbfb8aa3b, v109
	v_exp_f32_e32 v104, v104
	v_exp_f32_e32 v105, v105
	v_mul_f32_e32 v106, 0xbfb8aa3b, v106
	v_mul_f32_e32 v107, 0xbfb8aa3b, v107
; __device__ __forceinline__ unsigned cvt_pk_bf16(float lo, float hi) { const f32x2_cv v = {lo, hi}; const bf16x2_cv b = __builtin_convertvector(v, bf16x2_cv); return __builtin_bit_cast(unsigned, b); }
; __device__ __forceinline__ float sigm(float x) { return __builtin_amdgcn_rcpf(1.0f + __expf(-x)); }
; __device__ __forceinline__ float lo16(unsigned w) { return __uint_as_float(w << 16); }
; __device__ __forceinline__ float hi16(unsigned w) { return __uint_as_float(w & 0xffff0000u); }
; __device__ __forceinline__ float rstd_of(const float* rowss, int row) { return rsqrtf(rowss[row] * (1.0f / 1024.0f) + 1e-6f); }
;     __device__ __forceinline__ void operator()(const f32x4 (&acc)[2][2][4][2], const pg8::Unit& u, int wr, int wc, int fr, int fq) const {
;     ...
;                 const float s = rstd_of(rowss, row);
; #pragma unroll
;                 for (int bj = 0; bj < 2; ++bj) {
;                     const size_t off = (size_t)row * 1024 + col0 + bj * 128;
;                     const u32x4 tv = *(const u32x4*)(Tm + off);
;                     u32x4 pv = (u32x4){0u, 0u, 0u, 0u};
;                     if (ACC) pv = *(const u32x4*)(M + off);
;                     const f32x4 a0 = acc[ai][bj][m][0] * s, a1 = acc[ai][bj][m][1] * s;
;                     float o[8];
;                     o[0] = sigm(a0[0]) * lo16(tv.x); o[1] = sigm(a0[1]) * hi16(tv.x); o[2] = sigm(a0[2]) * lo16(tv.y); o[3] = sigm(a0[3]) * hi16(tv.y);
;                     o[4] = sigm(a1[0]) * lo16(tv.z); o[5] = sigm(a1[1]) * hi16(tv.z); o[6] = sigm(a1[2]) * lo16(tv.w); o[7] = sigm(a1[3]) * hi16(tv.w);
;                     if (ACC) { o[0] += lo16(pv.x); o[1] += hi16(pv.x); o[2] += lo16(pv.y); o[3] += hi16(pv.y); o[4] += lo16(pv.z); o[5] += hi16(pv.z); o[6] += lo16(pv.w); o[7] += hi16(pv.w); }
;                     u32x4 w; w.x = cvt_pk_bf16(o[0], o[1]); w.y = cvt_pk_bf16(o[2], o[3]); w.z = cvt_pk_bf16(o[4], o[5]); w.w = cvt_pk_bf16(o[6], o[7]);
;                     *(u32x4*)(M + off) = w; } }
	v_exp_f32_e32 v108, v108
	v_exp_f32_e32 v109, v109
	v_exp_f32_e32 v106, v106
	v_exp_f32_e32 v107, v107
	v_add_f32_e32 v110, 1.0, v110
	v_add_f32_e32 v111, 1.0, v111
	v_rcp_f32_e32 v110, v110
	v_rcp_f32_e32 v111, v111
	v_add_f32_e32 v104, 1.0, v104
	v_add_f32_e32 v105, 1.0, v105
	v_add_f32_e32 v108, 1.0, v108
	v_add_f32_e32 v109, 1.0, v109
	v_rcp_f32_e32 v104, v104
	v_rcp_f32_e32 v105, v105
	v_add_f32_e32 v106, 1.0, v106
	v_add_f32_e32 v107, 1.0, v107
	v_rcp_f32_e32 v108, v108
	v_rcp_f32_e32 v109, v109
	v_rcp_f32_e32 v106, v106
	v_rcp_f32_e32 v107, v107
	v_lshlrev_b32_e32 v116, 16, v117
	v_and_b32_e32 v117, 0xffff0000, v117
	v_lshlrev_b32_e32 v120, 16, v121
	v_and_b32_e32 v121, 0xffff0000, v121
	v_pk_fma_f32 v[110:111], v[110:111], v[116:117], v[120:121]
	v_lshlrev_b32_e32 v116, 16, v118
	v_and_b32_e32 v117, 0xffff0000, v118
	v_lshlrev_b32_e32 v120, 16, v122
	v_and_b32_e32 v121, 0xffff0000, v122
	v_pk_fma_f32 v[116:117], v[104:105], v[116:117], v[120:121]
	v_lshlrev_b32_e32 v104, 16, v119
	v_and_b32_e32 v105, 0xffff0000, v119
	v_lshlrev_b32_e32 v118, 16, v123
	v_and_b32_e32 v119, 0xffff0000, v123
	v_pk_fma_f32 v[108:109], v[108:109], v[126:127], v[168:169]
	v_pk_fma_f32 v[118:119], v[106:107], v[104:105], v[118:119]
	v_cvt_pk_bf16_f32 v104, v108, v109
	v_cvt_pk_bf16_f32 v105, v110, v111
	v_cvt_pk_bf16_f32 v106, v116, v117
	v_cvt_pk_bf16_f32 v107, v118, v119
	global_store_dwordx4 v[124:125], v[104:107], off
	v_pk_mul_f32 v[102:103], v[102:103], v[112:113] op_sel_hi:[1,0]
	v_pk_mul_f32 v[96:97], v[96:97], v[112:113] op_sel_hi:[1,0]
	v_lshl_add_u64 v[104:105], s[30:31], 0, v[114:115]
	v_lshl_add_u64 v[114:115], s[0:1], 0, v[114:115]
	s_nop 1
	v_mov_b32_e32 v104, v216
	v_mov_b32_e32 v105, v217
	v_mov_b32_e32 v106, v218
	v_mov_b32_e32 v107, v219
	v_mul_f32_e32 v102, 0xbfb8aa3b, v102
	s_nop 1
	v_mov_b32_e32 v108, v220
	v_mov_b32_e32 v109, v221
	v_mov_b32_e32 v110, v222
	v_mov_b32_e32 v111, v223
	v_add_u32_e32 v250, 0x40000, v249
	global_load_dwordx4 v[208:211], v250, s[30:31]
	global_load_dwordx4 v[212:215], v250, s[0:1]
	global_load_dwordx4 v[216:219], v250, s[30:31] offset:256
	global_load_dwordx4 v[220:223], v250, s[0:1] offset:256
	v_mul_f32_e32 v103, 0xbfb8aa3b, v103
	v_pk_mul_f32 v[100:101], v[100:101], v[112:113] op_sel_hi:[1,0]
	v_pk_mul_f32 v[98:99], v[98:99], v[112:113] op_sel_hi:[1,0]
	v_exp_f32_e32 v102, v102
	v_exp_f32_e32 v103, v103
	v_mul_f32_e32 v96, 0xbfb8aa3b, v96
	v_mul_f32_e32 v97, 0xbfb8aa3b, v97
	v_mul_f32_e32 v100, 0xbfb8aa3b, v100
	v_mul_f32_e32 v101, 0xbfb8aa3b, v101
	v_exp_f32_e32 v96, v96
	v_exp_f32_e32 v97, v97
	v_mul_f32_e32 v98, 0xbfb8aa3b, v98
	v_mul_f32_e32 v99, 0xbfb8aa3b, v99
	v_exp_f32_e32 v100, v100
	v_exp_f32_e32 v101, v101
	v_exp_f32_e32 v98, v98
	v_exp_f32_e32 v99, v99
	v_add_f32_e32 v102, 1.0, v102
	v_add_f32_e32 v103, 1.0, v103
	v_rcp_f32_e32 v102, v102
	v_rcp_f32_e32 v103, v103
	v_add_f32_e32 v96, 1.0, v96
	v_add_f32_e32 v97, 1.0, v97
	v_add_f32_e32 v100, 1.0, v100
	v_add_f32_e32 v101, 1.0, v101
	v_rcp_f32_e32 v96, v96
	v_rcp_f32_e32 v97, v97
	v_add_f32_e32 v98, 1.0, v98
	v_add_f32_e32 v99, 1.0, v99
	v_rcp_f32_e32 v100, v100
	v_rcp_f32_e32 v101, v101
	v_rcp_f32_e32 v98, v98
	v_rcp_f32_e32 v99, v99
	v_lshlrev_b32_e32 v112, 16, v104
	v_and_b32_e32 v113, 0xffff0000, v104
	v_lshlrev_b32_e32 v116, 16, v108
	v_and_b32_e32 v117, 0xffff0000, v108
	v_lshlrev_b32_e32 v104, 16, v105
	v_and_b32_e32 v105, 0xffff0000, v105
	v_lshlrev_b32_e32 v108, 16, v109
	v_and_b32_e32 v109, 0xffff0000, v109
	v_pk_fma_f32 v[102:103], v[102:103], v[104:105], v[108:109]
	v_lshlrev_b32_e32 v104, 16, v106
	v_and_b32_e32 v105, 0xffff0000, v106
	v_lshlrev_b32_e32 v108, 16, v110
	v_and_b32_e32 v109, 0xffff0000, v110
	v_pk_fma_f32 v[104:105], v[96:97], v[104:105], v[108:109]
	v_lshlrev_b32_e32 v96, 16, v107
	v_and_b32_e32 v97, 0xffff0000, v107
	v_lshlrev_b32_e32 v106, 16, v111
	v_and_b32_e32 v107, 0xffff0000, v111
	v_pk_fma_f32 v[100:101], v[100:101], v[112:113], v[116:117]
	v_pk_fma_f32 v[106:107], v[98:99], v[96:97], v[106:107]
	v_cvt_pk_bf16_f32 v96, v100, v101
	v_cvt_pk_bf16_f32 v97, v102, v103
	v_cvt_pk_bf16_f32 v98, v104, v105
	v_cvt_pk_bf16_f32 v99, v106, v107
	global_store_dwordx4 v[114:115], v[96:99], off
	s_nop 1
	v_mov_b32_e32 v96, v241
	s_nop 0
	v_or_b32_e32 v98, 32, v164
	v_ashrrev_i32_e32 v99, 31, v98
	v_lshlrev_b64 v[98:99], 10, v[98:99]
	v_lshl_add_u64 v[98:99], v[98:99], 0, v[162:163]
	v_lshlrev_b64 v[98:99], 1, v[98:99]
	v_lshl_add_u64 v[100:101], s[30:31], 0, v[98:99]
	v_lshl_add_u64 v[108:109], s[0:1], 0, v[98:99]
	s_nop 1
	v_mov_b32_e32 v100, v224
	v_mov_b32_e32 v101, v225
	v_mov_b32_e32 v102, v226
	v_mov_b32_e32 v103, v227
	v_or_b32_e32 v98, 0x100, v98
	s_nop 1
	v_mov_b32_e32 v104, v228
	v_mov_b32_e32 v105, v229
	v_mov_b32_e32 v106, v230
	v_mov_b32_e32 v107, v231
	v_fmamk_f32 v96, v96, 0x3a800000, v187
	v_cmp_gt_f32_e32 vcc, s67, v96
	v_mul_f32_e32 v97, 0x4b800000, v96
	v_lshlrev_b32_e32 v110, 16, v100
	v_cndmask_b32_e32 v96, v96, v97, vcc
	v_rsq_f32_e32 v96, v96
	v_and_b32_e32 v111, 0xffff0000, v100
	v_lshlrev_b32_e32 v112, 16, v104
	v_and_b32_e32 v113, 0xffff0000, v104
	v_mul_f32_e32 v97, 0x45800000, v96
	v_cndmask_b32_e32 v96, v96, v97, vcc
	v_pk_mul_f32 v[94:95], v[94:95], v[96:97] op_sel_hi:[1,0]
	v_pk_mul_f32 v[88:89], v[88:89], v[96:97] op_sel_hi:[1,0]
	v_mul_f32_e32 v94, 0xbfb8aa3b, v94
	v_mul_f32_e32 v95, 0xbfb8aa3b, v95
	v_pk_mul_f32 v[92:93], v[92:93], v[96:97] op_sel_hi:[1,0]
	v_pk_mul_f32 v[90:91], v[90:91], v[96:97] op_sel_hi:[1,0]
	v_exp_f32_e32 v94, v94
	v_exp_f32_e32 v95, v95
	v_mul_f32_e32 v88, 0xbfb8aa3b, v88
	v_mul_f32_e32 v89, 0xbfb8aa3b, v89
	v_mul_f32_e32 v92, 0xbfb8aa3b, v92
; __device__ __forceinline__ unsigned cvt_pk_bf16(float lo, float hi) { const f32x2_cv v = {lo, hi}; const bf16x2_cv b = __builtin_convertvector(v, bf16x2_cv); return __builtin_bit_cast(unsigned, b); }
; __device__ __forceinline__ float sigm(float x) { return __builtin_amdgcn_rcpf(1.0f + __expf(-x)); }
; __device__ __forceinline__ float lo16(unsigned w) { return __uint_as_float(w << 16); }
; __device__ __forceinline__ float hi16(unsigned w) { return __uint_as_float(w & 0xffff0000u); }
; __device__ __forceinline__ float rstd_of(const float* rowss, int row) { return rsqrtf(rowss[row] * (1.0f / 1024.0f) + 1e-6f); }
;     __device__ __forceinline__ void operator()(const f32x4 (&acc)[2][2][4][2], const pg8::Unit& u, int wr, int wc, int fr, int fq) const {
;     ...
;                 const float s = rstd_of(rowss, row);
; #pragma unroll
;                 for (int bj = 0; bj < 2; ++bj) {
;                     const size_t off = (size_t)row * 1024 + col0 + bj * 128;
;                     const u32x4 tv = *(const u32x4*)(Tm + off);
;                     u32x4 pv = (u32x4){0u, 0u, 0u, 0u};
;                     if (ACC) pv = *(const u32x4*)(M + off);
;                     const f32x4 a0 = acc[ai][bj][m][0] * s, a1 = acc[ai][bj][m][1] * s;
;                     float o[8];
;                     o[0] = sigm(a0[0]) * lo16(tv.x); o[1] = sigm(a0[1]) * hi16(tv.x); o[2] = sigm(a0[2]) * lo16(tv.y); o[3] = sigm(a0[3]) * hi16(tv.y);
;                     o[4] = sigm(a1[0]) * lo16(tv.z); o[5] = sigm(a1[1]) * hi16(tv.z); o[6] = sigm(a1[2]) * lo16(tv.w); o[7] = sigm(a1[3]) * hi16(tv.w);
;                     if (ACC) { o[0] += lo16(pv.x); o[1] += hi16(pv.x); o[2] += lo16(pv.y); o[3] += hi16(pv.y); o[4] += lo16(pv.z); o[5] += hi16(pv.z); o[6] += lo16(pv.w); o[7] += hi16(pv.w); }
;                     u32x4 w; w.x = cvt_pk_bf16(o[0], o[1]); w.y = cvt_pk_bf16(o[2], o[3]); w.z = cvt_pk_bf16(o[4], o[5]); w.w = cvt_pk_bf16(o[6], o[7]);
;                     *(u32x4*)(M + off) = w; } }
	v_mul_f32_e32 v93, 0xbfb8aa3b, v93
	v_exp_f32_e32 v88, v88
	v_exp_f32_e32 v89, v89
	v_mul_f32_e32 v90, 0xbfb8aa3b, v90
	v_mul_f32_e32 v91, 0xbfb8aa3b, v91
	v_exp_f32_e32 v92, v92
	v_exp_f32_e32 v93, v93
	v_exp_f32_e32 v90, v90
	v_exp_f32_e32 v91, v91
	v_add_f32_e32 v94, 1.0, v94
	v_add_f32_e32 v95, 1.0, v95
	v_rcp_f32_e32 v94, v94
	v_rcp_f32_e32 v95, v95
	v_add_f32_e32 v88, 1.0, v88
	v_add_f32_e32 v89, 1.0, v89
	v_add_f32_e32 v92, 1.0, v92
	v_add_f32_e32 v93, 1.0, v93
	v_rcp_f32_e32 v88, v88
	v_rcp_f32_e32 v89, v89
	v_add_f32_e32 v90, 1.0, v90
	v_add_f32_e32 v91, 1.0, v91
	v_rcp_f32_e32 v92, v92
	v_rcp_f32_e32 v93, v93
	v_rcp_f32_e32 v90, v90
	v_rcp_f32_e32 v91, v91
	v_lshlrev_b32_e32 v100, 16, v101
	v_and_b32_e32 v101, 0xffff0000, v101
	v_lshlrev_b32_e32 v104, 16, v105
	v_and_b32_e32 v105, 0xffff0000, v105
	v_pk_fma_f32 v[94:95], v[94:95], v[100:101], v[104:105]
	v_lshlrev_b32_e32 v100, 16, v102
	v_and_b32_e32 v101, 0xffff0000, v102
	v_lshlrev_b32_e32 v104, 16, v106
	v_and_b32_e32 v105, 0xffff0000, v106
	v_pk_fma_f32 v[100:101], v[88:89], v[100:101], v[104:105]
	v_lshlrev_b32_e32 v88, 16, v103
	v_and_b32_e32 v89, 0xffff0000, v103
	v_lshlrev_b32_e32 v102, 16, v107
	v_and_b32_e32 v103, 0xffff0000, v107
	v_pk_fma_f32 v[92:93], v[92:93], v[110:111], v[112:113]
	v_pk_fma_f32 v[102:103], v[90:91], v[88:89], v[102:103]
	v_cvt_pk_bf16_f32 v88, v92, v93
	v_cvt_pk_bf16_f32 v89, v94, v95
	v_cvt_pk_bf16_f32 v90, v100, v101
	v_cvt_pk_bf16_f32 v91, v102, v103
	global_store_dwordx4 v[108:109], v[88:91], off
	v_pk_mul_f32 v[86:87], v[86:87], v[96:97] op_sel_hi:[1,0]
	v_pk_mul_f32 v[80:81], v[80:81], v[96:97] op_sel_hi:[1,0]
	v_lshl_add_u64 v[88:89], s[30:31], 0, v[98:99]
	v_lshl_add_u64 v[98:99], s[0:1], 0, v[98:99]
	s_nop 1
	v_mov_b32_e32 v92, v232
	v_mov_b32_e32 v93, v233
	v_mov_b32_e32 v94, v234
	v_mov_b32_e32 v95, v235
	v_mul_f32_e32 v86, 0xbfb8aa3b, v86
	s_nop 1
	v_mov_b32_e32 v88, v236
	v_mov_b32_e32 v89, v237
	v_mov_b32_e32 v90, v238
	v_mov_b32_e32 v91, v239
	v_add_u32_e32 v250, 0x48000, v249
	global_load_dwordx4 v[224:227], v250, s[30:31]
	global_load_dwordx4 v[228:231], v250, s[0:1]
	global_load_dwordx4 v[232:235], v250, s[30:31] offset:256
	global_load_dwordx4 v[236:239], v250, s[0:1] offset:256
	v_mul_f32_e32 v87, 0xbfb8aa3b, v87
	v_pk_mul_f32 v[84:85], v[84:85], v[96:97] op_sel_hi:[1,0]
	v_pk_mul_f32 v[82:83], v[82:83], v[96:97] op_sel_hi:[1,0]
	v_exp_f32_e32 v86, v86
	v_exp_f32_e32 v87, v87
	v_mul_f32_e32 v80, 0xbfb8aa3b, v80
	v_mul_f32_e32 v81, 0xbfb8aa3b, v81
	v_mul_f32_e32 v84, 0xbfb8aa3b, v84
	v_mul_f32_e32 v85, 0xbfb8aa3b, v85
	v_exp_f32_e32 v80, v80
	v_exp_f32_e32 v81, v81
	v_mul_f32_e32 v82, 0xbfb8aa3b, v82
	v_mul_f32_e32 v83, 0xbfb8aa3b, v83
	v_exp_f32_e32 v84, v84
	v_exp_f32_e32 v85, v85
	v_exp_f32_e32 v82, v82
	v_exp_f32_e32 v83, v83
	v_add_f32_e32 v86, 1.0, v86
	v_add_f32_e32 v87, 1.0, v87
	v_rcp_f32_e32 v86, v86
	v_rcp_f32_e32 v87, v87
	v_add_f32_e32 v80, 1.0, v80
	v_add_f32_e32 v81, 1.0, v81
	v_add_f32_e32 v84, 1.0, v84
	v_add_f32_e32 v85, 1.0, v85
	v_rcp_f32_e32 v80, v80
	v_rcp_f32_e32 v81, v81
	v_add_f32_e32 v82, 1.0, v82
	v_add_f32_e32 v83, 1.0, v83
	v_rcp_f32_e32 v84, v84
	v_rcp_f32_e32 v85, v85
	v_rcp_f32_e32 v82, v82
	v_rcp_f32_e32 v83, v83
	v_lshlrev_b32_e32 v96, 16, v92
	v_and_b32_e32 v97, 0xffff0000, v92
	v_lshlrev_b32_e32 v100, 16, v88
	v_and_b32_e32 v101, 0xffff0000, v88
	v_lshlrev_b32_e32 v92, 16, v93
	v_and_b32_e32 v93, 0xffff0000, v93
	v_lshlrev_b32_e32 v88, 16, v89
	v_and_b32_e32 v89, 0xffff0000, v89
	v_pk_fma_f32 v[86:87], v[86:87], v[92:93], v[88:89]
	v_lshlrev_b32_e32 v88, 16, v94
	v_and_b32_e32 v89, 0xffff0000, v94
	v_lshlrev_b32_e32 v92, 16, v90
	v_and_b32_e32 v93, 0xffff0000, v90
	v_pk_fma_f32 v[88:89], v[80:81], v[88:89], v[92:93]
	v_lshlrev_b32_e32 v80, 16, v95
	v_and_b32_e32 v81, 0xffff0000, v95
	v_lshlrev_b32_e32 v90, 16, v91
	v_and_b32_e32 v91, 0xffff0000, v91
	v_pk_fma_f32 v[84:85], v[84:85], v[96:97], v[100:101]
	v_pk_fma_f32 v[90:91], v[82:83], v[80:81], v[90:91]
	v_cvt_pk_bf16_f32 v80, v84, v85
	v_cvt_pk_bf16_f32 v81, v86, v87
	v_cvt_pk_bf16_f32 v82, v88, v89
	v_cvt_pk_bf16_f32 v83, v90, v91
	global_store_dwordx4 v[98:99], v[80:83], off
	s_nop 1
	v_mov_b32_e32 v80, v244
	s_nop 0
	v_or_b32_e32 v82, 48, v164
	v_ashrrev_i32_e32 v83, 31, v82
	v_lshlrev_b64 v[82:83], 10, v[82:83]
	v_lshl_add_u64 v[82:83], v[82:83], 0, v[162:163]
	v_lshlrev_b64 v[82:83], 1, v[82:83]
	v_lshl_add_u64 v[84:85], s[30:31], 0, v[82:83]
	v_lshl_add_u64 v[92:93], s[0:1], 0, v[82:83]
	s_waitcnt vmcnt(13)
; __device__ __forceinline__ unsigned cvt_pk_bf16(float lo, float hi) { const f32x2_cv v = {lo, hi}; const bf16x2_cv b = __builtin_convertvector(v, bf16x2_cv); return __builtin_bit_cast(unsigned, b); }
; __device__ __forceinline__ float sigm(float x) { return __builtin_amdgcn_rcpf(1.0f + __expf(-x)); }
; __device__ __forceinline__ float lo16(unsigned w) { return __uint_as_float(w << 16); }
; __device__ __forceinline__ float hi16(unsigned w) { return __uint_as_float(w & 0xffff0000u); }
; __device__ __forceinline__ float rstd_of(const float* rowss, int row) { return rsqrtf(rowss[row] * (1.0f / 1024.0f) + 1e-6f); }
;     __device__ __forceinline__ void operator()(const f32x4 (&acc)[2][2][4][2], const pg8::Unit& u, int wr, int wc, int fr, int fq) const {
;     ...
;                 const float s = rstd_of(rowss, row);
; #pragma unroll
;                 for (int bj = 0; bj < 2; ++bj) {
;                     const size_t off = (size_t)row * 1024 + col0 + bj * 128;
;                     const u32x4 tv = *(const u32x4*)(Tm + off);
;                     u32x4 pv = (u32x4){0u, 0u, 0u, 0u};
;                     if (ACC) pv = *(const u32x4*)(M + off);
;                     const f32x4 a0 = acc[ai][bj][m][0] * s, a1 = acc[ai][bj][m][1] * s;
;                     float o[8];
;                     o[0] = sigm(a0[0]) * lo16(tv.x); o[1] = sigm(a0[1]) * hi16(tv.x); o[2] = sigm(a0[2]) * lo16(tv.y); o[3] = sigm(a0[3]) * hi16(tv.y);
;                     o[4] = sigm(a1[0]) * lo16(tv.z); o[5] = sigm(a1[1]) * hi16(tv.z); o[6] = sigm(a1[2]) * lo16(tv.w); o[7] = sigm(a1[3]) * hi16(tv.w);
;                     if (ACC) { o[0] += lo16(pv.x); o[1] += hi16(pv.x); o[2] += lo16(pv.y); o[3] += hi16(pv.y); o[4] += lo16(pv.z); o[5] += hi16(pv.z); o[6] += lo16(pv.w); o[7] += hi16(pv.w); }
;                     u32x4 w; w.x = cvt_pk_bf16(o[0], o[1]); w.y = cvt_pk_bf16(o[2], o[3]); w.z = cvt_pk_bf16(o[4], o[5]); w.w = cvt_pk_bf16(o[6], o[7]);
;                     *(u32x4*)(M + off) = w; } }
	s_nop 1
	v_mov_b32_e32 v84, v192
	v_mov_b32_e32 v85, v193
	v_mov_b32_e32 v86, v194
	v_mov_b32_e32 v87, v195
	v_or_b32_e32 v82, 0x100, v82
	s_nop 1
	v_mov_b32_e32 v88, v196
	v_mov_b32_e32 v89, v197
	v_mov_b32_e32 v90, v198
	v_mov_b32_e32 v91, v199
	v_fmamk_f32 v80, v80, 0x3a800000, v187
	v_cmp_gt_f32_e32 vcc, s67, v80
	v_mul_f32_e32 v81, 0x4b800000, v80
	v_lshlrev_b32_e32 v94, 16, v84
	v_cndmask_b32_e32 v80, v80, v81, vcc
	v_rsq_f32_e32 v80, v80
	v_and_b32_e32 v95, 0xffff0000, v84
	v_lshlrev_b32_e32 v96, 16, v88
	v_and_b32_e32 v97, 0xffff0000, v88
	v_mul_f32_e32 v81, 0x45800000, v80
	v_cndmask_b32_e32 v80, v80, v81, vcc
	v_pk_mul_f32 v[78:79], v[78:79], v[80:81] op_sel_hi:[1,0]
	v_pk_mul_f32 v[72:73], v[72:73], v[80:81] op_sel_hi:[1,0]
	v_mul_f32_e32 v78, 0xbfb8aa3b, v78
	v_mul_f32_e32 v79, 0xbfb8aa3b, v79
	v_pk_mul_f32 v[76:77], v[76:77], v[80:81] op_sel_hi:[1,0]
	v_pk_mul_f32 v[74:75], v[74:75], v[80:81] op_sel_hi:[1,0]
	v_exp_f32_e32 v78, v78
	v_exp_f32_e32 v79, v79
	v_mul_f32_e32 v72, 0xbfb8aa3b, v72
	v_mul_f32_e32 v73, 0xbfb8aa3b, v73
	v_mul_f32_e32 v76, 0xbfb8aa3b, v76
	v_mul_f32_e32 v77, 0xbfb8aa3b, v77
	v_exp_f32_e32 v72, v72
	v_exp_f32_e32 v73, v73
	v_mul_f32_e32 v74, 0xbfb8aa3b, v74
	v_mul_f32_e32 v75, 0xbfb8aa3b, v75
	v_exp_f32_e32 v76, v76
	v_exp_f32_e32 v77, v77
	v_exp_f32_e32 v74, v74
	v_exp_f32_e32 v75, v75
	v_add_f32_e32 v78, 1.0, v78
	v_add_f32_e32 v79, 1.0, v79
	v_rcp_f32_e32 v78, v78
	v_rcp_f32_e32 v79, v79
	v_add_f32_e32 v72, 1.0, v72
	v_add_f32_e32 v73, 1.0, v73
	v_add_f32_e32 v76, 1.0, v76
	v_add_f32_e32 v77, 1.0, v77
	v_rcp_f32_e32 v72, v72
	v_rcp_f32_e32 v73, v73
	v_add_f32_e32 v74, 1.0, v74
	v_add_f32_e32 v75, 1.0, v75
	v_rcp_f32_e32 v76, v76
	v_rcp_f32_e32 v77, v77
	v_rcp_f32_e32 v74, v74
	v_rcp_f32_e32 v75, v75
	v_lshlrev_b32_e32 v84, 16, v85
	v_and_b32_e32 v85, 0xffff0000, v85
	v_lshlrev_b32_e32 v88, 16, v89
	v_and_b32_e32 v89, 0xffff0000, v89
	v_pk_fma_f32 v[78:79], v[78:79], v[84:85], v[88:89]
	v_lshlrev_b32_e32 v84, 16, v86
	v_and_b32_e32 v85, 0xffff0000, v86
	v_lshlrev_b32_e32 v88, 16, v90
	v_and_b32_e32 v89, 0xffff0000, v90
	v_pk_fma_f32 v[84:85], v[72:73], v[84:85], v[88:89]
	v_lshlrev_b32_e32 v72, 16, v87
	v_and_b32_e32 v73, 0xffff0000, v87
	v_lshlrev_b32_e32 v86, 16, v91
	v_and_b32_e32 v87, 0xffff0000, v91
	v_pk_fma_f32 v[76:77], v[76:77], v[94:95], v[96:97]
	v_pk_fma_f32 v[86:87], v[74:75], v[72:73], v[86:87]
	v_cvt_pk_bf16_f32 v72, v76, v77
	v_cvt_pk_bf16_f32 v73, v78, v79
	v_cvt_pk_bf16_f32 v74, v84, v85
	v_cvt_pk_bf16_f32 v75, v86, v87
	global_store_dwordx4 v[92:93], v[72:75], off
	v_pk_mul_f32 v[70:71], v[70:71], v[80:81] op_sel_hi:[1,0]
	v_pk_mul_f32 v[64:65], v[64:65], v[80:81] op_sel_hi:[1,0]
	v_lshl_add_u64 v[72:73], s[30:31], 0, v[82:83]
	v_lshl_add_u64 v[82:83], s[0:1], 0, v[82:83]
	s_nop 1
	v_mov_b32_e32 v76, v200
	v_mov_b32_e32 v77, v201
	v_mov_b32_e32 v78, v202
	v_mov_b32_e32 v79, v203
	v_mul_f32_e32 v70, 0xbfb8aa3b, v70
	s_nop 1
	v_mov_b32_e32 v72, v204
	v_mov_b32_e32 v73, v205
	v_mov_b32_e32 v74, v206
	v_mov_b32_e32 v75, v207
	v_add_u32_e32 v250, 0x50000, v249
	global_load_dwordx4 v[192:195], v250, s[30:31]
	global_load_dwordx4 v[196:199], v250, s[0:1]
	global_load_dwordx4 v[200:203], v250, s[30:31] offset:256
	global_load_dwordx4 v[204:207], v250, s[0:1] offset:256
	v_mul_f32_e32 v71, 0xbfb8aa3b, v71
	v_pk_mul_f32 v[68:69], v[68:69], v[80:81] op_sel_hi:[1,0]
	v_pk_mul_f32 v[66:67], v[66:67], v[80:81] op_sel_hi:[1,0]
	v_exp_f32_e32 v70, v70
	v_exp_f32_e32 v71, v71
	v_mul_f32_e32 v64, 0xbfb8aa3b, v64
	v_mul_f32_e32 v65, 0xbfb8aa3b, v65
	v_mul_f32_e32 v68, 0xbfb8aa3b, v68
	v_mul_f32_e32 v69, 0xbfb8aa3b, v69
	v_exp_f32_e32 v64, v64
	v_exp_f32_e32 v65, v65
	v_mul_f32_e32 v66, 0xbfb8aa3b, v66
	v_mul_f32_e32 v67, 0xbfb8aa3b, v67
	v_exp_f32_e32 v68, v68
	v_exp_f32_e32 v69, v69
	v_exp_f32_e32 v66, v66
	v_exp_f32_e32 v67, v67
	v_add_f32_e32 v70, 1.0, v70
	v_add_f32_e32 v71, 1.0, v71
	v_rcp_f32_e32 v70, v70
	v_rcp_f32_e32 v71, v71
	v_add_f32_e32 v64, 1.0, v64
	v_add_f32_e32 v65, 1.0, v65
	v_add_f32_e32 v68, 1.0, v68
	v_add_f32_e32 v69, 1.0, v69
	v_rcp_f32_e32 v64, v64
	v_rcp_f32_e32 v65, v65
	v_add_f32_e32 v66, 1.0, v66
	v_add_f32_e32 v67, 1.0, v67
	v_rcp_f32_e32 v68, v68
	v_rcp_f32_e32 v69, v69
	v_rcp_f32_e32 v66, v66
	v_rcp_f32_e32 v67, v67
	v_lshlrev_b32_e32 v80, 16, v76
	v_and_b32_e32 v81, 0xffff0000, v76
	v_lshlrev_b32_e32 v84, 16, v72
	v_and_b32_e32 v85, 0xffff0000, v72
	v_lshlrev_b32_e32 v76, 16, v77
	v_and_b32_e32 v77, 0xffff0000, v77
	v_lshlrev_b32_e32 v72, 16, v73
	v_and_b32_e32 v73, 0xffff0000, v73
	v_pk_fma_f32 v[70:71], v[70:71], v[76:77], v[72:73]
	v_lshlrev_b32_e32 v72, 16, v78
	v_and_b32_e32 v73, 0xffff0000, v78
	v_lshlrev_b32_e32 v76, 16, v74
	v_and_b32_e32 v77, 0xffff0000, v74
	v_pk_fma_f32 v[72:73], v[64:65], v[72:73], v[76:77]
	v_lshlrev_b32_e32 v64, 16, v79
	v_and_b32_e32 v65, 0xffff0000, v79
	v_lshlrev_b32_e32 v74, 16, v75
	v_and_b32_e32 v75, 0xffff0000, v75
	v_pk_fma_f32 v[68:69], v[68:69], v[80:81], v[84:85]
	v_pk_fma_f32 v[74:75], v[66:67], v[64:65], v[74:75]
	v_cvt_pk_bf16_f32 v64, v68, v69
	v_cvt_pk_bf16_f32 v65, v70, v71
	v_cvt_pk_bf16_f32 v66, v72, v73
	v_cvt_pk_bf16_f32 v67, v74, v75
	global_store_dwordx4 v[82:83], v[64:67], off
	s_nop 1
	v_mov_b32_e32 v64, v245
	v_lshl_add_u64 v[70:71], v[158:159], 0, s[2:3]
	v_lshl_add_u64 v[66:67], s[30:31], 0, v[70:71]
	v_lshl_add_u64 v[74:75], s[0:1], 0, v[70:71]
	s_waitcnt vmcnt(13)
; __device__ __forceinline__ unsigned cvt_pk_bf16(float lo, float hi) { const f32x2_cv v = {lo, hi}; const bf16x2_cv b = __builtin_convertvector(v, bf16x2_cv); return __builtin_bit_cast(unsigned, b); }
; __device__ __forceinline__ float sigm(float x) { return __builtin_amdgcn_rcpf(1.0f + __expf(-x)); }
; __device__ __forceinline__ float lo16(unsigned w) { return __uint_as_float(w << 16); }
; __device__ __forceinline__ float hi16(unsigned w) { return __uint_as_float(w & 0xffff0000u); }
; __device__ __forceinline__ float rstd_of(const float* rowss, int row) { return rsqrtf(rowss[row] * (1.0f / 1024.0f) + 1e-6f); }
;     __device__ __forceinline__ void operator()(const f32x4 (&acc)[2][2][4][2], const pg8::Unit& u, int wr, int wc, int fr, int fq) const {
;     ...
;                 const float s = rstd_of(rowss, row);
; #pragma unroll
;                 for (int bj = 0; bj < 2; ++bj) {
;                     const size_t off = (size_t)row * 1024 + col0 + bj * 128;
;                     const u32x4 tv = *(const u32x4*)(Tm + off);
;                     u32x4 pv = (u32x4){0u, 0u, 0u, 0u};
;                     if (ACC) pv = *(const u32x4*)(M + off);
;                     const f32x4 a0 = acc[ai][bj][m][0] * s, a1 = acc[ai][bj][m][1] * s;
;                     float o[8];
;                     o[0] = sigm(a0[0]) * lo16(tv.x); o[1] = sigm(a0[1]) * hi16(tv.x); o[2] = sigm(a0[2]) * lo16(tv.y); o[3] = sigm(a0[3]) * hi16(tv.y);
;                     o[4] = sigm(a1[0]) * lo16(tv.z); o[5] = sigm(a1[1]) * hi16(tv.z); o[6] = sigm(a1[2]) * lo16(tv.w); o[7] = sigm(a1[3]) * hi16(tv.w);
;                     if (ACC) { o[0] += lo16(pv.x); o[1] += hi16(pv.x); o[2] += lo16(pv.y); o[3] += hi16(pv.y); o[4] += lo16(pv.z); o[5] += hi16(pv.z); o[6] += lo16(pv.w); o[7] += hi16(pv.w); }
;                     u32x4 w; w.x = cvt_pk_bf16(o[0], o[1]); w.y = cvt_pk_bf16(o[2], o[3]); w.z = cvt_pk_bf16(o[4], o[5]); w.w = cvt_pk_bf16(o[6], o[7]);
;                     *(u32x4*)(M + off) = w; } }
	s_nop 1
	v_mov_b32_e32 v66, v208
	v_mov_b32_e32 v67, v209
	v_mov_b32_e32 v68, v210
	v_mov_b32_e32 v69, v211
	s_mov_b64 s[2:3], 0x40100
	s_nop 1
	v_mov_b32_e32 v70, v212
	v_mov_b32_e32 v71, v213
	v_mov_b32_e32 v72, v214
	v_mov_b32_e32 v73, v215
	v_fmamk_f32 v64, v64, 0x3a800000, v187
	v_cmp_gt_f32_e32 vcc, s67, v64
	v_mul_f32_e32 v65, 0x4b800000, v64
	v_lshlrev_b32_e32 v76, 16, v66
	v_cndmask_b32_e32 v64, v64, v65, vcc
	v_rsq_f32_e32 v64, v64
	v_and_b32_e32 v77, 0xffff0000, v66
	v_lshlrev_b32_e32 v78, 16, v70
	v_and_b32_e32 v79, 0xffff0000, v70
	v_mul_f32_e32 v65, 0x45800000, v64
	v_cndmask_b32_e32 v64, v64, v65, vcc
	v_pk_mul_f32 v[62:63], v[62:63], v[64:65] op_sel_hi:[1,0]
	v_pk_mul_f32 v[56:57], v[56:57], v[64:65] op_sel_hi:[1,0]
	v_mul_f32_e32 v62, 0xbfb8aa3b, v62
	v_mul_f32_e32 v63, 0xbfb8aa3b, v63
	v_pk_mul_f32 v[60:61], v[60:61], v[64:65] op_sel_hi:[1,0]
	v_pk_mul_f32 v[58:59], v[58:59], v[64:65] op_sel_hi:[1,0]
	v_exp_f32_e32 v62, v62
	v_exp_f32_e32 v63, v63
	v_mul_f32_e32 v56, 0xbfb8aa3b, v56
	v_mul_f32_e32 v57, 0xbfb8aa3b, v57
	v_mul_f32_e32 v60, 0xbfb8aa3b, v60
	v_mul_f32_e32 v61, 0xbfb8aa3b, v61
	v_exp_f32_e32 v56, v56
	v_exp_f32_e32 v57, v57
	v_mul_f32_e32 v58, 0xbfb8aa3b, v58
	v_mul_f32_e32 v59, 0xbfb8aa3b, v59
	v_exp_f32_e32 v60, v60
	v_exp_f32_e32 v61, v61
	v_exp_f32_e32 v58, v58
	v_exp_f32_e32 v59, v59
	v_add_f32_e32 v62, 1.0, v62
	v_add_f32_e32 v63, 1.0, v63
	v_rcp_f32_e32 v62, v62
	v_rcp_f32_e32 v63, v63
	v_add_f32_e32 v56, 1.0, v56
	v_add_f32_e32 v57, 1.0, v57
	v_add_f32_e32 v60, 1.0, v60
	v_add_f32_e32 v61, 1.0, v61
	v_rcp_f32_e32 v56, v56
	v_rcp_f32_e32 v57, v57
	v_add_f32_e32 v58, 1.0, v58
	v_add_f32_e32 v59, 1.0, v59
	v_rcp_f32_e32 v60, v60
	v_rcp_f32_e32 v61, v61
	v_rcp_f32_e32 v58, v58
	v_rcp_f32_e32 v59, v59
	v_lshlrev_b32_e32 v66, 16, v67
	v_and_b32_e32 v67, 0xffff0000, v67
	v_lshlrev_b32_e32 v70, 16, v71
	v_and_b32_e32 v71, 0xffff0000, v71
	v_pk_fma_f32 v[62:63], v[62:63], v[66:67], v[70:71]
	v_lshlrev_b32_e32 v66, 16, v68
	v_and_b32_e32 v67, 0xffff0000, v68
	v_lshlrev_b32_e32 v70, 16, v72
	v_and_b32_e32 v71, 0xffff0000, v72
	v_pk_fma_f32 v[66:67], v[56:57], v[66:67], v[70:71]
	v_lshlrev_b32_e32 v56, 16, v69
	v_and_b32_e32 v57, 0xffff0000, v69
	v_lshlrev_b32_e32 v68, 16, v73
	v_and_b32_e32 v69, 0xffff0000, v73
	v_pk_fma_f32 v[60:61], v[60:61], v[76:77], v[78:79]
	v_pk_fma_f32 v[68:69], v[58:59], v[56:57], v[68:69]
	v_cvt_pk_bf16_f32 v56, v60, v61
	v_cvt_pk_bf16_f32 v57, v62, v63
	v_cvt_pk_bf16_f32 v58, v66, v67
	v_cvt_pk_bf16_f32 v59, v68, v69
	global_store_dwordx4 v[74:75], v[56:59], off
	v_pk_mul_f32 v[54:55], v[54:55], v[64:65] op_sel_hi:[1,0]
	v_pk_mul_f32 v[48:49], v[48:49], v[64:65] op_sel_hi:[1,0]
	v_lshl_add_u64 v[56:57], v[158:159], 0, s[2:3]
	v_lshl_add_u64 v[58:59], s[30:31], 0, v[56:57]
	v_lshl_add_u64 v[66:67], s[0:1], 0, v[56:57]
	s_nop 1
	v_mov_b32_e32 v60, v216
	v_mov_b32_e32 v61, v217
	v_mov_b32_e32 v62, v218
	v_mov_b32_e32 v63, v219
	v_mul_f32_e32 v54, 0xbfb8aa3b, v54
	s_nop 1
	v_mov_b32_e32 v56, v220
	v_mov_b32_e32 v57, v221
	v_mov_b32_e32 v58, v222
	v_mov_b32_e32 v59, v223
	v_add_u32_e32 v250, 0x58000, v249
	global_load_dwordx4 v[208:211], v250, s[30:31]
	global_load_dwordx4 v[212:215], v250, s[0:1]
	global_load_dwordx4 v[216:219], v250, s[30:31] offset:256
	global_load_dwordx4 v[220:223], v250, s[0:1] offset:256
	v_mul_f32_e32 v55, 0xbfb8aa3b, v55
	v_pk_mul_f32 v[52:53], v[52:53], v[64:65] op_sel_hi:[1,0]
	v_pk_mul_f32 v[50:51], v[50:51], v[64:65] op_sel_hi:[1,0]
	v_exp_f32_e32 v54, v54
	v_exp_f32_e32 v55, v55
	v_mul_f32_e32 v48, 0xbfb8aa3b, v48
	v_mul_f32_e32 v49, 0xbfb8aa3b, v49
	v_mul_f32_e32 v52, 0xbfb8aa3b, v52
	v_mul_f32_e32 v53, 0xbfb8aa3b, v53
	v_exp_f32_e32 v48, v48
	v_exp_f32_e32 v49, v49
	v_mul_f32_e32 v50, 0xbfb8aa3b, v50
	v_mul_f32_e32 v51, 0xbfb8aa3b, v51
	v_exp_f32_e32 v52, v52
	v_exp_f32_e32 v53, v53
	v_exp_f32_e32 v50, v50
	v_exp_f32_e32 v51, v51
	v_add_f32_e32 v54, 1.0, v54
	v_add_f32_e32 v55, 1.0, v55
	v_rcp_f32_e32 v54, v54
	v_rcp_f32_e32 v55, v55
	v_add_f32_e32 v48, 1.0, v48
	v_add_f32_e32 v49, 1.0, v49
	v_add_f32_e32 v52, 1.0, v52
	v_add_f32_e32 v53, 1.0, v53
	v_rcp_f32_e32 v48, v48
	v_rcp_f32_e32 v49, v49
	v_add_f32_e32 v50, 1.0, v50
	v_add_f32_e32 v51, 1.0, v51
	v_rcp_f32_e32 v52, v52
	v_rcp_f32_e32 v53, v53
	v_rcp_f32_e32 v50, v50
	v_rcp_f32_e32 v51, v51
	s_mov_b64 s[2:3], 0x48000
	v_lshlrev_b32_e32 v64, 16, v60
	v_and_b32_e32 v65, 0xffff0000, v60
	v_lshlrev_b32_e32 v68, 16, v56
	v_and_b32_e32 v69, 0xffff0000, v56
	v_lshlrev_b32_e32 v60, 16, v61
	v_and_b32_e32 v61, 0xffff0000, v61
	v_lshlrev_b32_e32 v56, 16, v57
	v_and_b32_e32 v57, 0xffff0000, v57
	v_pk_fma_f32 v[54:55], v[54:55], v[60:61], v[56:57]
	v_lshlrev_b32_e32 v56, 16, v62
	v_and_b32_e32 v57, 0xffff0000, v62
	v_lshlrev_b32_e32 v60, 16, v58
	v_and_b32_e32 v61, 0xffff0000, v58
	v_pk_fma_f32 v[56:57], v[48:49], v[56:57], v[60:61]
	v_lshlrev_b32_e32 v48, 16, v63
	v_and_b32_e32 v49, 0xffff0000, v63
	v_lshlrev_b32_e32 v58, 16, v59
	v_and_b32_e32 v59, 0xffff0000, v59
	v_pk_fma_f32 v[52:53], v[52:53], v[64:65], v[68:69]
	v_pk_fma_f32 v[58:59], v[50:51], v[48:49], v[58:59]
	v_cvt_pk_bf16_f32 v48, v52, v53
	v_cvt_pk_bf16_f32 v49, v54, v55
	v_cvt_pk_bf16_f32 v50, v56, v57
	v_cvt_pk_bf16_f32 v51, v58, v59
	global_store_dwordx4 v[66:67], v[48:51], off
	s_nop 1
	v_mov_b32_e32 v48, v246
	v_lshl_add_u64 v[54:55], v[158:159], 0, s[2:3]
	v_lshl_add_u64 v[50:51], s[30:31], 0, v[54:55]
	v_lshl_add_u64 v[58:59], s[0:1], 0, v[54:55]
	s_waitcnt vmcnt(13)
; __device__ __forceinline__ unsigned cvt_pk_bf16(float lo, float hi) { const f32x2_cv v = {lo, hi}; const bf16x2_cv b = __builtin_convertvector(v, bf16x2_cv); return __builtin_bit_cast(unsigned, b); }
; __device__ __forceinline__ float sigm(float x) { return __builtin_amdgcn_rcpf(1.0f + __expf(-x)); }
; __device__ __forceinline__ float lo16(unsigned w) { return __uint_as_float(w << 16); }
; __device__ __forceinline__ float hi16(unsigned w) { return __uint_as_float(w & 0xffff0000u); }
; __device__ __forceinline__ float rstd_of(const float* rowss, int row) { return rsqrtf(rowss[row] * (1.0f / 1024.0f) + 1e-6f); }
;     __device__ __forceinline__ void operator()(const f32x4 (&acc)[2][2][4][2], const pg8::Unit& u, int wr, int wc, int fr, int fq) const {
;     ...
;                 const float s = rstd_of(rowss, row);
; #pragma unroll
;                 for (int bj = 0; bj < 2; ++bj) {
;                     const size_t off = (size_t)row * 1024 + col0 + bj * 128;
;                     const u32x4 tv = *(const u32x4*)(Tm + off);
;                     u32x4 pv = (u32x4){0u, 0u, 0u, 0u};
;                     if (ACC) pv = *(const u32x4*)(M + off);
;                     const f32x4 a0 = acc[ai][bj][m][0] * s, a1 = acc[ai][bj][m][1] * s;
;                     float o[8];
;                     o[0] = sigm(a0[0]) * lo16(tv.x); o[1] = sigm(a0[1]) * hi16(tv.x); o[2] = sigm(a0[2]) * lo16(tv.y); o[3] = sigm(a0[3]) * hi16(tv.y);
;                     o[4] = sigm(a1[0]) * lo16(tv.z); o[5] = sigm(a1[1]) * hi16(tv.z); o[6] = sigm(a1[2]) * lo16(tv.w); o[7] = sigm(a1[3]) * hi16(tv.w);
;                     if (ACC) { o[0] += lo16(pv.x); o[1] += hi16(pv.x); o[2] += lo16(pv.y); o[3] += hi16(pv.y); o[4] += lo16(pv.z); o[5] += hi16(pv.z); o[6] += lo16(pv.w); o[7] += hi16(pv.w); }
;                     u32x4 w; w.x = cvt_pk_bf16(o[0], o[1]); w.y = cvt_pk_bf16(o[2], o[3]); w.z = cvt_pk_bf16(o[4], o[5]); w.w = cvt_pk_bf16(o[6], o[7]);
;                     *(u32x4*)(M + off) = w; } }
	s_nop 1
	v_mov_b32_e32 v50, v224
	v_mov_b32_e32 v51, v225
	v_mov_b32_e32 v52, v226
	v_mov_b32_e32 v53, v227
	s_mov_b64 s[2:3], 0x48100
	s_nop 1
	v_mov_b32_e32 v54, v228
	v_mov_b32_e32 v55, v229
	v_mov_b32_e32 v56, v230
	v_mov_b32_e32 v57, v231
	v_fmamk_f32 v48, v48, 0x3a800000, v187
	v_cmp_gt_f32_e32 vcc, s67, v48
	v_mul_f32_e32 v49, 0x4b800000, v48
	v_lshlrev_b32_e32 v60, 16, v50
	v_cndmask_b32_e32 v48, v48, v49, vcc
	v_rsq_f32_e32 v48, v48
	v_and_b32_e32 v61, 0xffff0000, v50
	v_lshlrev_b32_e32 v62, 16, v54
	v_and_b32_e32 v63, 0xffff0000, v54
	v_mul_f32_e32 v49, 0x45800000, v48
	v_cndmask_b32_e32 v48, v48, v49, vcc
	v_pk_mul_f32 v[46:47], v[46:47], v[48:49] op_sel_hi:[1,0]
	v_pk_mul_f32 v[40:41], v[40:41], v[48:49] op_sel_hi:[1,0]
	v_mul_f32_e32 v46, 0xbfb8aa3b, v46
	v_mul_f32_e32 v47, 0xbfb8aa3b, v47
	v_pk_mul_f32 v[44:45], v[44:45], v[48:49] op_sel_hi:[1,0]
	v_pk_mul_f32 v[42:43], v[42:43], v[48:49] op_sel_hi:[1,0]
	v_exp_f32_e32 v46, v46
	v_exp_f32_e32 v47, v47
	v_mul_f32_e32 v40, 0xbfb8aa3b, v40
	v_mul_f32_e32 v41, 0xbfb8aa3b, v41
	v_mul_f32_e32 v44, 0xbfb8aa3b, v44
	v_mul_f32_e32 v45, 0xbfb8aa3b, v45
	v_exp_f32_e32 v40, v40
	v_exp_f32_e32 v41, v41
	v_mul_f32_e32 v42, 0xbfb8aa3b, v42
	v_mul_f32_e32 v43, 0xbfb8aa3b, v43
	v_exp_f32_e32 v44, v44
	v_exp_f32_e32 v45, v45
	v_exp_f32_e32 v42, v42
	v_exp_f32_e32 v43, v43
	v_add_f32_e32 v46, 1.0, v46
	v_add_f32_e32 v47, 1.0, v47
	v_rcp_f32_e32 v46, v46
	v_rcp_f32_e32 v47, v47
	v_add_f32_e32 v40, 1.0, v40
	v_add_f32_e32 v41, 1.0, v41
	v_add_f32_e32 v44, 1.0, v44
	v_add_f32_e32 v45, 1.0, v45
	v_rcp_f32_e32 v40, v40
	v_rcp_f32_e32 v41, v41
	v_add_f32_e32 v42, 1.0, v42
	v_add_f32_e32 v43, 1.0, v43
	v_rcp_f32_e32 v44, v44
	v_rcp_f32_e32 v45, v45
	v_rcp_f32_e32 v42, v42
	v_rcp_f32_e32 v43, v43
	v_lshlrev_b32_e32 v50, 16, v51
	v_and_b32_e32 v51, 0xffff0000, v51
	v_lshlrev_b32_e32 v54, 16, v55
	v_and_b32_e32 v55, 0xffff0000, v55
	v_pk_fma_f32 v[46:47], v[46:47], v[50:51], v[54:55]
	v_lshlrev_b32_e32 v50, 16, v52
	v_and_b32_e32 v51, 0xffff0000, v52
	v_lshlrev_b32_e32 v54, 16, v56
	v_and_b32_e32 v55, 0xffff0000, v56
	v_pk_fma_f32 v[50:51], v[40:41], v[50:51], v[54:55]
	v_lshlrev_b32_e32 v40, 16, v53
	v_and_b32_e32 v41, 0xffff0000, v53
	v_lshlrev_b32_e32 v52, 16, v57
	v_and_b32_e32 v53, 0xffff0000, v57
	v_pk_fma_f32 v[44:45], v[44:45], v[60:61], v[62:63]
	v_pk_fma_f32 v[52:53], v[42:43], v[40:41], v[52:53]
	v_cvt_pk_bf16_f32 v40, v44, v45
	v_cvt_pk_bf16_f32 v41, v46, v47
	v_cvt_pk_bf16_f32 v42, v50, v51
	v_cvt_pk_bf16_f32 v43, v52, v53
	global_store_dwordx4 v[58:59], v[40:43], off
	v_pk_mul_f32 v[38:39], v[38:39], v[48:49] op_sel_hi:[1,0]
	v_pk_mul_f32 v[32:33], v[32:33], v[48:49] op_sel_hi:[1,0]
	v_lshl_add_u64 v[40:41], v[158:159], 0, s[2:3]
	v_lshl_add_u64 v[42:43], s[30:31], 0, v[40:41]
	v_lshl_add_u64 v[50:51], s[0:1], 0, v[40:41]
	s_nop 1
	v_mov_b32_e32 v44, v232
	v_mov_b32_e32 v45, v233
	v_mov_b32_e32 v46, v234
	v_mov_b32_e32 v47, v235
	v_mul_f32_e32 v38, 0xbfb8aa3b, v38
	s_nop 1
	v_mov_b32_e32 v40, v236
	v_mov_b32_e32 v41, v237
	v_mov_b32_e32 v42, v238
	v_mov_b32_e32 v43, v239
	v_mul_f32_e32 v39, 0xbfb8aa3b, v39
	v_pk_mul_f32 v[36:37], v[36:37], v[48:49] op_sel_hi:[1,0]
	v_pk_mul_f32 v[34:35], v[34:35], v[48:49] op_sel_hi:[1,0]
	v_exp_f32_e32 v38, v38
	v_exp_f32_e32 v39, v39
	v_mul_f32_e32 v32, 0xbfb8aa3b, v32
	v_mul_f32_e32 v33, 0xbfb8aa3b, v33
	v_mul_f32_e32 v36, 0xbfb8aa3b, v36
	v_mul_f32_e32 v37, 0xbfb8aa3b, v37
	v_exp_f32_e32 v32, v32
	v_exp_f32_e32 v33, v33
	v_mul_f32_e32 v34, 0xbfb8aa3b, v34
	v_mul_f32_e32 v35, 0xbfb8aa3b, v35
	v_exp_f32_e32 v36, v36
	v_exp_f32_e32 v37, v37
	v_exp_f32_e32 v34, v34
	v_exp_f32_e32 v35, v35
	v_add_f32_e32 v38, 1.0, v38
	v_add_f32_e32 v39, 1.0, v39
	v_rcp_f32_e32 v38, v38
	v_rcp_f32_e32 v39, v39
	v_add_f32_e32 v32, 1.0, v32
	v_add_f32_e32 v33, 1.0, v33
	v_add_f32_e32 v36, 1.0, v36
	v_add_f32_e32 v37, 1.0, v37
	v_rcp_f32_e32 v32, v32
	v_rcp_f32_e32 v33, v33
	v_add_f32_e32 v34, 1.0, v34
	v_add_f32_e32 v35, 1.0, v35
	v_rcp_f32_e32 v36, v36
	v_rcp_f32_e32 v37, v37
	v_rcp_f32_e32 v34, v34
	v_rcp_f32_e32 v35, v35
	s_mov_b64 s[2:3], 0x50000
	v_lshlrev_b32_e32 v48, 16, v44
	v_and_b32_e32 v49, 0xffff0000, v44
	v_lshlrev_b32_e32 v52, 16, v40
	v_and_b32_e32 v53, 0xffff0000, v40
	v_lshlrev_b32_e32 v44, 16, v45
	v_and_b32_e32 v45, 0xffff0000, v45
	v_lshlrev_b32_e32 v40, 16, v41
	v_and_b32_e32 v41, 0xffff0000, v41
	v_pk_fma_f32 v[38:39], v[38:39], v[44:45], v[40:41]
	v_lshlrev_b32_e32 v40, 16, v46
	v_and_b32_e32 v41, 0xffff0000, v46
	v_lshlrev_b32_e32 v44, 16, v42
	v_and_b32_e32 v45, 0xffff0000, v42
	v_pk_fma_f32 v[40:41], v[32:33], v[40:41], v[44:45]
	v_lshlrev_b32_e32 v32, 16, v47
	v_and_b32_e32 v33, 0xffff0000, v47
	v_lshlrev_b32_e32 v42, 16, v43
	v_and_b32_e32 v43, 0xffff0000, v43
	v_pk_fma_f32 v[36:37], v[36:37], v[48:49], v[52:53]
	v_pk_fma_f32 v[42:43], v[34:35], v[32:33], v[42:43]
	v_cvt_pk_bf16_f32 v32, v36, v37
	v_cvt_pk_bf16_f32 v33, v38, v39
	v_cvt_pk_bf16_f32 v34, v40, v41
	v_cvt_pk_bf16_f32 v35, v42, v43
	global_store_dwordx4 v[50:51], v[32:35], off
	s_nop 1
	v_mov_b32_e32 v32, v247
	v_lshl_add_u64 v[38:39], v[158:159], 0, s[2:3]
	v_lshl_add_u64 v[34:35], s[30:31], 0, v[38:39]
	v_lshl_add_u64 v[42:43], s[0:1], 0, v[38:39]
	s_waitcnt vmcnt(9)
; __device__ __forceinline__ unsigned cvt_pk_bf16(float lo, float hi) { const f32x2_cv v = {lo, hi}; const bf16x2_cv b = __builtin_convertvector(v, bf16x2_cv); return __builtin_bit_cast(unsigned, b); }
; __device__ __forceinline__ float sigm(float x) { return __builtin_amdgcn_rcpf(1.0f + __expf(-x)); }
; __device__ __forceinline__ float lo16(unsigned w) { return __uint_as_float(w << 16); }
; __device__ __forceinline__ float hi16(unsigned w) { return __uint_as_float(w & 0xffff0000u); }
; __device__ __forceinline__ float rstd_of(const float* rowss, int row) { return rsqrtf(rowss[row] * (1.0f / 1024.0f) + 1e-6f); }
;     __device__ __forceinline__ void operator()(const f32x4 (&acc)[2][2][4][2], const pg8::Unit& u, int wr, int wc, int fr, int fq) const {
;     ...
;                 const float s = rstd_of(rowss, row);
; #pragma unroll
;                 for (int bj = 0; bj < 2; ++bj) {
;                     const size_t off = (size_t)row * 1024 + col0 + bj * 128;
;                     const u32x4 tv = *(const u32x4*)(Tm + off);
;                     u32x4 pv = (u32x4){0u, 0u, 0u, 0u};
;                     if (ACC) pv = *(const u32x4*)(M + off);
;                     const f32x4 a0 = acc[ai][bj][m][0] * s, a1 = acc[ai][bj][m][1] * s;
;                     float o[8];
;                     o[0] = sigm(a0[0]) * lo16(tv.x); o[1] = sigm(a0[1]) * hi16(tv.x); o[2] = sigm(a0[2]) * lo16(tv.y); o[3] = sigm(a0[3]) * hi16(tv.y);
;                     o[4] = sigm(a1[0]) * lo16(tv.z); o[5] = sigm(a1[1]) * hi16(tv.z); o[6] = sigm(a1[2]) * lo16(tv.w); o[7] = sigm(a1[3]) * hi16(tv.w);
;                     if (ACC) { o[0] += lo16(pv.x); o[1] += hi16(pv.x); o[2] += lo16(pv.y); o[3] += hi16(pv.y); o[4] += lo16(pv.z); o[5] += hi16(pv.z); o[6] += lo16(pv.w); o[7] += hi16(pv.w); }
;                     u32x4 w; w.x = cvt_pk_bf16(o[0], o[1]); w.y = cvt_pk_bf16(o[2], o[3]); w.z = cvt_pk_bf16(o[4], o[5]); w.w = cvt_pk_bf16(o[6], o[7]);
;                     *(u32x4*)(M + off) = w; } }
	s_nop 1
	v_mov_b32_e32 v34, v192
	v_mov_b32_e32 v35, v193
	v_mov_b32_e32 v36, v194
	v_mov_b32_e32 v37, v195
	s_mov_b64 s[2:3], 0x50100
	s_nop 1
	v_mov_b32_e32 v38, v196
	v_mov_b32_e32 v39, v197
	v_mov_b32_e32 v40, v198
	v_mov_b32_e32 v41, v199
	v_fmamk_f32 v32, v32, 0x3a800000, v187
	v_cmp_gt_f32_e32 vcc, s67, v32
	v_mul_f32_e32 v33, 0x4b800000, v32
	v_lshlrev_b32_e32 v44, 16, v34
	v_cndmask_b32_e32 v32, v32, v33, vcc
	v_rsq_f32_e32 v32, v32
	v_and_b32_e32 v45, 0xffff0000, v34
	v_lshlrev_b32_e32 v46, 16, v38
	v_and_b32_e32 v47, 0xffff0000, v38
	v_mul_f32_e32 v33, 0x45800000, v32
	v_cndmask_b32_e32 v32, v32, v33, vcc
	v_pk_mul_f32 v[30:31], v[30:31], v[32:33] op_sel_hi:[1,0]
	v_pk_mul_f32 v[24:25], v[24:25], v[32:33] op_sel_hi:[1,0]
	v_mul_f32_e32 v30, 0xbfb8aa3b, v30
	v_mul_f32_e32 v31, 0xbfb8aa3b, v31
	v_pk_mul_f32 v[28:29], v[28:29], v[32:33] op_sel_hi:[1,0]
	v_pk_mul_f32 v[26:27], v[26:27], v[32:33] op_sel_hi:[1,0]
	v_exp_f32_e32 v30, v30
	v_exp_f32_e32 v31, v31
	v_mul_f32_e32 v24, 0xbfb8aa3b, v24
	v_mul_f32_e32 v25, 0xbfb8aa3b, v25
	v_mul_f32_e32 v28, 0xbfb8aa3b, v28
	v_mul_f32_e32 v29, 0xbfb8aa3b, v29
	v_exp_f32_e32 v24, v24
	v_exp_f32_e32 v25, v25
	v_mul_f32_e32 v26, 0xbfb8aa3b, v26
	v_mul_f32_e32 v27, 0xbfb8aa3b, v27
	v_exp_f32_e32 v28, v28
	v_exp_f32_e32 v29, v29
	v_exp_f32_e32 v26, v26
	v_exp_f32_e32 v27, v27
	v_add_f32_e32 v30, 1.0, v30
	v_add_f32_e32 v31, 1.0, v31
	v_rcp_f32_e32 v30, v30
	v_rcp_f32_e32 v31, v31
	v_add_f32_e32 v24, 1.0, v24
	v_add_f32_e32 v25, 1.0, v25
	v_add_f32_e32 v28, 1.0, v28
	v_add_f32_e32 v29, 1.0, v29
	v_rcp_f32_e32 v24, v24
	v_rcp_f32_e32 v25, v25
	v_add_f32_e32 v26, 1.0, v26
	v_add_f32_e32 v27, 1.0, v27
	v_rcp_f32_e32 v28, v28
	v_rcp_f32_e32 v29, v29
	v_rcp_f32_e32 v26, v26
	v_rcp_f32_e32 v27, v27
	v_lshlrev_b32_e32 v34, 16, v35
	v_and_b32_e32 v35, 0xffff0000, v35
	v_lshlrev_b32_e32 v38, 16, v39
	v_and_b32_e32 v39, 0xffff0000, v39
	v_pk_fma_f32 v[30:31], v[30:31], v[34:35], v[38:39]
	v_lshlrev_b32_e32 v34, 16, v36
	v_and_b32_e32 v35, 0xffff0000, v36
	v_lshlrev_b32_e32 v38, 16, v40
	v_and_b32_e32 v39, 0xffff0000, v40
	v_pk_fma_f32 v[34:35], v[24:25], v[34:35], v[38:39]
	v_lshlrev_b32_e32 v24, 16, v37
	v_and_b32_e32 v25, 0xffff0000, v37
	v_lshlrev_b32_e32 v36, 16, v41
	v_and_b32_e32 v37, 0xffff0000, v41
	v_pk_fma_f32 v[28:29], v[28:29], v[44:45], v[46:47]
	v_pk_fma_f32 v[36:37], v[26:27], v[24:25], v[36:37]
	v_cvt_pk_bf16_f32 v24, v28, v29
	v_cvt_pk_bf16_f32 v25, v30, v31
	v_cvt_pk_bf16_f32 v26, v34, v35
	v_cvt_pk_bf16_f32 v27, v36, v37
	global_store_dwordx4 v[42:43], v[24:27], off
	v_pk_mul_f32 v[22:23], v[22:23], v[32:33] op_sel_hi:[1,0]
	v_pk_mul_f32 v[16:17], v[16:17], v[32:33] op_sel_hi:[1,0]
	v_lshl_add_u64 v[24:25], v[158:159], 0, s[2:3]
	v_lshl_add_u64 v[26:27], s[30:31], 0, v[24:25]
	v_lshl_add_u64 v[34:35], s[0:1], 0, v[24:25]
	s_nop 1
	v_mov_b32_e32 v28, v200
	v_mov_b32_e32 v29, v201
	v_mov_b32_e32 v30, v202
	v_mov_b32_e32 v31, v203
	v_mul_f32_e32 v22, 0xbfb8aa3b, v22
	s_nop 1
	v_mov_b32_e32 v24, v204
	v_mov_b32_e32 v25, v205
	v_mov_b32_e32 v26, v206
	v_mov_b32_e32 v27, v207
	v_mul_f32_e32 v23, 0xbfb8aa3b, v23
	v_pk_mul_f32 v[20:21], v[20:21], v[32:33] op_sel_hi:[1,0]
	v_pk_mul_f32 v[18:19], v[18:19], v[32:33] op_sel_hi:[1,0]
	v_exp_f32_e32 v22, v22
	v_exp_f32_e32 v23, v23
	v_mul_f32_e32 v16, 0xbfb8aa3b, v16
	v_mul_f32_e32 v17, 0xbfb8aa3b, v17
	v_mul_f32_e32 v20, 0xbfb8aa3b, v20
	v_mul_f32_e32 v21, 0xbfb8aa3b, v21
	v_exp_f32_e32 v16, v16
	v_exp_f32_e32 v17, v17
	v_mul_f32_e32 v18, 0xbfb8aa3b, v18
	v_mul_f32_e32 v19, 0xbfb8aa3b, v19
	v_exp_f32_e32 v20, v20
	v_exp_f32_e32 v21, v21
	v_exp_f32_e32 v18, v18
	v_exp_f32_e32 v19, v19
	v_add_f32_e32 v22, 1.0, v22
	v_add_f32_e32 v23, 1.0, v23
	v_rcp_f32_e32 v22, v22
	v_rcp_f32_e32 v23, v23
	v_add_f32_e32 v16, 1.0, v16
	v_add_f32_e32 v17, 1.0, v17
	v_add_f32_e32 v20, 1.0, v20
	v_add_f32_e32 v21, 1.0, v21
	v_rcp_f32_e32 v16, v16
	v_rcp_f32_e32 v17, v17
	v_add_f32_e32 v18, 1.0, v18
	v_add_f32_e32 v19, 1.0, v19
	v_rcp_f32_e32 v20, v20
	v_rcp_f32_e32 v21, v21
	v_rcp_f32_e32 v18, v18
	v_rcp_f32_e32 v19, v19
	s_mov_b64 s[2:3], 0x58000
	v_lshlrev_b32_e32 v32, 16, v28
	v_and_b32_e32 v33, 0xffff0000, v28
	v_lshlrev_b32_e32 v36, 16, v24
	v_and_b32_e32 v37, 0xffff0000, v24
	v_lshlrev_b32_e32 v28, 16, v29
	v_and_b32_e32 v29, 0xffff0000, v29
	v_lshlrev_b32_e32 v24, 16, v25
	v_and_b32_e32 v25, 0xffff0000, v25
	v_pk_fma_f32 v[22:23], v[22:23], v[28:29], v[24:25]
	v_lshlrev_b32_e32 v24, 16, v30
	v_and_b32_e32 v25, 0xffff0000, v30
	v_lshlrev_b32_e32 v28, 16, v26
	v_and_b32_e32 v29, 0xffff0000, v26
	v_pk_fma_f32 v[24:25], v[16:17], v[24:25], v[28:29]
	v_lshlrev_b32_e32 v16, 16, v31
	v_and_b32_e32 v17, 0xffff0000, v31
	v_lshlrev_b32_e32 v26, 16, v27
	v_and_b32_e32 v27, 0xffff0000, v27
	v_pk_fma_f32 v[20:21], v[20:21], v[32:33], v[36:37]
	v_pk_fma_f32 v[26:27], v[18:19], v[16:17], v[26:27]
	v_cvt_pk_bf16_f32 v16, v20, v21
	v_cvt_pk_bf16_f32 v17, v22, v23
	v_cvt_pk_bf16_f32 v18, v24, v25
	v_cvt_pk_bf16_f32 v19, v26, v27
	global_store_dwordx4 v[34:35], v[16:19], off
	s_nop 1
	v_mov_b32_e32 v16, v248
	v_lshl_add_u64 v[22:23], v[158:159], 0, s[2:3]
	v_lshl_add_u64 v[18:19], s[30:31], 0, v[22:23]
	v_lshl_add_u64 v[26:27], s[0:1], 0, v[22:23]
	s_waitcnt vmcnt(5)
; __device__ __forceinline__ unsigned cvt_pk_bf16(float lo, float hi) { const f32x2_cv v = {lo, hi}; const bf16x2_cv b = __builtin_convertvector(v, bf16x2_cv); return __builtin_bit_cast(unsigned, b); }
; #define PG8_WAIT_V(n) asm volatile("s_waitcnt vmcnt(" #n ")" ::: "memory")
; template <class Epi, class Sched, bool STAMP = false>
; __device__ __forceinline__ void gemm_phase(PG8_LAS unsigned char* lds, const Gemm g, const Sched& S, const Epi& E, unsigned long long* stamps) {
;     ...
;         if constexpr (!Epi::AFTER_DRAIN) { E(acc, cur, wr, wc, fr, fq); S.done(cur); }
;         if (!has_next) break;
; #pragma unroll
;         for (int a = 0; a < 2; ++a)
; #pragma unroll
;             for (int b = 0; b < 2; ++b)
; #pragma unroll
;                 for (int m = 0; m < 4; ++m)
; #pragma unroll
;                     for (int n = 0; n < 2; ++n) acc[a][b][m][n] = (f32x4){0.f, 0.f, 0.f, 0.f};
;         cur = nxt; cA = nA; cB = nB; ++ui;
;     }
;     PG8_WAIT_V(0);
;     if (wr == 0) PG8_BAR;
;     PG8_BAR;
;     __device__ __forceinline__ void operator()(const f32x4 (&acc)[2][2][4][2], const pg8::Unit& u, int wr, int wc, int fr, int fq) const {
;     ...
;                 const float s = rstd_of(rowss, row);
; #pragma unroll
;                 for (int bj = 0; bj < 2; ++bj) {
;                     const size_t off = (size_t)row * 1024 + col0 + bj * 128;
;                     const u32x4 tv = *(const u32x4*)(Tm + off);
;                     u32x4 pv = (u32x4){0u, 0u, 0u, 0u};
;                     if (ACC) pv = *(const u32x4*)(M + off);
;                     const f32x4 a0 = acc[ai][bj][m][0] * s, a1 = acc[ai][bj][m][1] * s;
;                     float o[8];
;                     o[0] = sigm(a0[0]) * lo16(tv.x); o[1] = sigm(a0[1]) * hi16(tv.x); o[2] = sigm(a0[2]) * lo16(tv.y); o[3] = sigm(a0[3]) * hi16(tv.y);
;                     o[4] = sigm(a1[0]) * lo16(tv.z); o[5] = sigm(a1[1]) * hi16(tv.z); o[6] = sigm(a1[2]) * lo16(tv.w); o[7] = sigm(a1[3]) * hi16(tv.w);
;                     if (ACC) { o[0] += lo16(pv.x); o[1] += hi16(pv.x); o[2] += lo16(pv.y); o[3] += hi16(pv.y); o[4] += lo16(pv.z); o[5] += hi16(pv.z); o[6] += lo16(pv.w); o[7] += hi16(pv.w); }
;                     u32x4 w; w.x = cvt_pk_bf16(o[0], o[1]); w.y = cvt_pk_bf16(o[2], o[3]); w.z = cvt_pk_bf16(o[4], o[5]); w.w = cvt_pk_bf16(o[6], o[7]);
;                     *(u32x4*)(M + off) = w; } }
	s_nop 1
	v_mov_b32_e32 v18, v208
	v_mov_b32_e32 v19, v209
	v_mov_b32_e32 v20, v210
	v_mov_b32_e32 v21, v211
	s_mov_b64 s[2:3], 0x58100
	s_nop 1
	v_mov_b32_e32 v22, v212
	v_mov_b32_e32 v23, v213
	v_mov_b32_e32 v24, v214
	v_mov_b32_e32 v25, v215
	v_fmamk_f32 v16, v16, 0x3a800000, v187
	v_cmp_gt_f32_e32 vcc, s67, v16
	v_mul_f32_e32 v17, 0x4b800000, v16
	v_lshlrev_b32_e32 v28, 16, v18
	v_cndmask_b32_e32 v16, v16, v17, vcc
	v_rsq_f32_e32 v16, v16
	v_and_b32_e32 v29, 0xffff0000, v18
	v_lshlrev_b32_e32 v30, 16, v22
	v_and_b32_e32 v31, 0xffff0000, v22
	v_mul_f32_e32 v17, 0x45800000, v16
	v_cndmask_b32_e32 v16, v16, v17, vcc
	v_pk_mul_f32 v[14:15], v[14:15], v[16:17] op_sel_hi:[1,0]
	v_pk_mul_f32 v[8:9], v[8:9], v[16:17] op_sel_hi:[1,0]
	v_mul_f32_e32 v14, 0xbfb8aa3b, v14
	v_mul_f32_e32 v15, 0xbfb8aa3b, v15
	v_pk_mul_f32 v[12:13], v[12:13], v[16:17] op_sel_hi:[1,0]
	v_pk_mul_f32 v[10:11], v[10:11], v[16:17] op_sel_hi:[1,0]
	v_exp_f32_e32 v14, v14
	v_exp_f32_e32 v15, v15
	v_mul_f32_e32 v8, 0xbfb8aa3b, v8
	v_mul_f32_e32 v9, 0xbfb8aa3b, v9
	v_mul_f32_e32 v12, 0xbfb8aa3b, v12
	v_mul_f32_e32 v13, 0xbfb8aa3b, v13
	v_exp_f32_e32 v8, v8
	v_exp_f32_e32 v9, v9
	v_mul_f32_e32 v10, 0xbfb8aa3b, v10
	v_mul_f32_e32 v11, 0xbfb8aa3b, v11
	v_exp_f32_e32 v12, v12
	v_exp_f32_e32 v13, v13
	v_exp_f32_e32 v10, v10
	v_exp_f32_e32 v11, v11
	v_add_f32_e32 v14, 1.0, v14
	v_add_f32_e32 v15, 1.0, v15
	v_rcp_f32_e32 v14, v14
	v_rcp_f32_e32 v15, v15
	v_add_f32_e32 v8, 1.0, v8
	v_add_f32_e32 v9, 1.0, v9
	v_add_f32_e32 v12, 1.0, v12
	v_add_f32_e32 v13, 1.0, v13
	v_rcp_f32_e32 v8, v8
	v_rcp_f32_e32 v9, v9
	v_add_f32_e32 v10, 1.0, v10
	v_add_f32_e32 v11, 1.0, v11
	v_rcp_f32_e32 v12, v12
	v_rcp_f32_e32 v13, v13
	v_rcp_f32_e32 v10, v10
	v_rcp_f32_e32 v11, v11
	v_lshlrev_b32_e32 v18, 16, v19
	v_and_b32_e32 v19, 0xffff0000, v19
	v_lshlrev_b32_e32 v22, 16, v23
	v_and_b32_e32 v23, 0xffff0000, v23
	v_pk_fma_f32 v[14:15], v[14:15], v[18:19], v[22:23]
	v_lshlrev_b32_e32 v18, 16, v20
	v_and_b32_e32 v19, 0xffff0000, v20
	v_lshlrev_b32_e32 v22, 16, v24
	v_and_b32_e32 v23, 0xffff0000, v24
	v_pk_fma_f32 v[18:19], v[8:9], v[18:19], v[22:23]
	v_lshlrev_b32_e32 v8, 16, v21
	v_and_b32_e32 v9, 0xffff0000, v21
	v_lshlrev_b32_e32 v20, 16, v25
	v_and_b32_e32 v21, 0xffff0000, v25
	v_pk_fma_f32 v[12:13], v[12:13], v[28:29], v[30:31]
	v_pk_fma_f32 v[20:21], v[10:11], v[8:9], v[20:21]
	v_cvt_pk_bf16_f32 v8, v12, v13
	v_cvt_pk_bf16_f32 v9, v14, v15
	v_cvt_pk_bf16_f32 v10, v18, v19
	v_cvt_pk_bf16_f32 v11, v20, v21
	global_store_dwordx4 v[26:27], v[8:11], off
	v_pk_mul_f32 v[6:7], v[6:7], v[16:17] op_sel_hi:[1,0]
	v_pk_mul_f32 v[0:1], v[0:1], v[16:17] op_sel_hi:[1,0]
	v_lshl_add_u64 v[8:9], v[158:159], 0, s[2:3]
	v_lshl_add_u64 v[10:11], s[30:31], 0, v[8:9]
	v_lshl_add_u64 v[18:19], s[0:1], 0, v[8:9]
	s_nop 1
	v_mov_b32_e32 v12, v216
	v_mov_b32_e32 v13, v217
	v_mov_b32_e32 v14, v218
	v_mov_b32_e32 v15, v219
	v_mul_f32_e32 v6, 0xbfb8aa3b, v6
	s_nop 1
	v_mov_b32_e32 v8, v220
	v_mov_b32_e32 v9, v221
	v_mov_b32_e32 v10, v222
	v_mov_b32_e32 v11, v223
	v_mul_f32_e32 v7, 0xbfb8aa3b, v7
	v_pk_mul_f32 v[4:5], v[4:5], v[16:17] op_sel_hi:[1,0]
	v_pk_mul_f32 v[2:3], v[2:3], v[16:17] op_sel_hi:[1,0]
	v_exp_f32_e32 v6, v6
	v_exp_f32_e32 v7, v7
	v_mul_f32_e32 v0, 0xbfb8aa3b, v0
	v_mul_f32_e32 v1, 0xbfb8aa3b, v1
	v_mul_f32_e32 v4, 0xbfb8aa3b, v4
	v_mul_f32_e32 v5, 0xbfb8aa3b, v5
	v_exp_f32_e32 v0, v0
	v_exp_f32_e32 v1, v1
	v_mul_f32_e32 v2, 0xbfb8aa3b, v2
	v_mul_f32_e32 v3, 0xbfb8aa3b, v3
	v_exp_f32_e32 v4, v4
	v_exp_f32_e32 v5, v5
	v_exp_f32_e32 v2, v2
	v_exp_f32_e32 v3, v3
	v_add_f32_e32 v6, 1.0, v6
	v_add_f32_e32 v7, 1.0, v7
	v_rcp_f32_e32 v6, v6
	v_rcp_f32_e32 v7, v7
	v_add_f32_e32 v0, 1.0, v0
	v_add_f32_e32 v1, 1.0, v1
	v_add_f32_e32 v4, 1.0, v4
	v_add_f32_e32 v5, 1.0, v5
	v_rcp_f32_e32 v0, v0
	v_rcp_f32_e32 v1, v1
	v_add_f32_e32 v2, 1.0, v2
	v_add_f32_e32 v3, 1.0, v3
	v_rcp_f32_e32 v4, v4
	v_rcp_f32_e32 v5, v5
	v_rcp_f32_e32 v2, v2
	v_rcp_f32_e32 v3, v3
	s_and_b64 vcc, exec, s[38:39]
	s_mov_b32 s3, s26
	s_mov_b32 s2, s12
	v_lshlrev_b32_e32 v16, 16, v12
	v_and_b32_e32 v17, 0xffff0000, v12
	v_lshlrev_b32_e32 v20, 16, v8
	v_and_b32_e32 v21, 0xffff0000, v8
	v_lshlrev_b32_e32 v12, 16, v13
	v_and_b32_e32 v13, 0xffff0000, v13
	v_lshlrev_b32_e32 v8, 16, v9
	v_and_b32_e32 v9, 0xffff0000, v9
	v_pk_fma_f32 v[6:7], v[6:7], v[12:13], v[8:9]
	v_lshlrev_b32_e32 v8, 16, v14
	v_and_b32_e32 v9, 0xffff0000, v14
	v_lshlrev_b32_e32 v12, 16, v10
	v_and_b32_e32 v13, 0xffff0000, v10
	v_pk_fma_f32 v[8:9], v[0:1], v[8:9], v[12:13]
	v_lshlrev_b32_e32 v0, 16, v15
	v_and_b32_e32 v1, 0xffff0000, v15
	v_lshlrev_b32_e32 v10, 16, v11
	v_and_b32_e32 v11, 0xffff0000, v11
	v_pk_fma_f32 v[4:5], v[4:5], v[16:17], v[20:21]
	v_pk_fma_f32 v[10:11], v[2:3], v[0:1], v[10:11]
	v_cvt_pk_bf16_f32 v0, v4, v5
	v_cvt_pk_bf16_f32 v1, v6, v7
	v_cvt_pk_bf16_f32 v2, v8, v9
	v_cvt_pk_bf16_f32 v3, v10, v11
	global_store_dwordx4 v[18:19], v[0:3], off
	s_cbranch_vccz .LBB0_346
	s_cmpk_gt_u32 s70, 0xff
	s_cbranch_scc1 .LBB0_357
	s_barrier

; #define PG8_WAIT_V(n) asm volatile("s_waitcnt vmcnt(" #n ")" ::: "memory")
; #define PG8_BAR __builtin_amdgcn_s_barrier()
; template <class Epi, class Sched, bool STAMP = false>
; __device__ __forceinline__ void gemm_phase(PG8_LAS unsigned char* lds, const Gemm g, const Sched& S, const Epi& E, unsigned long long* stamps) {
;     ...
;     PG8_WAIT_V(0);
;     if (wr == 0) PG8_BAR;
;     PG8_BAR;
.LBB0_1200:
	s_cmpk_gt_u32 s44, 0xff
	v_readlane_b32 s39, v242, 28
	s_movk_i32 s58, 0xff60
	s_mov_b32 s38, 0x1ffff
	s_cbranch_scc1 .LBB0_1202
	s_barrier
